# v064 + LDS fragment-read base hoisted out of the K-loops (one loop-invariant VGPR + immediate offsets): no VALU instructions left in the six K-loops
# speedup vs baseline: 1.0205x; 1.0078x over previous
.LBB0_133:
	s_ashr_i32 s19, s18, 31
	s_lshl_b64 s[28:29], s[18:19], 19
	v_cmp_lt_i64_e32 vcc, s[62:63], v[182:183]
	s_add_u32 s62, s27, s28
	s_addc_u32 s63, s37, s29
	s_and_b64 s[28:29], vcc, exec
	s_cselect_b32 s5, s63, s67
	s_cselect_b32 s7, s62, s66
	s_ashr_i32 s17, s16, 31
	s_lshl_b64 s[28:29], s[16:17], 19
	s_add_u32 s64, s46, s28
	s_addc_u32 s65, s47, s29
	s_and_b64 s[28:29], vcc, exec
	s_cselect_b32 s17, s65, s69
	s_cselect_b32 s19, s64, s68
	s_add_u32 s66, s66, 0x40080
	s_addc_u32 s67, s67, 0
	s_add_u32 s85, s68, 0x100
	v_mov_b64_e32 v[0:1], 0
	v_mov_b64_e32 v[2:3], 0
	v_mov_b64_e32 v[4:5], 0
	v_mov_b64_e32 v[6:7], 0
	v_mov_b64_e32 v[8:9], 0
	v_mov_b64_e32 v[10:11], 0
	v_mov_b64_e32 v[12:13], 0
	v_mov_b64_e32 v[14:15], 0
	v_mov_b64_e32 v[16:17], 0
	v_mov_b64_e32 v[18:19], 0
	v_mov_b64_e32 v[20:21], 0
	v_mov_b64_e32 v[22:23], 0
	v_mov_b64_e32 v[24:25], 0
	v_mov_b64_e32 v[26:27], 0
	v_mov_b64_e32 v[28:29], 0
	v_mov_b64_e32 v[30:31], 0
	v_mov_b64_e32 v[32:33], 0
	v_mov_b64_e32 v[34:35], 0
	v_mov_b64_e32 v[36:37], 0
	v_mov_b64_e32 v[38:39], 0
	v_mov_b64_e32 v[40:41], 0
	v_mov_b64_e32 v[42:43], 0
	v_mov_b64_e32 v[44:45], 0
	v_mov_b64_e32 v[46:47], 0
	v_mov_b64_e32 v[48:49], 0
	v_mov_b64_e32 v[50:51], 0
	v_mov_b64_e32 v[52:53], 0
	v_mov_b64_e32 v[54:55], 0
	v_mov_b64_e32 v[56:57], 0
	v_mov_b64_e32 v[58:59], 0
	v_mov_b64_e32 v[60:61], 0
	v_mov_b64_e32 v[62:63], 0
	v_mov_b64_e32 v[64:65], 0
	v_mov_b64_e32 v[66:67], 0
	v_mov_b64_e32 v[68:69], 0
	v_mov_b64_e32 v[70:71], 0
	v_mov_b64_e32 v[72:73], 0
	v_mov_b64_e32 v[74:75], 0
	v_mov_b64_e32 v[76:77], 0
	v_mov_b64_e32 v[78:79], 0
	v_mov_b64_e32 v[80:81], 0
	v_mov_b64_e32 v[82:83], 0
	v_mov_b64_e32 v[84:85], 0
	v_mov_b64_e32 v[86:87], 0
	v_mov_b64_e32 v[88:89], 0
	v_mov_b64_e32 v[90:91], 0
	v_mov_b64_e32 v[92:93], 0
	v_mov_b64_e32 v[94:95], 0
	v_mov_b64_e32 v[96:97], 0
	v_mov_b64_e32 v[98:99], 0
	v_mov_b64_e32 v[100:101], 0
	v_mov_b64_e32 v[102:103], 0
	v_mov_b64_e32 v[104:105], 0
	v_mov_b64_e32 v[106:107], 0
	v_mov_b64_e32 v[108:109], 0
	v_mov_b64_e32 v[110:111], 0
	v_mov_b64_e32 v[112:113], 0
	v_mov_b64_e32 v[114:115], 0
	v_mov_b64_e32 v[116:117], 0
	v_mov_b64_e32 v[118:119], 0
	v_mov_b64_e32 v[120:121], 0
	v_mov_b64_e32 v[122:123], 0
	v_mov_b64_e32 v[124:125], 0
	v_mov_b64_e32 v[126:127], 0
	s_addc_u32 s91, s69, 0
	s_mov_b32 vcc_lo, -2
	s_waitcnt vmcnt(0)
	v_add_u32_e32 v172, 0x10000, v191
.LBB0_134:
	s_add_u32 s28, s66, 0xfffc0080
	s_addc_u32 s29, s67, -1
	s_add_i32 s88, 0, 0x10000
	ds_read_b128 v[128:131], v172
	ds_read_b128 v[132:135], v172 offset:1024
	ds_read_b128 v[148:151], v172 offset:2048
	ds_read_b128 v[152:155], v172 offset:3072
	s_cmp_eq_u32 vcc_lo, 12
	s_cselect_b32 s71, s5, s29
	s_cselect_b32 s70, s7, s28
	s_cselect_b32 s69, s17, s91
	s_cselect_b32 s68, s19, s85
	s_add_i32 m0, s73, 0xc000
	ds_read_b128 v[156:159], v192
	ds_read_b128 v[164:167], v192 offset:2048
	ds_read_b128 v[194:197], v192 offset:4096
	ds_read_b128 v[202:205], v192 offset:6144
	ds_read_b128 v[160:163], v192 offset:1024
	ds_read_b128 v[168:171], v192 offset:3072
	ds_read_b128 v[198:201], v192 offset:5120
	ds_read_b128 v[206:209], v192 offset:7168
	global_load_lds_dwordx4 v144, s[66:67]
	s_add_i32 m0, s73, 0xe000
	s_nop 0
	global_load_lds_dwordx4 v146, s[66:67]
	s_waitcnt lgkmcnt(8)
	s_barrier
	s_waitcnt lgkmcnt(7)
	v_mfma_f32_16x16x32_bf16 v[124:127], v[128:131], v[156:159], v[124:127]
	v_mfma_f32_16x16x32_bf16 v[120:123], v[148:151], v[156:159], v[120:123]
	s_waitcnt lgkmcnt(6)
	v_mfma_f32_16x16x32_bf16 v[108:111], v[128:131], v[164:167], v[108:111]
	v_mfma_f32_16x16x32_bf16 v[104:107], v[148:151], v[164:167], v[104:107]
	s_waitcnt lgkmcnt(5)
	v_mfma_f32_16x16x32_bf16 v[92:95], v[128:131], v[194:197], v[92:95]
	v_mfma_f32_16x16x32_bf16 v[88:91], v[148:151], v[194:197], v[88:91]
	s_waitcnt lgkmcnt(4)
	v_mfma_f32_16x16x32_bf16 v[76:79], v[128:131], v[202:205], v[76:79]
	v_mfma_f32_16x16x32_bf16 v[72:75], v[148:151], v[202:205], v[72:75]
	s_waitcnt lgkmcnt(3)
	v_mfma_f32_16x16x32_bf16 v[124:127], v[132:135], v[160:163], v[124:127]
	v_mfma_f32_16x16x32_bf16 v[120:123], v[152:155], v[160:163], v[120:123]
	s_waitcnt lgkmcnt(2)
	v_mfma_f32_16x16x32_bf16 v[108:111], v[132:135], v[168:171], v[108:111]
	v_mfma_f32_16x16x32_bf16 v[104:107], v[152:155], v[168:171], v[104:107]
	s_waitcnt lgkmcnt(1)
	v_mfma_f32_16x16x32_bf16 v[92:95], v[132:135], v[198:201], v[92:95]
	v_mfma_f32_16x16x32_bf16 v[88:91], v[152:155], v[198:201], v[88:91]
	s_waitcnt lgkmcnt(0)
	v_mfma_f32_16x16x32_bf16 v[76:79], v[132:135], v[206:209], v[76:79]
	v_mfma_f32_16x16x32_bf16 v[72:75], v[152:155], v[206:209], v[72:75]
	s_barrier
	s_add_i32 s89, 0, 0x14000
	s_add_i32 s28, s88, s72
	ds_read_b128 v[210:213], v172 offset:16384
	ds_read_b128 v[214:217], v172 offset:17408
	ds_read_b128 v[232:235], v172 offset:18432
	ds_read_b128 v[236:239], v172 offset:19456
	s_mov_b32 m0, s28
	s_nop 0
	global_load_lds_dwordx4 v138, s[68:69]
	s_add_i32 m0, s28, 0x2000
	s_nop 0
	global_load_lds_dwordx4 v142, s[68:69]
	s_barrier
	s_waitcnt lgkmcnt(3)
	v_mfma_f32_16x16x32_bf16 v[116:119], v[210:213], v[156:159], v[116:119]
	s_waitcnt lgkmcnt(1)
	v_mfma_f32_16x16x32_bf16 v[112:115], v[232:235], v[156:159], v[112:115]
	v_mfma_f32_16x16x32_bf16 v[100:103], v[210:213], v[164:167], v[100:103]
	v_mfma_f32_16x16x32_bf16 v[96:99], v[232:235], v[164:167], v[96:99]
	v_mfma_f32_16x16x32_bf16 v[84:87], v[210:213], v[194:197], v[84:87]
	v_mfma_f32_16x16x32_bf16 v[80:83], v[232:235], v[194:197], v[80:83]
	v_mfma_f32_16x16x32_bf16 v[68:71], v[210:213], v[202:205], v[68:71]
	v_mfma_f32_16x16x32_bf16 v[64:67], v[232:235], v[202:205], v[64:67]
	v_mfma_f32_16x16x32_bf16 v[116:119], v[214:217], v[160:163], v[116:119]
	s_waitcnt lgkmcnt(0)
	v_mfma_f32_16x16x32_bf16 v[112:115], v[236:239], v[160:163], v[112:115]
	v_mfma_f32_16x16x32_bf16 v[100:103], v[214:217], v[168:171], v[100:103]
	v_mfma_f32_16x16x32_bf16 v[96:99], v[236:239], v[168:171], v[96:99]
	v_mfma_f32_16x16x32_bf16 v[84:87], v[214:217], v[198:201], v[84:87]
	v_mfma_f32_16x16x32_bf16 v[80:83], v[236:239], v[198:201], v[80:83]
	v_mfma_f32_16x16x32_bf16 v[68:71], v[214:217], v[206:209], v[68:71]
	v_mfma_f32_16x16x32_bf16 v[64:67], v[236:239], v[206:209], v[64:67]
	s_mov_b32 m0, s73
	s_barrier
	ds_read_b128 v[156:159], v192 offset:16384
	ds_read_b128 v[164:167], v192 offset:18432
	ds_read_b128 v[194:197], v192 offset:20480
	ds_read_b128 v[202:205], v192 offset:22528
	ds_read_b128 v[160:163], v192 offset:17408
	ds_read_b128 v[168:171], v192 offset:19456
	ds_read_b128 v[198:201], v192 offset:21504
	ds_read_b128 v[206:209], v192 offset:23552
	global_load_lds_dwordx4 v136, s[70:71]
	s_mov_b32 m0, s74
	s_nop 0
	global_load_lds_dwordx4 v140, s[70:71]
	s_barrier
	s_waitcnt lgkmcnt(7)
	v_mfma_f32_16x16x32_bf16 v[60:63], v[128:131], v[156:159], v[60:63]
	v_mfma_f32_16x16x32_bf16 v[56:59], v[148:151], v[156:159], v[56:59]
	s_waitcnt lgkmcnt(6)
	v_mfma_f32_16x16x32_bf16 v[44:47], v[128:131], v[164:167], v[44:47]
	v_mfma_f32_16x16x32_bf16 v[40:43], v[148:151], v[164:167], v[40:43]
	s_waitcnt lgkmcnt(5)
	v_mfma_f32_16x16x32_bf16 v[28:31], v[128:131], v[194:197], v[28:31]
	v_mfma_f32_16x16x32_bf16 v[24:27], v[148:151], v[194:197], v[24:27]
	s_waitcnt lgkmcnt(4)
	v_mfma_f32_16x16x32_bf16 v[12:15], v[128:131], v[202:205], v[12:15]
	v_mfma_f32_16x16x32_bf16 v[8:11], v[148:151], v[202:205], v[8:11]
	s_waitcnt lgkmcnt(3)
	v_mfma_f32_16x16x32_bf16 v[60:63], v[132:135], v[160:163], v[60:63]
	v_mfma_f32_16x16x32_bf16 v[56:59], v[152:155], v[160:163], v[56:59]
	s_waitcnt lgkmcnt(2)
	v_mfma_f32_16x16x32_bf16 v[44:47], v[132:135], v[168:171], v[44:47]
	v_mfma_f32_16x16x32_bf16 v[40:43], v[152:155], v[168:171], v[40:43]
	s_waitcnt lgkmcnt(1)
	v_mfma_f32_16x16x32_bf16 v[28:31], v[132:135], v[198:201], v[28:31]
	v_mfma_f32_16x16x32_bf16 v[24:27], v[152:155], v[198:201], v[24:27]
	s_waitcnt lgkmcnt(0)
	v_mfma_f32_16x16x32_bf16 v[12:15], v[132:135], v[206:209], v[12:15]
	v_mfma_f32_16x16x32_bf16 v[8:11], v[152:155], v[206:209], v[8:11]
	s_barrier
	s_add_u32 s28, s68, 0x40000
	s_addc_u32 s29, s69, 0
	s_add_i32 s88, s89, s72
	s_mov_b32 m0, s88
	s_nop 0
	global_load_lds_dwordx4 v138, s[28:29]
	s_add_i32 m0, s88, 0x2000
	s_nop 0
	global_load_lds_dwordx4 v142, s[28:29]
	s_waitcnt vmcnt(6)
	s_barrier
	v_mfma_f32_16x16x32_bf16 v[52:55], v[210:213], v[156:159], v[52:55]
	v_mfma_f32_16x16x32_bf16 v[48:51], v[232:235], v[156:159], v[48:51]
	v_mfma_f32_16x16x32_bf16 v[36:39], v[210:213], v[164:167], v[36:39]
	v_mfma_f32_16x16x32_bf16 v[32:35], v[232:235], v[164:167], v[32:35]
	v_mfma_f32_16x16x32_bf16 v[20:23], v[210:213], v[194:197], v[20:23]
	v_mfma_f32_16x16x32_bf16 v[16:19], v[232:235], v[194:197], v[16:19]
	v_mfma_f32_16x16x32_bf16 v[4:7], v[210:213], v[202:205], v[4:7]
	v_mfma_f32_16x16x32_bf16 v[0:3], v[232:235], v[202:205], v[0:3]
	v_mfma_f32_16x16x32_bf16 v[52:55], v[214:217], v[160:163], v[52:55]
	v_mfma_f32_16x16x32_bf16 v[48:51], v[236:239], v[160:163], v[48:51]
	v_mfma_f32_16x16x32_bf16 v[36:39], v[214:217], v[168:171], v[36:39]
	v_mfma_f32_16x16x32_bf16 v[32:35], v[236:239], v[168:171], v[32:35]
	v_mfma_f32_16x16x32_bf16 v[20:23], v[214:217], v[198:201], v[20:23]
	v_mfma_f32_16x16x32_bf16 v[16:19], v[236:239], v[198:201], v[16:19]
	v_mfma_f32_16x16x32_bf16 v[4:7], v[214:217], v[206:209], v[4:7]
	v_mfma_f32_16x16x32_bf16 v[0:3], v[236:239], v[206:209], v[0:3]
	s_add_i32 s88, 0, 0x18000
	s_barrier
	ds_read_b128 v[128:131], v172 offset:32768
	ds_read_b128 v[132:135], v172 offset:33792
	ds_read_b128 v[148:151], v172 offset:34816
	ds_read_b128 v[152:155], v172 offset:35840
	s_add_u32 s28, s70, 0x40000
	s_addc_u32 s29, s71, 0
	s_mov_b32 m0, s75
	ds_read_b128 v[156:159], v192 offset:32768
	ds_read_b128 v[164:167], v192 offset:34816
	ds_read_b128 v[194:197], v192 offset:36864
	ds_read_b128 v[202:205], v192 offset:38912
	ds_read_b128 v[160:163], v192 offset:33792
	ds_read_b128 v[168:171], v192 offset:35840
	ds_read_b128 v[198:201], v192 offset:37888
	ds_read_b128 v[206:209], v192 offset:39936
	global_load_lds_dwordx4 v136, s[28:29]
	s_mov_b32 m0, s76
	s_nop 0
	global_load_lds_dwordx4 v140, s[28:29]
	s_waitcnt lgkmcnt(8)
	s_barrier
	s_waitcnt lgkmcnt(7)
	v_mfma_f32_16x16x32_bf16 v[124:127], v[128:131], v[156:159], v[124:127]
	v_mfma_f32_16x16x32_bf16 v[120:123], v[148:151], v[156:159], v[120:123]
	s_waitcnt lgkmcnt(6)
	v_mfma_f32_16x16x32_bf16 v[108:111], v[128:131], v[164:167], v[108:111]
	v_mfma_f32_16x16x32_bf16 v[104:107], v[148:151], v[164:167], v[104:107]
	s_waitcnt lgkmcnt(5)
	v_mfma_f32_16x16x32_bf16 v[92:95], v[128:131], v[194:197], v[92:95]
	v_mfma_f32_16x16x32_bf16 v[88:91], v[148:151], v[194:197], v[88:91]
	s_waitcnt lgkmcnt(4)
	v_mfma_f32_16x16x32_bf16 v[76:79], v[128:131], v[202:205], v[76:79]
	v_mfma_f32_16x16x32_bf16 v[72:75], v[148:151], v[202:205], v[72:75]
	s_waitcnt lgkmcnt(3)
	v_mfma_f32_16x16x32_bf16 v[124:127], v[132:135], v[160:163], v[124:127]
	v_mfma_f32_16x16x32_bf16 v[120:123], v[152:155], v[160:163], v[120:123]
	s_waitcnt lgkmcnt(2)
	v_mfma_f32_16x16x32_bf16 v[108:111], v[132:135], v[168:171], v[108:111]
	v_mfma_f32_16x16x32_bf16 v[104:107], v[152:155], v[168:171], v[104:107]
	s_waitcnt lgkmcnt(1)
	v_mfma_f32_16x16x32_bf16 v[92:95], v[132:135], v[198:201], v[92:95]
	v_mfma_f32_16x16x32_bf16 v[88:91], v[152:155], v[198:201], v[88:91]
	s_waitcnt lgkmcnt(0)
	v_mfma_f32_16x16x32_bf16 v[76:79], v[132:135], v[206:209], v[76:79]
	v_mfma_f32_16x16x32_bf16 v[72:75], v[152:155], v[206:209], v[72:75]
	s_barrier
	s_add_i32 s98, 0, 0x1c000
	s_add_i32 s28, s88, s72
	s_add_i32 m0, s28, 0xffffff80
	ds_read_b128 v[210:213], v172 offset:49152
	ds_read_b128 v[214:217], v172 offset:50176
	ds_read_b128 v[232:235], v172 offset:51200
	ds_read_b128 v[236:239], v172 offset:52224
	global_load_lds_dwordx4 v138, s[68:69] offset:128
	s_add_i32 m0, s28, 0x1f80
	s_nop 0
	global_load_lds_dwordx4 v142, s[68:69] offset:128
	s_barrier
	s_waitcnt lgkmcnt(3)
	v_mfma_f32_16x16x32_bf16 v[116:119], v[210:213], v[156:159], v[116:119]
	s_waitcnt lgkmcnt(1)
	v_mfma_f32_16x16x32_bf16 v[112:115], v[232:235], v[156:159], v[112:115]
	v_mfma_f32_16x16x32_bf16 v[100:103], v[210:213], v[164:167], v[100:103]
	v_mfma_f32_16x16x32_bf16 v[96:99], v[232:235], v[164:167], v[96:99]
	v_mfma_f32_16x16x32_bf16 v[84:87], v[210:213], v[194:197], v[84:87]
	v_mfma_f32_16x16x32_bf16 v[80:83], v[232:235], v[194:197], v[80:83]
	v_mfma_f32_16x16x32_bf16 v[68:71], v[210:213], v[202:205], v[68:71]
	v_mfma_f32_16x16x32_bf16 v[64:67], v[232:235], v[202:205], v[64:67]
	v_mfma_f32_16x16x32_bf16 v[116:119], v[214:217], v[160:163], v[116:119]
	s_waitcnt lgkmcnt(0)
	v_mfma_f32_16x16x32_bf16 v[112:115], v[236:239], v[160:163], v[112:115]
	v_mfma_f32_16x16x32_bf16 v[100:103], v[214:217], v[168:171], v[100:103]
	v_mfma_f32_16x16x32_bf16 v[96:99], v[236:239], v[168:171], v[96:99]
	v_mfma_f32_16x16x32_bf16 v[84:87], v[214:217], v[198:201], v[84:87]
	v_mfma_f32_16x16x32_bf16 v[80:83], v[236:239], v[198:201], v[80:83]
	v_mfma_f32_16x16x32_bf16 v[68:71], v[214:217], v[206:209], v[68:71]
	v_mfma_f32_16x16x32_bf16 v[64:67], v[236:239], v[206:209], v[64:67]
	s_add_i32 m0, s79, 0xffffff80
	s_barrier
	ds_read_b128 v[156:159], v192 offset:49152
	ds_read_b128 v[164:167], v192 offset:51200
	ds_read_b128 v[194:197], v192 offset:53248
	ds_read_b128 v[202:205], v192 offset:55296
	ds_read_b128 v[160:163], v192 offset:50176
	ds_read_b128 v[168:171], v192 offset:52224
	ds_read_b128 v[198:201], v192 offset:54272
	ds_read_b128 v[206:209], v192 offset:56320
	global_load_lds_dwordx4 v136, s[70:71] offset:128
	s_add_i32 m0, s80, 0xffffff80
	s_nop 0
	global_load_lds_dwordx4 v140, s[70:71] offset:128
	s_barrier
	s_waitcnt lgkmcnt(7)
	v_mfma_f32_16x16x32_bf16 v[60:63], v[128:131], v[156:159], v[60:63]
	v_mfma_f32_16x16x32_bf16 v[56:59], v[148:151], v[156:159], v[56:59]
	s_waitcnt lgkmcnt(6)
	v_mfma_f32_16x16x32_bf16 v[44:47], v[128:131], v[164:167], v[44:47]
	v_mfma_f32_16x16x32_bf16 v[40:43], v[148:151], v[164:167], v[40:43]
	s_waitcnt lgkmcnt(5)
	v_mfma_f32_16x16x32_bf16 v[28:31], v[128:131], v[194:197], v[28:31]
	v_mfma_f32_16x16x32_bf16 v[24:27], v[148:151], v[194:197], v[24:27]
	s_waitcnt lgkmcnt(4)
	v_mfma_f32_16x16x32_bf16 v[12:15], v[128:131], v[202:205], v[12:15]
	v_mfma_f32_16x16x32_bf16 v[8:11], v[148:151], v[202:205], v[8:11]
	s_waitcnt lgkmcnt(3)
	v_mfma_f32_16x16x32_bf16 v[60:63], v[132:135], v[160:163], v[60:63]
	v_mfma_f32_16x16x32_bf16 v[56:59], v[152:155], v[160:163], v[56:59]
	s_waitcnt lgkmcnt(2)
	v_mfma_f32_16x16x32_bf16 v[44:47], v[132:135], v[168:171], v[44:47]
	v_mfma_f32_16x16x32_bf16 v[40:43], v[152:155], v[168:171], v[40:43]
	s_waitcnt lgkmcnt(1)
	v_mfma_f32_16x16x32_bf16 v[28:31], v[132:135], v[198:201], v[28:31]
	v_mfma_f32_16x16x32_bf16 v[24:27], v[152:155], v[198:201], v[24:27]
	s_waitcnt lgkmcnt(0)
	v_mfma_f32_16x16x32_bf16 v[12:15], v[132:135], v[206:209], v[12:15]
	v_mfma_f32_16x16x32_bf16 v[8:11], v[152:155], v[206:209], v[8:11]
	s_barrier
	s_add_u32 s28, s68, 0x40080
	s_addc_u32 s29, s69, 0
	s_add_i32 s68, s98, s72
	s_mov_b32 m0, s68
	s_nop 0
	global_load_lds_dwordx4 v138, s[28:29]
	s_add_i32 m0, s68, 0x2000
	s_nop 0
	global_load_lds_dwordx4 v142, s[28:29]
	s_waitcnt vmcnt(6)
	s_barrier
	v_mfma_f32_16x16x32_bf16 v[52:55], v[210:213], v[156:159], v[52:55]
	v_mfma_f32_16x16x32_bf16 v[48:51], v[232:235], v[156:159], v[48:51]
	v_mfma_f32_16x16x32_bf16 v[36:39], v[210:213], v[164:167], v[36:39]
	v_mfma_f32_16x16x32_bf16 v[32:35], v[232:235], v[164:167], v[32:35]
	v_mfma_f32_16x16x32_bf16 v[20:23], v[210:213], v[194:197], v[20:23]
	v_mfma_f32_16x16x32_bf16 v[16:19], v[232:235], v[194:197], v[16:19]
	v_mfma_f32_16x16x32_bf16 v[4:7], v[210:213], v[202:205], v[4:7]
	v_mfma_f32_16x16x32_bf16 v[0:3], v[232:235], v[202:205], v[0:3]
	v_mfma_f32_16x16x32_bf16 v[52:55], v[214:217], v[160:163], v[52:55]
	v_mfma_f32_16x16x32_bf16 v[48:51], v[236:239], v[160:163], v[48:51]
	v_mfma_f32_16x16x32_bf16 v[36:39], v[214:217], v[168:171], v[36:39]
	v_mfma_f32_16x16x32_bf16 v[32:35], v[236:239], v[168:171], v[32:35]
	v_mfma_f32_16x16x32_bf16 v[20:23], v[214:217], v[198:201], v[20:23]
	v_mfma_f32_16x16x32_bf16 v[16:19], v[236:239], v[198:201], v[16:19]
	v_mfma_f32_16x16x32_bf16 v[4:7], v[214:217], v[206:209], v[4:7]
	v_mfma_f32_16x16x32_bf16 v[0:3], v[236:239], v[206:209], v[0:3]
	s_add_i32 vcc_lo, vcc_lo, 2
	s_add_u32 s66, s66, 0x100
	s_addc_u32 s67, s67, 0
	s_add_u32 s85, s85, 0x100
	s_addc_u32 s91, s91, 0
	s_cmp_lt_u32 vcc_lo, 14
	s_barrier
	s_cbranch_scc1 .LBB0_134
	s_lshl_b32 s4, s4, 8
	v_mov_b32_e32 v176, v175
	v_mov_b32_e32 v188, v190
	s_add_i32 s4, s4, s77
	s_cmp_gt_i32 s6, 7
	v_add_u32_e32 v148, s4, v176
	v_lshlrev_b32_e32 v128, 2, v188
	v_ashrrev_i32_e32 v129, 31, v128
	v_ashrrev_i32_e32 v149, 31, v148
	v_lshl_add_u64 v[128:129], v[128:129], 2, s[8:9]
	v_lshlrev_b64 v[130:131], 6, v[148:149]
	v_add_u32_e32 v166, 16, v148
	v_lshl_add_u64 v[130:131], v[128:129], 0, v[130:131]
	v_ashrrev_i32_e32 v167, 31, v166
	global_load_dwordx4 v[160:163], v[130:131], off
	v_lshlrev_b64 v[130:131], 6, v[166:167]
	v_lshl_add_u64 v[130:131], v[128:129], 0, v[130:131]
	global_load_dwordx4 v[168:171], v[130:131], off
	v_add_u32_e32 v164, 32, v148
	v_ashrrev_i32_e32 v165, 31, v164
	v_lshlrev_b64 v[130:131], 6, v[164:165]
	v_add_u32_e32 v158, 48, v148
	v_lshl_add_u64 v[130:131], v[128:129], 0, v[130:131]
	v_ashrrev_i32_e32 v159, 31, v158
	global_load_dwordx4 v[194:197], v[130:131], off
	v_lshlrev_b64 v[130:131], 6, v[158:159]
	v_lshl_add_u64 v[130:131], v[128:129], 0, v[130:131]
	global_load_dwordx4 v[198:201], v[130:131], off
	v_add_u32_e32 v156, 0x80, v148
	v_ashrrev_i32_e32 v157, 31, v156
	v_lshlrev_b64 v[130:131], 6, v[156:157]
	v_add_u32_e32 v154, 0x90, v148
	v_lshl_add_u64 v[130:131], v[128:129], 0, v[130:131]
	v_ashrrev_i32_e32 v155, 31, v154
	global_load_dwordx4 v[202:205], v[130:131], off
	v_lshlrev_b64 v[130:131], 6, v[154:155]
	v_add_u32_e32 v152, 0xa0, v148
	v_lshl_add_u64 v[130:131], v[128:129], 0, v[130:131]
	v_ashrrev_i32_e32 v153, 31, v152
	global_load_dwordx4 v[206:209], v[130:131], off
	v_lshlrev_b64 v[130:131], 6, v[152:153]
	v_add_u32_e32 v150, 0xb0, v148
	v_lshl_add_u64 v[130:131], v[128:129], 0, v[130:131]
	v_ashrrev_i32_e32 v151, 31, v150
	global_load_dwordx4 v[132:135], v[130:131], off
	v_lshlrev_b64 v[130:131], 6, v[150:151]
	v_lshl_add_u64 v[128:129], v[128:129], 0, v[130:131]
	global_load_dwordx4 v[128:131], v[128:129], off
	s_cselect_b64 s[66:67], -1, 0
	s_lshl_b32 s7, s6, 8
	s_add_i32 s7, s81, s7
	s_cmp_lt_i32 s6, 8
	s_mov_b64 s[68:69], -1
	s_waitcnt vmcnt(0)
	v_mov_b32_e32 v172, v161
	v_mov_b32_e32 v173, v162
	v_mov_b32_e32 v161, v163
	v_mov_b32_e32 v162, v169
	v_mov_b32_e32 v163, v170
	v_mov_b32_e32 v169, v171
	v_pk_add_f32 v[160:161], v[172:173], v[160:161]
	v_pk_add_f32 v[162:163], v[162:163], v[168:169]
	v_mov_b32_e32 v169, v160
	v_mov_b32_e32 v168, v162
	v_mov_b32_e32 v160, v163
	v_pk_add_f32 v[160:161], v[168:169], v[160:161]
	ds_bpermute_b32 v163, v219, v161
	ds_bpermute_b32 v162, v219, v160
	s_waitcnt lgkmcnt(0)
	v_pk_add_f32 v[160:161], v[160:161], v[162:163]
	ds_bpermute_b32 v163, v218, v161
	ds_bpermute_b32 v162, v218, v160
	s_waitcnt lgkmcnt(0)
	v_pk_add_f32 v[160:161], v[160:161], v[162:163]
	s_nop 0
	v_pk_fma_f32 v[172:173], v[160:161], s[30:31], v[178:179] op_sel_hi:[1,0,0]
	v_mov_b32_e32 v162, v199
	v_mul_f32_e32 v160, 0x4b800000, v173
	v_cmp_gt_f32_e32 vcc, s86, v173
	v_mov_b32_e32 v163, v200
	v_mov_b32_e32 v199, v201
	v_cndmask_b32_e32 v160, v173, v160, vcc
	v_rsq_f32_e32 v160, v160
	v_pk_add_f32 v[162:163], v[162:163], v[198:199]
	v_cmp_gt_f32_e64 s[4:5], s86, v172
	v_mov_b32_e32 v168, v162
	v_mul_f32_e32 v161, 0x45800000, v160
	v_cndmask_b32_e32 v174, v160, v161, vcc
	v_mov_b32_e32 v160, v195
	v_mov_b32_e32 v161, v196
	v_mov_b32_e32 v195, v197
	v_pk_add_f32 v[160:161], v[160:161], v[194:195]
	s_nop 0
	v_mov_b32_e32 v169, v160
	v_mov_b32_e32 v160, v163
	v_pk_add_f32 v[160:161], v[168:169], v[160:161]
	ds_bpermute_b32 v163, v219, v161
	ds_bpermute_b32 v162, v219, v160
	s_waitcnt lgkmcnt(0)
	v_pk_add_f32 v[168:169], v[160:161], v[162:163]
	v_mov_b32_e32 v160, v203
	v_mov_b32_e32 v161, v204
	v_mov_b32_e32 v203, v205
	v_mov_b32_e32 v162, v207
	v_mov_b32_e32 v163, v208
	v_mov_b32_e32 v207, v209
	v_pk_add_f32 v[160:161], v[160:161], v[202:203]
	v_pk_add_f32 v[162:163], v[162:163], v[206:207]
	v_mov_b32_e32 v195, v160
	v_mov_b32_e32 v194, v162
	v_mov_b32_e32 v160, v163
	v_pk_add_f32 v[160:161], v[194:195], v[160:161]
	v_mov_b32_e32 v194, v133
	v_mov_b32_e32 v195, v134
	v_mov_b32_e32 v133, v135
	v_mov_b32_e32 v134, v129
	v_mov_b32_e32 v135, v130
	v_mov_b32_e32 v129, v131
	v_pk_add_f32 v[132:133], v[194:195], v[132:133]
	v_pk_add_f32 v[128:129], v[134:135], v[128:129]
	v_mov_b32_e32 v131, v132
	v_mov_b32_e32 v130, v128
	v_mov_b32_e32 v132, v129
	v_pk_add_f32 v[128:129], v[130:131], v[132:133]
	ds_bpermute_b32 v163, v219, v161
	ds_bpermute_b32 v162, v219, v160
	ds_bpermute_b32 v131, v219, v129
	ds_bpermute_b32 v130, v219, v128
	ds_bpermute_b32 v171, v218, v169
	ds_bpermute_b32 v170, v218, v168
	s_waitcnt lgkmcnt(4)
	v_pk_add_f32 v[160:161], v[160:161], v[162:163]
	ds_bpermute_b32 v163, v218, v161
	s_waitcnt lgkmcnt(3)
	v_pk_add_f32 v[132:133], v[128:129], v[130:131]
	ds_bpermute_b32 v162, v218, v160
	ds_bpermute_b32 v135, v218, v133
	ds_bpermute_b32 v134, v218, v132
	v_lshlrev_b32_e32 v128, 3, v188
	v_add_u32_e32 v130, s7, v128
	v_lshlrev_b64 v[188:189], 11, v[148:149]
	v_ashrrev_i32_e32 v131, 31, v130
	s_cbranch_scc1 .LBB0_137
	v_mul_f32_e32 v196, v120, v174
	v_mul_f32_e32 v197, v121, v174
	v_mul_f32_e32 v198, v122, v174
	v_mul_f32_e32 v199, v123, v174
	v_mul_f32_e32 v129, v124, v174
	v_mul_f32_e32 v149, v125, v174
	v_mul_f32_e32 v173, v126, v174
	v_mul_f32_e32 v193, v127, v174
	v_cvt_pk_bf16_f32 v194, v129, v149
	v_cvt_pk_bf16_f32 v195, v173, v193
	v_cvt_pk_bf16_f32 v196, v196, v197
	v_cvt_pk_bf16_f32 v197, v198, v199
	v_lshl_add_u64 v[198:199], s[12:13], 0, v[188:189]
	v_lshl_add_u64 v[198:199], v[130:131], 1, v[198:199]
	global_store_dwordx4 v[198:199], v[194:197], off
	s_mov_b64 s[68:69], 0
	v_mul_f32_e32 v129, v116, v174
	v_mul_f32_e32 v196, v112, v174
	v_mul_f32_e32 v197, v113, v174
	v_mul_f32_e32 v149, v117, v174
	v_mul_f32_e32 v173, v118, v174
	v_mul_f32_e32 v193, v119, v174
	v_mul_f32_e32 v200, v114, v174
	v_mul_f32_e32 v201, v115, v174
	v_cvt_pk_bf16_f32 v194, v129, v149
	v_cvt_pk_bf16_f32 v195, v173, v193
	v_cvt_pk_bf16_f32 v196, v196, v197
	v_cvt_pk_bf16_f32 v197, v200, v201
	global_store_dwordx4 v[198:199], v[194:197], off offset:256

.LBB0_412:
	s_add_i32 s13, s67, -2
	s_add_u32 s85, s62, 0x100
	v_mov_b64_e32 v[0:1], 0
	v_mov_b64_e32 v[2:3], 0
	v_mov_b64_e32 v[4:5], 0
	v_mov_b64_e32 v[6:7], 0
	v_mov_b64_e32 v[8:9], 0
	v_mov_b64_e32 v[10:11], 0
	v_mov_b64_e32 v[12:13], 0
	v_mov_b64_e32 v[14:15], 0
	v_mov_b64_e32 v[16:17], 0
	v_mov_b64_e32 v[18:19], 0
	v_mov_b64_e32 v[20:21], 0
	v_mov_b64_e32 v[22:23], 0
	v_mov_b64_e32 v[24:25], 0
	v_mov_b64_e32 v[26:27], 0
	v_mov_b64_e32 v[28:29], 0
	v_mov_b64_e32 v[30:31], 0
	v_mov_b64_e32 v[32:33], 0
	v_mov_b64_e32 v[34:35], 0
	v_mov_b64_e32 v[36:37], 0
	v_mov_b64_e32 v[38:39], 0
	v_mov_b64_e32 v[40:41], 0
	v_mov_b64_e32 v[42:43], 0
	v_mov_b64_e32 v[44:45], 0
	v_mov_b64_e32 v[46:47], 0
	v_mov_b64_e32 v[48:49], 0
	v_mov_b64_e32 v[50:51], 0
	v_mov_b64_e32 v[52:53], 0
	v_mov_b64_e32 v[54:55], 0
	v_mov_b64_e32 v[56:57], 0
	v_mov_b64_e32 v[58:59], 0
	v_mov_b64_e32 v[60:61], 0
	v_mov_b64_e32 v[62:63], 0
	v_mov_b64_e32 v[64:65], 0
	v_mov_b64_e32 v[66:67], 0
	v_mov_b64_e32 v[68:69], 0
	v_mov_b64_e32 v[70:71], 0
	v_mov_b64_e32 v[72:73], 0
	v_mov_b64_e32 v[74:75], 0
	v_mov_b64_e32 v[76:77], 0
	v_mov_b64_e32 v[78:79], 0
	v_mov_b64_e32 v[80:81], 0
	v_mov_b64_e32 v[82:83], 0
	v_mov_b64_e32 v[84:85], 0
	v_mov_b64_e32 v[86:87], 0
	v_mov_b64_e32 v[88:89], 0
	v_mov_b64_e32 v[90:91], 0
	v_mov_b64_e32 v[92:93], 0
	v_mov_b64_e32 v[94:95], 0
	v_mov_b64_e32 v[96:97], 0
	v_mov_b64_e32 v[98:99], 0
	v_mov_b64_e32 v[100:101], 0
	v_mov_b64_e32 v[102:103], 0
	v_mov_b64_e32 v[104:105], 0
	v_mov_b64_e32 v[106:107], 0
	v_mov_b64_e32 v[108:109], 0
	v_mov_b64_e32 v[110:111], 0
	v_mov_b64_e32 v[112:113], 0
	v_mov_b64_e32 v[114:115], 0
	v_mov_b64_e32 v[116:117], 0
	v_mov_b64_e32 v[118:119], 0
	v_mov_b64_e32 v[120:121], 0
	v_mov_b64_e32 v[122:123], 0
	v_mov_b64_e32 v[124:125], 0
	v_mov_b64_e32 v[126:127], 0
	s_addc_u32 s91, s63, 0
	s_mov_b32 s62, 0
	v_add_u32_e32 v174, 0x10000, v164
.LBB0_413:
	s_add_i32 vcc_lo, s62, 2
	s_add_u32 s4, s18, 0x100
	s_addc_u32 s5, s19, 0
	s_add_i32 s28, 0, 0x10000
	ds_read_b128 v[128:131], v174
	ds_read_b128 v[132:135], v174 offset:1024
	ds_read_b128 v[136:139], v174 offset:2048
	ds_read_b128 v[140:143], v174 offset:3072
	s_cmp_eq_u32 s13, s62
	s_cselect_b32 s62, s6, s85
	s_cselect_b32 s65, s17, s5
	s_cselect_b32 s64, s16, s4
	s_cselect_b32 s63, s7, s91
	s_add_i32 m0, s69, 0xc000
	ds_read_b128 v[154:157], v165
	ds_read_b128 v[166:169], v165 offset:2048
	ds_read_b128 v[188:191], v165 offset:4096
	ds_read_b128 v[196:199], v165 offset:6144
	ds_read_b128 v[158:161], v165 offset:1024
	ds_read_b128 v[170:173], v165 offset:3072
	ds_read_b128 v[192:195], v165 offset:5120
	ds_read_b128 v[200:203], v165 offset:7168
	global_load_lds_dwordx4 v150, s[18:19]
	s_add_i32 m0, s69, 0xe000
	s_nop 0
	global_load_lds_dwordx4 v152, s[18:19]
	s_waitcnt lgkmcnt(8)
	s_barrier
	s_waitcnt lgkmcnt(7)
	v_mfma_f32_16x16x32_bf16 v[124:127], v[128:131], v[154:157], v[124:127]
	v_mfma_f32_16x16x32_bf16 v[120:123], v[136:139], v[154:157], v[120:123]
	s_waitcnt lgkmcnt(6)
	v_mfma_f32_16x16x32_bf16 v[108:111], v[128:131], v[166:169], v[108:111]
	v_mfma_f32_16x16x32_bf16 v[104:107], v[136:139], v[166:169], v[104:107]
	s_waitcnt lgkmcnt(5)
	v_mfma_f32_16x16x32_bf16 v[92:95], v[128:131], v[188:191], v[92:95]
	v_mfma_f32_16x16x32_bf16 v[88:91], v[136:139], v[188:191], v[88:91]
	s_waitcnt lgkmcnt(4)
	v_mfma_f32_16x16x32_bf16 v[76:79], v[128:131], v[196:199], v[76:79]
	v_mfma_f32_16x16x32_bf16 v[72:75], v[136:139], v[196:199], v[72:75]
	s_waitcnt lgkmcnt(3)
	v_mfma_f32_16x16x32_bf16 v[124:127], v[132:135], v[158:161], v[124:127]
	v_mfma_f32_16x16x32_bf16 v[120:123], v[140:143], v[158:161], v[120:123]
	s_waitcnt lgkmcnt(2)
	v_mfma_f32_16x16x32_bf16 v[108:111], v[132:135], v[170:173], v[108:111]
	v_mfma_f32_16x16x32_bf16 v[104:107], v[140:143], v[170:173], v[104:107]
	s_waitcnt lgkmcnt(1)
	v_mfma_f32_16x16x32_bf16 v[92:95], v[132:135], v[192:195], v[92:95]
	v_mfma_f32_16x16x32_bf16 v[88:91], v[140:143], v[192:195], v[88:91]
	s_waitcnt lgkmcnt(0)
	v_mfma_f32_16x16x32_bf16 v[76:79], v[132:135], v[200:203], v[76:79]
	v_mfma_f32_16x16x32_bf16 v[72:75], v[140:143], v[200:203], v[72:75]
	s_barrier
	s_add_i32 s29, 0, 0x14000
	s_add_i32 s18, s28, s68
	ds_read_b128 v[204:207], v174 offset:16384
	ds_read_b128 v[208:211], v174 offset:17408
	ds_read_b128 v[212:215], v174 offset:18432
	ds_read_b128 v[232:235], v174 offset:19456
	s_mov_b32 m0, s18
	s_nop 0
	global_load_lds_dwordx4 v176, s[62:63]
	s_add_i32 m0, s18, 0x2000
	s_nop 0
	global_load_lds_dwordx4 v148, s[62:63]
	s_barrier
	s_waitcnt lgkmcnt(3)
	v_mfma_f32_16x16x32_bf16 v[116:119], v[204:207], v[154:157], v[116:119]
	s_waitcnt lgkmcnt(1)
	v_mfma_f32_16x16x32_bf16 v[112:115], v[212:215], v[154:157], v[112:115]
	v_mfma_f32_16x16x32_bf16 v[100:103], v[204:207], v[166:169], v[100:103]
	v_mfma_f32_16x16x32_bf16 v[96:99], v[212:215], v[166:169], v[96:99]
	v_mfma_f32_16x16x32_bf16 v[84:87], v[204:207], v[188:191], v[84:87]
	v_mfma_f32_16x16x32_bf16 v[80:83], v[212:215], v[188:191], v[80:83]
	v_mfma_f32_16x16x32_bf16 v[68:71], v[204:207], v[196:199], v[68:71]
	v_mfma_f32_16x16x32_bf16 v[64:67], v[212:215], v[196:199], v[64:67]
	v_mfma_f32_16x16x32_bf16 v[116:119], v[208:211], v[158:161], v[116:119]
	s_waitcnt lgkmcnt(0)
	v_mfma_f32_16x16x32_bf16 v[112:115], v[232:235], v[158:161], v[112:115]
	v_mfma_f32_16x16x32_bf16 v[100:103], v[208:211], v[170:173], v[100:103]
	v_mfma_f32_16x16x32_bf16 v[96:99], v[232:235], v[170:173], v[96:99]
	v_mfma_f32_16x16x32_bf16 v[84:87], v[208:211], v[192:195], v[84:87]
	v_mfma_f32_16x16x32_bf16 v[80:83], v[232:235], v[192:195], v[80:83]
	v_mfma_f32_16x16x32_bf16 v[68:71], v[208:211], v[200:203], v[68:71]
	v_mfma_f32_16x16x32_bf16 v[64:67], v[232:235], v[200:203], v[64:67]
	s_mov_b32 m0, s69
	s_barrier
	ds_read_b128 v[154:157], v165 offset:16384
	ds_read_b128 v[166:169], v165 offset:18432
	ds_read_b128 v[188:191], v165 offset:20480
	ds_read_b128 v[196:199], v165 offset:22528
	ds_read_b128 v[158:161], v165 offset:17408
	ds_read_b128 v[170:173], v165 offset:19456
	ds_read_b128 v[192:195], v165 offset:21504
	ds_read_b128 v[200:203], v165 offset:23552
	global_load_lds_dwordx4 v144, s[64:65]
	s_mov_b32 m0, s70
	s_nop 0
	global_load_lds_dwordx4 v146, s[64:65]
	s_barrier
	s_waitcnt lgkmcnt(7)
	v_mfma_f32_16x16x32_bf16 v[60:63], v[128:131], v[154:157], v[60:63]
	v_mfma_f32_16x16x32_bf16 v[56:59], v[136:139], v[154:157], v[56:59]
	s_waitcnt lgkmcnt(6)
	v_mfma_f32_16x16x32_bf16 v[44:47], v[128:131], v[166:169], v[44:47]
	v_mfma_f32_16x16x32_bf16 v[40:43], v[136:139], v[166:169], v[40:43]
	s_waitcnt lgkmcnt(5)
	v_mfma_f32_16x16x32_bf16 v[28:31], v[128:131], v[188:191], v[28:31]
	v_mfma_f32_16x16x32_bf16 v[24:27], v[136:139], v[188:191], v[24:27]
	s_waitcnt lgkmcnt(4)
	v_mfma_f32_16x16x32_bf16 v[12:15], v[128:131], v[196:199], v[12:15]
	v_mfma_f32_16x16x32_bf16 v[8:11], v[136:139], v[196:199], v[8:11]
	s_waitcnt lgkmcnt(3)
	v_mfma_f32_16x16x32_bf16 v[60:63], v[132:135], v[158:161], v[60:63]
	v_mfma_f32_16x16x32_bf16 v[56:59], v[140:143], v[158:161], v[56:59]
	s_waitcnt lgkmcnt(2)
	v_mfma_f32_16x16x32_bf16 v[44:47], v[132:135], v[170:173], v[44:47]
	v_mfma_f32_16x16x32_bf16 v[40:43], v[140:143], v[170:173], v[40:43]
	s_waitcnt lgkmcnt(1)
	v_mfma_f32_16x16x32_bf16 v[28:31], v[132:135], v[192:195], v[28:31]
	v_mfma_f32_16x16x32_bf16 v[24:27], v[140:143], v[192:195], v[24:27]
	s_waitcnt lgkmcnt(0)
	v_mfma_f32_16x16x32_bf16 v[12:15], v[132:135], v[200:203], v[12:15]
	v_mfma_f32_16x16x32_bf16 v[8:11], v[140:143], v[200:203], v[8:11]
	s_barrier
	s_add_u32 s18, s62, 0x18000
	s_addc_u32 s19, s63, 0
	s_add_i32 s28, s29, s68
	s_mov_b32 m0, s28
	s_nop 0
	global_load_lds_dwordx4 v176, s[18:19]
	s_add_i32 m0, s28, 0x2000
	s_nop 0
	global_load_lds_dwordx4 v148, s[18:19]
	s_waitcnt vmcnt(6)
	s_barrier
	v_mfma_f32_16x16x32_bf16 v[52:55], v[204:207], v[154:157], v[52:55]
	v_mfma_f32_16x16x32_bf16 v[48:51], v[212:215], v[154:157], v[48:51]
	v_mfma_f32_16x16x32_bf16 v[36:39], v[204:207], v[166:169], v[36:39]
	v_mfma_f32_16x16x32_bf16 v[32:35], v[212:215], v[166:169], v[32:35]
	v_mfma_f32_16x16x32_bf16 v[20:23], v[204:207], v[188:191], v[20:23]
	v_mfma_f32_16x16x32_bf16 v[16:19], v[212:215], v[188:191], v[16:19]
	v_mfma_f32_16x16x32_bf16 v[4:7], v[204:207], v[196:199], v[4:7]
	v_mfma_f32_16x16x32_bf16 v[0:3], v[212:215], v[196:199], v[0:3]
	v_mfma_f32_16x16x32_bf16 v[52:55], v[208:211], v[158:161], v[52:55]
	v_mfma_f32_16x16x32_bf16 v[48:51], v[232:235], v[158:161], v[48:51]
	v_mfma_f32_16x16x32_bf16 v[36:39], v[208:211], v[170:173], v[36:39]
	v_mfma_f32_16x16x32_bf16 v[32:35], v[232:235], v[170:173], v[32:35]
	v_mfma_f32_16x16x32_bf16 v[20:23], v[208:211], v[192:195], v[20:23]
	v_mfma_f32_16x16x32_bf16 v[16:19], v[232:235], v[192:195], v[16:19]
	v_mfma_f32_16x16x32_bf16 v[4:7], v[208:211], v[200:203], v[4:7]
	v_mfma_f32_16x16x32_bf16 v[0:3], v[232:235], v[200:203], v[0:3]
	s_add_i32 s28, 0, 0x18000
	s_barrier
	ds_read_b128 v[128:131], v174 offset:32768
	ds_read_b128 v[132:135], v174 offset:33792
	ds_read_b128 v[136:139], v174 offset:34816
	ds_read_b128 v[140:143], v174 offset:35840
	s_add_u32 s18, s64, 0x18000
	s_addc_u32 s19, s65, 0
	s_mov_b32 m0, s71
	ds_read_b128 v[154:157], v165 offset:32768
	ds_read_b128 v[166:169], v165 offset:34816
	ds_read_b128 v[188:191], v165 offset:36864
	ds_read_b128 v[196:199], v165 offset:38912
	ds_read_b128 v[158:161], v165 offset:33792
	ds_read_b128 v[170:173], v165 offset:35840
	ds_read_b128 v[192:195], v165 offset:37888
	ds_read_b128 v[200:203], v165 offset:39936
	global_load_lds_dwordx4 v144, s[18:19]
	s_mov_b32 m0, s72
	s_nop 0
	global_load_lds_dwordx4 v146, s[18:19]
	s_waitcnt lgkmcnt(8)
	s_barrier
	s_waitcnt lgkmcnt(7)
	v_mfma_f32_16x16x32_bf16 v[124:127], v[128:131], v[154:157], v[124:127]
	v_mfma_f32_16x16x32_bf16 v[120:123], v[136:139], v[154:157], v[120:123]
	s_waitcnt lgkmcnt(6)
	v_mfma_f32_16x16x32_bf16 v[108:111], v[128:131], v[166:169], v[108:111]
	v_mfma_f32_16x16x32_bf16 v[104:107], v[136:139], v[166:169], v[104:107]
	s_waitcnt lgkmcnt(5)
	v_mfma_f32_16x16x32_bf16 v[92:95], v[128:131], v[188:191], v[92:95]
	v_mfma_f32_16x16x32_bf16 v[88:91], v[136:139], v[188:191], v[88:91]
	s_waitcnt lgkmcnt(4)
	v_mfma_f32_16x16x32_bf16 v[76:79], v[128:131], v[196:199], v[76:79]
	v_mfma_f32_16x16x32_bf16 v[72:75], v[136:139], v[196:199], v[72:75]
	s_waitcnt lgkmcnt(3)
	v_mfma_f32_16x16x32_bf16 v[124:127], v[132:135], v[158:161], v[124:127]
	v_mfma_f32_16x16x32_bf16 v[120:123], v[140:143], v[158:161], v[120:123]
	s_waitcnt lgkmcnt(2)
	v_mfma_f32_16x16x32_bf16 v[108:111], v[132:135], v[170:173], v[108:111]
	v_mfma_f32_16x16x32_bf16 v[104:107], v[140:143], v[170:173], v[104:107]
	s_waitcnt lgkmcnt(1)
	v_mfma_f32_16x16x32_bf16 v[92:95], v[132:135], v[192:195], v[92:95]
	v_mfma_f32_16x16x32_bf16 v[88:91], v[140:143], v[192:195], v[88:91]
	s_waitcnt lgkmcnt(0)
	v_mfma_f32_16x16x32_bf16 v[76:79], v[132:135], v[200:203], v[76:79]
	v_mfma_f32_16x16x32_bf16 v[72:75], v[140:143], v[200:203], v[72:75]
	s_barrier
	s_add_i32 s29, 0, 0x1c000
	s_add_i32 s18, s28, s68
	s_add_i32 m0, s18, 0xffffff80
	ds_read_b128 v[204:207], v174 offset:49152
	ds_read_b128 v[208:211], v174 offset:50176
	ds_read_b128 v[212:215], v174 offset:51200
	ds_read_b128 v[232:235], v174 offset:52224
	global_load_lds_dwordx4 v176, s[62:63] offset:128
	s_add_i32 m0, s18, 0x1f80
	s_nop 0
	global_load_lds_dwordx4 v148, s[62:63] offset:128
	s_barrier
	s_waitcnt lgkmcnt(3)
	v_mfma_f32_16x16x32_bf16 v[116:119], v[204:207], v[154:157], v[116:119]
	s_waitcnt lgkmcnt(1)
	v_mfma_f32_16x16x32_bf16 v[112:115], v[212:215], v[154:157], v[112:115]
	v_mfma_f32_16x16x32_bf16 v[100:103], v[204:207], v[166:169], v[100:103]
	v_mfma_f32_16x16x32_bf16 v[96:99], v[212:215], v[166:169], v[96:99]
	v_mfma_f32_16x16x32_bf16 v[84:87], v[204:207], v[188:191], v[84:87]
	v_mfma_f32_16x16x32_bf16 v[80:83], v[212:215], v[188:191], v[80:83]
	v_mfma_f32_16x16x32_bf16 v[68:71], v[204:207], v[196:199], v[68:71]
	v_mfma_f32_16x16x32_bf16 v[64:67], v[212:215], v[196:199], v[64:67]
	v_mfma_f32_16x16x32_bf16 v[116:119], v[208:211], v[158:161], v[116:119]
	s_waitcnt lgkmcnt(0)
	v_mfma_f32_16x16x32_bf16 v[112:115], v[232:235], v[158:161], v[112:115]
	v_mfma_f32_16x16x32_bf16 v[100:103], v[208:211], v[170:173], v[100:103]
	v_mfma_f32_16x16x32_bf16 v[96:99], v[232:235], v[170:173], v[96:99]
	v_mfma_f32_16x16x32_bf16 v[84:87], v[208:211], v[192:195], v[84:87]
	v_mfma_f32_16x16x32_bf16 v[80:83], v[232:235], v[192:195], v[80:83]
	v_mfma_f32_16x16x32_bf16 v[68:71], v[208:211], v[200:203], v[68:71]
	v_mfma_f32_16x16x32_bf16 v[64:67], v[232:235], v[200:203], v[64:67]
	s_add_i32 m0, s75, 0xffffff80
	s_barrier
	ds_read_b128 v[154:157], v165 offset:49152
	ds_read_b128 v[166:169], v165 offset:51200
	ds_read_b128 v[188:191], v165 offset:53248
	ds_read_b128 v[196:199], v165 offset:55296
	ds_read_b128 v[158:161], v165 offset:50176
	ds_read_b128 v[170:173], v165 offset:52224
	ds_read_b128 v[192:195], v165 offset:54272
	ds_read_b128 v[200:203], v165 offset:56320
	global_load_lds_dwordx4 v144, s[64:65] offset:128
	s_add_i32 m0, s76, 0xffffff80
	s_nop 0
	global_load_lds_dwordx4 v146, s[64:65] offset:128
	s_barrier
	s_waitcnt lgkmcnt(7)
	v_mfma_f32_16x16x32_bf16 v[60:63], v[128:131], v[154:157], v[60:63]
	v_mfma_f32_16x16x32_bf16 v[56:59], v[136:139], v[154:157], v[56:59]
	s_waitcnt lgkmcnt(6)
	v_mfma_f32_16x16x32_bf16 v[44:47], v[128:131], v[166:169], v[44:47]
	v_mfma_f32_16x16x32_bf16 v[40:43], v[136:139], v[166:169], v[40:43]
	s_waitcnt lgkmcnt(5)
	v_mfma_f32_16x16x32_bf16 v[28:31], v[128:131], v[188:191], v[28:31]
	v_mfma_f32_16x16x32_bf16 v[24:27], v[136:139], v[188:191], v[24:27]
	s_waitcnt lgkmcnt(4)
	v_mfma_f32_16x16x32_bf16 v[12:15], v[128:131], v[196:199], v[12:15]
	v_mfma_f32_16x16x32_bf16 v[8:11], v[136:139], v[196:199], v[8:11]
	s_waitcnt lgkmcnt(3)
	v_mfma_f32_16x16x32_bf16 v[60:63], v[132:135], v[158:161], v[60:63]
	v_mfma_f32_16x16x32_bf16 v[56:59], v[140:143], v[158:161], v[56:59]
	s_waitcnt lgkmcnt(2)
	v_mfma_f32_16x16x32_bf16 v[44:47], v[132:135], v[170:173], v[44:47]
	v_mfma_f32_16x16x32_bf16 v[40:43], v[140:143], v[170:173], v[40:43]
	s_waitcnt lgkmcnt(1)
	v_mfma_f32_16x16x32_bf16 v[28:31], v[132:135], v[192:195], v[28:31]
	v_mfma_f32_16x16x32_bf16 v[24:27], v[140:143], v[192:195], v[24:27]
	s_waitcnt lgkmcnt(0)
	v_mfma_f32_16x16x32_bf16 v[12:15], v[132:135], v[200:203], v[12:15]
	v_mfma_f32_16x16x32_bf16 v[8:11], v[140:143], v[200:203], v[8:11]
	s_barrier
	s_add_u32 s18, s62, 0x18080
	s_addc_u32 s19, s63, 0
	s_add_i32 s28, s29, s68
	s_mov_b32 m0, s28
	s_nop 0
	global_load_lds_dwordx4 v176, s[18:19]
	s_add_i32 m0, s28, 0x2000
	s_nop 0
	global_load_lds_dwordx4 v148, s[18:19]
	s_waitcnt vmcnt(6)
	s_barrier
	v_mfma_f32_16x16x32_bf16 v[52:55], v[204:207], v[154:157], v[52:55]
	v_mfma_f32_16x16x32_bf16 v[48:51], v[212:215], v[154:157], v[48:51]
	v_mfma_f32_16x16x32_bf16 v[36:39], v[204:207], v[166:169], v[36:39]
	v_mfma_f32_16x16x32_bf16 v[32:35], v[212:215], v[166:169], v[32:35]
	v_mfma_f32_16x16x32_bf16 v[20:23], v[204:207], v[188:191], v[20:23]
	v_mfma_f32_16x16x32_bf16 v[16:19], v[212:215], v[188:191], v[16:19]
	v_mfma_f32_16x16x32_bf16 v[4:7], v[204:207], v[196:199], v[4:7]
	v_mfma_f32_16x16x32_bf16 v[0:3], v[212:215], v[196:199], v[0:3]
	v_mfma_f32_16x16x32_bf16 v[52:55], v[208:211], v[158:161], v[52:55]
	v_mfma_f32_16x16x32_bf16 v[48:51], v[232:235], v[158:161], v[48:51]
	v_mfma_f32_16x16x32_bf16 v[36:39], v[208:211], v[170:173], v[36:39]
	v_mfma_f32_16x16x32_bf16 v[32:35], v[232:235], v[170:173], v[32:35]
	v_mfma_f32_16x16x32_bf16 v[20:23], v[208:211], v[192:195], v[20:23]
	v_mfma_f32_16x16x32_bf16 v[16:19], v[232:235], v[192:195], v[16:19]
	v_mfma_f32_16x16x32_bf16 v[4:7], v[208:211], v[200:203], v[4:7]
	v_mfma_f32_16x16x32_bf16 v[0:3], v[232:235], v[200:203], v[0:3]
	s_add_u32 s85, s85, 0x100
	s_addc_u32 s91, s91, 0
	s_cmp_lt_i32 vcc_lo, s67
	s_mov_b64 s[18:19], s[4:5]
	s_mov_b32 s62, vcc_lo
	s_barrier
	s_cbranch_scc1 .LBB0_413
	s_ashr_i32 s4, s66, 2
	v_mov_b32_e32 v128, v163
	v_mov_b32_e32 v166, v162
	s_cmp_eq_u32 s4, 2
	s_cbranch_scc1 .LBB0_416
	s_mul_i32 s13, s4, 0x2280000
	s_mul_hi_i32 s5, s4, 0x2280000
	s_add_u32 s18, s13, 0x5858000
	s_addc_u32 s19, s5, 0
	s_mov_b32 s62, 1.0
	s_branch .LBB0_417

.LBB0_504:
	v_mov_b64_e32 v[0:1], 0x3c6
	s_ashr_i32 s65, s64, 31
	v_cmp_lt_i64_e32 vcc, s[8:9], v[0:1]
	s_lshl_b64 s[8:9], s[64:65], 20
	s_add_u32 s66, s27, s8
	s_addc_u32 s67, s74, s9
	s_and_b64 s[8:9], vcc, exec
	s_cselect_b32 s10, s67, s5
	s_cselect_b32 s11, s66, s4
	s_ashr_i32 s63, s62, 31
	s_lshl_b64 s[8:9], s[62:63], 20
	s_add_u32 s68, s75, s8
	s_addc_u32 s69, s76, s9
	s_and_b64 s[8:9], vcc, exec
	s_cselect_b32 s63, s69, s7
	s_cselect_b32 s65, s68, s6
	s_add_u32 s4, s4, 0x80080
	s_addc_u32 s5, s5, 0
	s_add_u32 s70, s6, 0x100
	v_mov_b64_e32 v[0:1], 0
	v_mov_b64_e32 v[2:3], 0
	v_mov_b64_e32 v[4:5], 0
	v_mov_b64_e32 v[6:7], 0
	v_mov_b64_e32 v[8:9], 0
	v_mov_b64_e32 v[10:11], 0
	v_mov_b64_e32 v[12:13], 0
	v_mov_b64_e32 v[14:15], 0
	v_mov_b64_e32 v[16:17], 0
	v_mov_b64_e32 v[18:19], 0
	v_mov_b64_e32 v[20:21], 0
	v_mov_b64_e32 v[22:23], 0
	v_mov_b64_e32 v[24:25], 0
	v_mov_b64_e32 v[26:27], 0
	v_mov_b64_e32 v[28:29], 0
	v_mov_b64_e32 v[30:31], 0
	v_mov_b64_e32 v[32:33], 0
	v_mov_b64_e32 v[34:35], 0
	v_mov_b64_e32 v[36:37], 0
	v_mov_b64_e32 v[38:39], 0
	v_mov_b64_e32 v[40:41], 0
	v_mov_b64_e32 v[42:43], 0
	v_mov_b64_e32 v[44:45], 0
	v_mov_b64_e32 v[46:47], 0
	v_mov_b64_e32 v[48:49], 0
	v_mov_b64_e32 v[50:51], 0
	v_mov_b64_e32 v[52:53], 0
	v_mov_b64_e32 v[54:55], 0
	v_mov_b64_e32 v[56:57], 0
	v_mov_b64_e32 v[58:59], 0
	v_mov_b64_e32 v[60:61], 0
	v_mov_b64_e32 v[62:63], 0
	v_mov_b64_e32 v[64:65], 0
	v_mov_b64_e32 v[66:67], 0
	v_mov_b64_e32 v[68:69], 0
	v_mov_b64_e32 v[70:71], 0
	v_mov_b64_e32 v[72:73], 0
	v_mov_b64_e32 v[74:75], 0
	v_mov_b64_e32 v[76:77], 0
	v_mov_b64_e32 v[78:79], 0
	v_mov_b64_e32 v[80:81], 0
	v_mov_b64_e32 v[82:83], 0
	v_mov_b64_e32 v[84:85], 0
	v_mov_b64_e32 v[86:87], 0
	v_mov_b64_e32 v[88:89], 0
	v_mov_b64_e32 v[90:91], 0
	v_mov_b64_e32 v[92:93], 0
	v_mov_b64_e32 v[94:95], 0
	v_mov_b64_e32 v[96:97], 0
	v_mov_b64_e32 v[98:99], 0
	v_mov_b64_e32 v[100:101], 0
	v_mov_b64_e32 v[102:103], 0
	v_mov_b64_e32 v[104:105], 0
	v_mov_b64_e32 v[106:107], 0
	v_mov_b64_e32 v[108:109], 0
	v_mov_b64_e32 v[110:111], 0
	v_mov_b64_e32 v[112:113], 0
	v_mov_b64_e32 v[114:115], 0
	v_mov_b64_e32 v[116:117], 0
	v_mov_b64_e32 v[118:119], 0
	v_mov_b64_e32 v[120:121], 0
	v_mov_b64_e32 v[122:123], 0
	v_mov_b64_e32 v[124:125], 0
	v_mov_b64_e32 v[126:127], 0
	s_addc_u32 s71, s7, 0
	s_mov_b32 s72, -2
	v_add_u32_e32 v174, 0x10000, v144
.LBB0_505:
	s_add_u32 s6, s4, 0xfff80080
	s_addc_u32 s7, s5, -1
	s_add_i32 s28, 0, 0x10000
	ds_read_b128 v[138:141], v174
	ds_read_b128 v[146:149], v174 offset:1024
	ds_read_b128 v[150:153], v174 offset:2048
	ds_read_b128 v[154:157], v174 offset:3072
	s_cmp_eq_u32 s72, 28
	s_cselect_b32 s9, s10, s7
	s_cselect_b32 s8, s11, s6
	s_cselect_b32 s7, s63, s71
	s_cselect_b32 s6, s65, s70
	s_add_i32 m0, s17, 0xc000
	ds_read_b128 v[158:161], v145
	ds_read_b128 v[166:169], v145 offset:2048
	ds_read_b128 v[188:191], v145 offset:4096
	ds_read_b128 v[196:199], v145 offset:6144
	ds_read_b128 v[162:165], v145 offset:1024
	ds_read_b128 v[170:173], v145 offset:3072
	ds_read_b128 v[192:195], v145 offset:5120
	ds_read_b128 v[200:203], v145 offset:7168
	global_load_lds_dwordx4 v134, s[4:5]
	s_add_i32 m0, s17, 0xe000
	s_nop 0
	global_load_lds_dwordx4 v136, s[4:5]
	s_waitcnt lgkmcnt(8)
	s_barrier
	s_waitcnt lgkmcnt(7)
	v_mfma_f32_16x16x32_bf16 v[124:127], v[138:141], v[158:161], v[124:127]
	v_mfma_f32_16x16x32_bf16 v[120:123], v[150:153], v[158:161], v[120:123]
	s_waitcnt lgkmcnt(6)
	v_mfma_f32_16x16x32_bf16 v[116:119], v[138:141], v[166:169], v[116:119]
	v_mfma_f32_16x16x32_bf16 v[108:111], v[150:153], v[166:169], v[108:111]
	s_waitcnt lgkmcnt(5)
	v_mfma_f32_16x16x32_bf16 v[100:103], v[138:141], v[188:191], v[100:103]
	v_mfma_f32_16x16x32_bf16 v[92:95], v[150:153], v[188:191], v[92:95]
	s_waitcnt lgkmcnt(4)
	v_mfma_f32_16x16x32_bf16 v[84:87], v[138:141], v[196:199], v[84:87]
	v_mfma_f32_16x16x32_bf16 v[76:79], v[150:153], v[196:199], v[76:79]
	s_waitcnt lgkmcnt(3)
	v_mfma_f32_16x16x32_bf16 v[124:127], v[146:149], v[162:165], v[124:127]
	v_mfma_f32_16x16x32_bf16 v[120:123], v[154:157], v[162:165], v[120:123]
	s_waitcnt lgkmcnt(2)
	v_mfma_f32_16x16x32_bf16 v[116:119], v[146:149], v[170:173], v[116:119]
	v_mfma_f32_16x16x32_bf16 v[108:111], v[154:157], v[170:173], v[108:111]
	s_waitcnt lgkmcnt(1)
	v_mfma_f32_16x16x32_bf16 v[100:103], v[146:149], v[192:195], v[100:103]
	v_mfma_f32_16x16x32_bf16 v[92:95], v[154:157], v[192:195], v[92:95]
	s_waitcnt lgkmcnt(0)
	v_mfma_f32_16x16x32_bf16 v[84:87], v[146:149], v[200:203], v[84:87]
	v_mfma_f32_16x16x32_bf16 v[76:79], v[154:157], v[200:203], v[76:79]
	s_barrier
	s_add_i32 s29, 0, 0x14000
	s_add_i32 s28, s28, s77
	ds_read_b128 v[204:207], v174 offset:16384
	ds_read_b128 v[208:211], v174 offset:17408
	ds_read_b128 v[212:215], v174 offset:18432
	ds_read_b128 v[232:235], v174 offset:19456
	s_mov_b32 m0, s28
	s_nop 0
	global_load_lds_dwordx4 v176, s[6:7]
	s_add_i32 m0, s28, 0x2000
	s_nop 0
	global_load_lds_dwordx4 v132, s[6:7]
	s_barrier
	s_waitcnt lgkmcnt(3)
	v_mfma_f32_16x16x32_bf16 v[112:115], v[204:207], v[158:161], v[112:115]
	s_waitcnt lgkmcnt(1)
	v_mfma_f32_16x16x32_bf16 v[104:107], v[212:215], v[158:161], v[104:107]
	v_mfma_f32_16x16x32_bf16 v[96:99], v[204:207], v[166:169], v[96:99]
	v_mfma_f32_16x16x32_bf16 v[88:91], v[212:215], v[166:169], v[88:91]
	v_mfma_f32_16x16x32_bf16 v[80:83], v[204:207], v[188:191], v[80:83]
	v_mfma_f32_16x16x32_bf16 v[72:75], v[212:215], v[188:191], v[72:75]
	v_mfma_f32_16x16x32_bf16 v[68:71], v[204:207], v[196:199], v[68:71]
	v_mfma_f32_16x16x32_bf16 v[64:67], v[212:215], v[196:199], v[64:67]
	v_mfma_f32_16x16x32_bf16 v[112:115], v[208:211], v[162:165], v[112:115]
	s_waitcnt lgkmcnt(0)
	v_mfma_f32_16x16x32_bf16 v[104:107], v[232:235], v[162:165], v[104:107]
	v_mfma_f32_16x16x32_bf16 v[96:99], v[208:211], v[170:173], v[96:99]
	v_mfma_f32_16x16x32_bf16 v[88:91], v[232:235], v[170:173], v[88:91]
	v_mfma_f32_16x16x32_bf16 v[80:83], v[208:211], v[192:195], v[80:83]
	v_mfma_f32_16x16x32_bf16 v[72:75], v[232:235], v[192:195], v[72:75]
	v_mfma_f32_16x16x32_bf16 v[68:71], v[208:211], v[200:203], v[68:71]
	v_mfma_f32_16x16x32_bf16 v[64:67], v[232:235], v[200:203], v[64:67]
	s_mov_b32 m0, s17
	s_barrier
	ds_read_b128 v[158:161], v145 offset:16384
	ds_read_b128 v[166:169], v145 offset:18432
	ds_read_b128 v[188:191], v145 offset:20480
	ds_read_b128 v[196:199], v145 offset:22528
	ds_read_b128 v[162:165], v145 offset:17408
	ds_read_b128 v[170:173], v145 offset:19456
	ds_read_b128 v[192:195], v145 offset:21504
	ds_read_b128 v[200:203], v145 offset:23552
	global_load_lds_dwordx4 v128, s[8:9]
	s_mov_b32 m0, s19
	s_nop 0
	global_load_lds_dwordx4 v130, s[8:9]
	s_barrier
	s_waitcnt lgkmcnt(7)
	v_mfma_f32_16x16x32_bf16 v[60:63], v[138:141], v[158:161], v[60:63]
	v_mfma_f32_16x16x32_bf16 v[56:59], v[150:153], v[158:161], v[56:59]
	s_waitcnt lgkmcnt(6)
	v_mfma_f32_16x16x32_bf16 v[52:55], v[138:141], v[166:169], v[52:55]
	v_mfma_f32_16x16x32_bf16 v[44:47], v[150:153], v[166:169], v[44:47]
	s_waitcnt lgkmcnt(5)
	v_mfma_f32_16x16x32_bf16 v[36:39], v[138:141], v[188:191], v[36:39]
	v_mfma_f32_16x16x32_bf16 v[28:31], v[150:153], v[188:191], v[28:31]
	s_waitcnt lgkmcnt(4)
	v_mfma_f32_16x16x32_bf16 v[20:23], v[138:141], v[196:199], v[20:23]
	v_mfma_f32_16x16x32_bf16 v[12:15], v[150:153], v[196:199], v[12:15]
	s_waitcnt lgkmcnt(3)
	v_mfma_f32_16x16x32_bf16 v[60:63], v[146:149], v[162:165], v[60:63]
	v_mfma_f32_16x16x32_bf16 v[56:59], v[154:157], v[162:165], v[56:59]
	s_waitcnt lgkmcnt(2)
	v_mfma_f32_16x16x32_bf16 v[52:55], v[146:149], v[170:173], v[52:55]
	v_mfma_f32_16x16x32_bf16 v[44:47], v[154:157], v[170:173], v[44:47]
	s_waitcnt lgkmcnt(1)
	v_mfma_f32_16x16x32_bf16 v[36:39], v[146:149], v[192:195], v[36:39]
	v_mfma_f32_16x16x32_bf16 v[28:31], v[154:157], v[192:195], v[28:31]
	s_waitcnt lgkmcnt(0)
	v_mfma_f32_16x16x32_bf16 v[20:23], v[146:149], v[200:203], v[20:23]
	v_mfma_f32_16x16x32_bf16 v[12:15], v[154:157], v[200:203], v[12:15]
	s_barrier
	s_add_u32 vcc_lo, s6, 0x80000
	s_addc_u32 vcc_hi, s7, 0
	s_add_i32 s28, s29, s77
	s_mov_b32 m0, s28
	s_nop 0
	global_load_lds_dwordx4 v176, vcc
	s_add_i32 m0, s28, 0x2000
	s_nop 0
	global_load_lds_dwordx4 v132, vcc
	s_waitcnt vmcnt(6)
	s_barrier
	v_mfma_f32_16x16x32_bf16 v[48:51], v[204:207], v[158:161], v[48:51]
	v_mfma_f32_16x16x32_bf16 v[40:43], v[212:215], v[158:161], v[40:43]
	v_mfma_f32_16x16x32_bf16 v[32:35], v[204:207], v[166:169], v[32:35]
	v_mfma_f32_16x16x32_bf16 v[24:27], v[212:215], v[166:169], v[24:27]
	v_mfma_f32_16x16x32_bf16 v[16:19], v[204:207], v[188:191], v[16:19]
	v_mfma_f32_16x16x32_bf16 v[8:11], v[212:215], v[188:191], v[8:11]
	v_mfma_f32_16x16x32_bf16 v[4:7], v[204:207], v[196:199], v[4:7]
	v_mfma_f32_16x16x32_bf16 v[0:3], v[212:215], v[196:199], v[0:3]
	v_mfma_f32_16x16x32_bf16 v[48:51], v[208:211], v[162:165], v[48:51]
	v_mfma_f32_16x16x32_bf16 v[40:43], v[232:235], v[162:165], v[40:43]
	v_mfma_f32_16x16x32_bf16 v[32:35], v[208:211], v[170:173], v[32:35]
	v_mfma_f32_16x16x32_bf16 v[24:27], v[232:235], v[170:173], v[24:27]
	v_mfma_f32_16x16x32_bf16 v[16:19], v[208:211], v[192:195], v[16:19]
	v_mfma_f32_16x16x32_bf16 v[8:11], v[232:235], v[192:195], v[8:11]
	v_mfma_f32_16x16x32_bf16 v[4:7], v[208:211], v[200:203], v[4:7]
	v_mfma_f32_16x16x32_bf16 v[0:3], v[232:235], v[200:203], v[0:3]
	s_add_i32 s28, 0, 0x18000
	s_barrier
	ds_read_b128 v[138:141], v174 offset:32768
	ds_read_b128 v[146:149], v174 offset:33792
	ds_read_b128 v[150:153], v174 offset:34816
	ds_read_b128 v[154:157], v174 offset:35840
	s_add_u32 s98, s8, 0x80000
	s_addc_u32 s99, s9, 0
	s_mov_b32 m0, s78
	ds_read_b128 v[158:161], v145 offset:32768
	ds_read_b128 v[166:169], v145 offset:34816
	ds_read_b128 v[188:191], v145 offset:36864
	ds_read_b128 v[196:199], v145 offset:38912
	ds_read_b128 v[162:165], v145 offset:33792
	ds_read_b128 v[170:173], v145 offset:35840
	ds_read_b128 v[192:195], v145 offset:37888
	ds_read_b128 v[200:203], v145 offset:39936
	global_load_lds_dwordx4 v128, s[98:99]
	s_mov_b32 m0, s79
	s_nop 0
	global_load_lds_dwordx4 v130, s[98:99]
	s_waitcnt lgkmcnt(8)
	s_barrier
	s_waitcnt lgkmcnt(7)
	v_mfma_f32_16x16x32_bf16 v[124:127], v[138:141], v[158:161], v[124:127]
	v_mfma_f32_16x16x32_bf16 v[120:123], v[150:153], v[158:161], v[120:123]
	s_waitcnt lgkmcnt(6)
	v_mfma_f32_16x16x32_bf16 v[116:119], v[138:141], v[166:169], v[116:119]
	v_mfma_f32_16x16x32_bf16 v[108:111], v[150:153], v[166:169], v[108:111]
	s_waitcnt lgkmcnt(5)
	v_mfma_f32_16x16x32_bf16 v[100:103], v[138:141], v[188:191], v[100:103]
	v_mfma_f32_16x16x32_bf16 v[92:95], v[150:153], v[188:191], v[92:95]
	s_waitcnt lgkmcnt(4)
	v_mfma_f32_16x16x32_bf16 v[84:87], v[138:141], v[196:199], v[84:87]
	v_mfma_f32_16x16x32_bf16 v[76:79], v[150:153], v[196:199], v[76:79]
	s_waitcnt lgkmcnt(3)
	v_mfma_f32_16x16x32_bf16 v[124:127], v[146:149], v[162:165], v[124:127]
	v_mfma_f32_16x16x32_bf16 v[120:123], v[154:157], v[162:165], v[120:123]
	s_waitcnt lgkmcnt(2)
	v_mfma_f32_16x16x32_bf16 v[116:119], v[146:149], v[170:173], v[116:119]
	v_mfma_f32_16x16x32_bf16 v[108:111], v[154:157], v[170:173], v[108:111]
	s_waitcnt lgkmcnt(1)
	v_mfma_f32_16x16x32_bf16 v[100:103], v[146:149], v[192:195], v[100:103]
	v_mfma_f32_16x16x32_bf16 v[92:95], v[154:157], v[192:195], v[92:95]
	s_waitcnt lgkmcnt(0)
	v_mfma_f32_16x16x32_bf16 v[84:87], v[146:149], v[200:203], v[84:87]
	v_mfma_f32_16x16x32_bf16 v[76:79], v[154:157], v[200:203], v[76:79]
	s_barrier
	s_add_i32 s100, 0, 0x1c000
	s_add_i32 s101, s28, s77
	s_add_i32 m0, s101, 0xffffff80
	ds_read_b128 v[204:207], v174 offset:49152
	ds_read_b128 v[208:211], v174 offset:50176
	ds_read_b128 v[212:215], v174 offset:51200
	ds_read_b128 v[232:235], v174 offset:52224
	global_load_lds_dwordx4 v176, s[6:7] offset:128
	s_add_i32 m0, s101, 0x1f80
	s_nop 0
	global_load_lds_dwordx4 v132, s[6:7] offset:128
	s_barrier
	s_waitcnt lgkmcnt(3)
	v_mfma_f32_16x16x32_bf16 v[112:115], v[204:207], v[158:161], v[112:115]
	s_waitcnt lgkmcnt(1)
	v_mfma_f32_16x16x32_bf16 v[104:107], v[212:215], v[158:161], v[104:107]
	v_mfma_f32_16x16x32_bf16 v[96:99], v[204:207], v[166:169], v[96:99]
	v_mfma_f32_16x16x32_bf16 v[88:91], v[212:215], v[166:169], v[88:91]
	v_mfma_f32_16x16x32_bf16 v[80:83], v[204:207], v[188:191], v[80:83]
	v_mfma_f32_16x16x32_bf16 v[72:75], v[212:215], v[188:191], v[72:75]
	v_mfma_f32_16x16x32_bf16 v[68:71], v[204:207], v[196:199], v[68:71]
	v_mfma_f32_16x16x32_bf16 v[64:67], v[212:215], v[196:199], v[64:67]
	v_mfma_f32_16x16x32_bf16 v[112:115], v[208:211], v[162:165], v[112:115]
	s_waitcnt lgkmcnt(0)
	v_mfma_f32_16x16x32_bf16 v[104:107], v[232:235], v[162:165], v[104:107]
	v_mfma_f32_16x16x32_bf16 v[96:99], v[208:211], v[170:173], v[96:99]
	v_mfma_f32_16x16x32_bf16 v[88:91], v[232:235], v[170:173], v[88:91]
	v_mfma_f32_16x16x32_bf16 v[80:83], v[208:211], v[192:195], v[80:83]
	v_mfma_f32_16x16x32_bf16 v[72:75], v[232:235], v[192:195], v[72:75]
	v_mfma_f32_16x16x32_bf16 v[68:71], v[208:211], v[200:203], v[68:71]
	v_mfma_f32_16x16x32_bf16 v[64:67], v[232:235], v[200:203], v[64:67]
	s_add_i32 m0, s82, 0xffffff80
	s_barrier
	ds_read_b128 v[158:161], v145 offset:49152
	ds_read_b128 v[166:169], v145 offset:51200
	ds_read_b128 v[188:191], v145 offset:53248
	ds_read_b128 v[196:199], v145 offset:55296
	ds_read_b128 v[162:165], v145 offset:50176
	ds_read_b128 v[170:173], v145 offset:52224
	ds_read_b128 v[192:195], v145 offset:54272
	ds_read_b128 v[200:203], v145 offset:56320
	global_load_lds_dwordx4 v128, s[8:9] offset:128
	s_add_i32 m0, s83, 0xffffff80
	s_nop 0
	global_load_lds_dwordx4 v130, s[8:9] offset:128
	s_barrier
	s_waitcnt lgkmcnt(7)
	v_mfma_f32_16x16x32_bf16 v[60:63], v[138:141], v[158:161], v[60:63]
	v_mfma_f32_16x16x32_bf16 v[56:59], v[150:153], v[158:161], v[56:59]
	s_waitcnt lgkmcnt(6)
	v_mfma_f32_16x16x32_bf16 v[52:55], v[138:141], v[166:169], v[52:55]
	v_mfma_f32_16x16x32_bf16 v[44:47], v[150:153], v[166:169], v[44:47]
	s_waitcnt lgkmcnt(5)
	v_mfma_f32_16x16x32_bf16 v[36:39], v[138:141], v[188:191], v[36:39]
	v_mfma_f32_16x16x32_bf16 v[28:31], v[150:153], v[188:191], v[28:31]
	s_waitcnt lgkmcnt(4)
	v_mfma_f32_16x16x32_bf16 v[20:23], v[138:141], v[196:199], v[20:23]
	v_mfma_f32_16x16x32_bf16 v[12:15], v[150:153], v[196:199], v[12:15]
	s_waitcnt lgkmcnt(3)
	v_mfma_f32_16x16x32_bf16 v[60:63], v[146:149], v[162:165], v[60:63]
	v_mfma_f32_16x16x32_bf16 v[56:59], v[154:157], v[162:165], v[56:59]
	s_waitcnt lgkmcnt(2)
	v_mfma_f32_16x16x32_bf16 v[52:55], v[146:149], v[170:173], v[52:55]
	v_mfma_f32_16x16x32_bf16 v[44:47], v[154:157], v[170:173], v[44:47]
	s_waitcnt lgkmcnt(1)
	v_mfma_f32_16x16x32_bf16 v[36:39], v[146:149], v[192:195], v[36:39]
	v_mfma_f32_16x16x32_bf16 v[28:31], v[154:157], v[192:195], v[28:31]
	s_waitcnt lgkmcnt(0)
	v_mfma_f32_16x16x32_bf16 v[20:23], v[146:149], v[200:203], v[20:23]
	v_mfma_f32_16x16x32_bf16 v[12:15], v[154:157], v[200:203], v[12:15]
	s_barrier
	s_add_u32 s6, s6, 0x80080
	s_addc_u32 s7, s7, 0
	s_add_i32 s100, s100, s77
	s_mov_b32 m0, s100
	s_nop 0
	global_load_lds_dwordx4 v176, s[6:7]
	s_add_i32 m0, s100, 0x2000
	s_nop 0
	global_load_lds_dwordx4 v132, s[6:7]
	s_waitcnt vmcnt(6)
	s_barrier
	v_mfma_f32_16x16x32_bf16 v[48:51], v[204:207], v[158:161], v[48:51]
	v_mfma_f32_16x16x32_bf16 v[40:43], v[212:215], v[158:161], v[40:43]
	v_mfma_f32_16x16x32_bf16 v[32:35], v[204:207], v[166:169], v[32:35]
	v_mfma_f32_16x16x32_bf16 v[24:27], v[212:215], v[166:169], v[24:27]
	v_mfma_f32_16x16x32_bf16 v[16:19], v[204:207], v[188:191], v[16:19]
	v_mfma_f32_16x16x32_bf16 v[8:11], v[212:215], v[188:191], v[8:11]
	v_mfma_f32_16x16x32_bf16 v[4:7], v[204:207], v[196:199], v[4:7]
	v_mfma_f32_16x16x32_bf16 v[0:3], v[212:215], v[196:199], v[0:3]
	v_mfma_f32_16x16x32_bf16 v[48:51], v[208:211], v[162:165], v[48:51]
	v_mfma_f32_16x16x32_bf16 v[40:43], v[232:235], v[162:165], v[40:43]
	v_mfma_f32_16x16x32_bf16 v[32:35], v[208:211], v[170:173], v[32:35]
	v_mfma_f32_16x16x32_bf16 v[24:27], v[232:235], v[170:173], v[24:27]
	v_mfma_f32_16x16x32_bf16 v[16:19], v[208:211], v[192:195], v[16:19]
	v_mfma_f32_16x16x32_bf16 v[8:11], v[232:235], v[192:195], v[8:11]
	v_mfma_f32_16x16x32_bf16 v[4:7], v[208:211], v[200:203], v[4:7]
	v_mfma_f32_16x16x32_bf16 v[0:3], v[232:235], v[200:203], v[0:3]
	s_add_i32 s72, s72, 2
	s_add_u32 s4, s4, 0x100
	s_addc_u32 s5, s5, 0
	s_add_u32 s70, s70, 0x100
	s_addc_u32 s71, s71, 0
	s_cmp_lt_u32 s72, 30
	s_barrier
	s_cbranch_scc1 .LBB0_505
	v_mov_b32_e32 v147, v142
	v_mov_b32_e32 v146, v143
	s_cmp_lt_i32 s16, 12
	s_mov_b64 s[4:5], -1
	s_cbranch_scc1 .LBB0_1052
	s_lshl_b32 s4, s18, 8
	s_add_i32 s4, s4, s80
	v_add_u32_e32 v149, s4, v147
	s_lshl_b32 s4, s16, 8
	s_add_i32 s4, s84, s4
	v_lshl_add_u32 v138, v146, 3, s4
	v_mad_i64_i32 v[140:141], s[4:5], v149, s97, 0
	v_cmp_gt_i32_e32 vcc, s34, v138
	s_and_saveexec_b64 s[10:11], vcc
	s_cbranch_execz .LBB0_541
	v_cmp_lt_i32_e64 s[8:9], 63, v138
	v_cmp_gt_u32_e64 s[4:5], s93, v138
	v_cmp_gt_u32_e64 s[6:7], s96, v138
	s_and_saveexec_b64 s[70:71], s[8:9]
	s_xor_b64 s[70:71], exec, s[70:71]
	s_cbranch_execz .LBB0_510
	v_mul_f32_e32 v139, 0xbfb8aa3b, v124
	v_exp_f32_e32 v139, v139
	s_nop 0
	v_add_f32_e32 v139, 1.0, v139
	v_rcp_f32_e32 v139, v139
	s_nop 0
	v_cndmask_b32_e64 v139, 0, v139, s[6:7]
	v_cndmask_b32_e64 v139, v139, v124, s[4:5]
	s_andn2_saveexec_b64 s[70:71], s[70:71]
	s_cbranch_execz .LBB0_512
	s_branch .LBB0_511

.LBB0_1113:
	s_add_i32 s85, s76, -2
	s_add_u32 s64, s64, 0x80
	s_addc_u32 s65, s65, 0
	s_add_u32 s91, s66, 0x100
	v_mov_b64_e32 v[0:1], 0
	v_mov_b64_e32 v[2:3], 0
	v_mov_b64_e32 v[4:5], 0
	v_mov_b64_e32 v[6:7], 0
	v_mov_b64_e32 v[8:9], 0
	v_mov_b64_e32 v[10:11], 0
	v_mov_b64_e32 v[12:13], 0
	v_mov_b64_e32 v[14:15], 0
	v_mov_b64_e32 v[16:17], 0
	v_mov_b64_e32 v[18:19], 0
	v_mov_b64_e32 v[20:21], 0
	v_mov_b64_e32 v[22:23], 0
	v_mov_b64_e32 v[24:25], 0
	v_mov_b64_e32 v[26:27], 0
	v_mov_b64_e32 v[28:29], 0
	v_mov_b64_e32 v[30:31], 0
	v_mov_b64_e32 v[32:33], 0
	v_mov_b64_e32 v[34:35], 0
	v_mov_b64_e32 v[36:37], 0
	v_mov_b64_e32 v[38:39], 0
	v_mov_b64_e32 v[40:41], 0
	v_mov_b64_e32 v[42:43], 0
	v_mov_b64_e32 v[44:45], 0
	v_mov_b64_e32 v[46:47], 0
	v_mov_b64_e32 v[48:49], 0
	v_mov_b64_e32 v[50:51], 0
	v_mov_b64_e32 v[52:53], 0
	v_mov_b64_e32 v[54:55], 0
	v_mov_b64_e32 v[56:57], 0
	v_mov_b64_e32 v[58:59], 0
	v_mov_b64_e32 v[60:61], 0
	v_mov_b64_e32 v[62:63], 0
	v_mov_b64_e32 v[64:65], 0
	v_mov_b64_e32 v[66:67], 0
	v_mov_b64_e32 v[68:69], 0
	v_mov_b64_e32 v[70:71], 0
	v_mov_b64_e32 v[72:73], 0
	v_mov_b64_e32 v[74:75], 0
	v_mov_b64_e32 v[76:77], 0
	v_mov_b64_e32 v[78:79], 0
	v_mov_b64_e32 v[80:81], 0
	v_mov_b64_e32 v[82:83], 0
	v_mov_b64_e32 v[84:85], 0
	v_mov_b64_e32 v[86:87], 0
	v_mov_b64_e32 v[88:89], 0
	v_mov_b64_e32 v[90:91], 0
	v_mov_b64_e32 v[92:93], 0
	v_mov_b64_e32 v[94:95], 0
	v_mov_b64_e32 v[96:97], 0
	v_mov_b64_e32 v[98:99], 0
	v_mov_b64_e32 v[100:101], 0
	v_mov_b64_e32 v[102:103], 0
	v_mov_b64_e32 v[104:105], 0
	v_mov_b64_e32 v[106:107], 0
	v_mov_b64_e32 v[108:109], 0
	v_mov_b64_e32 v[110:111], 0
	v_mov_b64_e32 v[112:113], 0
	v_mov_b64_e32 v[114:115], 0
	v_mov_b64_e32 v[116:117], 0
	v_mov_b64_e32 v[118:119], 0
	v_mov_b64_e32 v[120:121], 0
	v_mov_b64_e32 v[122:123], 0
	v_mov_b64_e32 v[124:125], 0
	v_mov_b64_e32 v[126:127], 0
	s_addc_u32 vcc_lo, s67, 0
	s_mov_b32 s66, 0
	v_add_u32_e32 v174, 0x10000, v194
.LBB0_1114:
	s_add_i32 vcc_hi, s66, 2
	s_add_u32 s28, s64, 0x80
	s_addc_u32 s29, s65, 0
	s_add_i32 s88, 0, 0x10000
	ds_read_b128 v[128:131], v174
	ds_read_b128 v[132:135], v174 offset:1024
	ds_read_b128 v[136:139], v174 offset:2048
	ds_read_b128 v[140:143], v174 offset:3072
	s_cmp_eq_u32 s85, s66
	s_cselect_b32 s66, s4, s28
	s_cselect_b32 s67, s5, s29
	s_cselect_b32 s69, s7, vcc_lo
	s_cselect_b32 s68, s6, s91
	s_add_i32 m0, s70, 0xc000
	ds_read_b128 v[144:147], v195
	ds_read_b128 v[162:165], v195 offset:2048
	ds_read_b128 v[170:173], v195 offset:4096
	ds_read_b128 v[196:199], v195 offset:6144
	ds_read_b128 v[148:151], v195 offset:1024
	ds_read_b128 v[166:169], v195 offset:3072
	ds_read_b128 v[188:191], v195 offset:5120
	ds_read_b128 v[200:203], v195 offset:7168
	global_load_lds_dwordx4 v158, s[64:65]
	s_add_i32 m0, s70, 0xe000
	s_nop 0
	global_load_lds_dwordx4 v160, s[64:65]
	s_waitcnt lgkmcnt(8)
	s_barrier
	s_waitcnt lgkmcnt(7)
	v_mfma_f32_16x16x32_bf16 v[124:127], v[128:131], v[144:147], v[124:127]
	v_mfma_f32_16x16x32_bf16 v[120:123], v[136:139], v[144:147], v[120:123]
	s_waitcnt lgkmcnt(6)
	v_mfma_f32_16x16x32_bf16 v[108:111], v[128:131], v[162:165], v[108:111]
	v_mfma_f32_16x16x32_bf16 v[104:107], v[136:139], v[162:165], v[104:107]
	s_waitcnt lgkmcnt(5)
	v_mfma_f32_16x16x32_bf16 v[92:95], v[128:131], v[170:173], v[92:95]
	v_mfma_f32_16x16x32_bf16 v[88:91], v[136:139], v[170:173], v[88:91]
	s_waitcnt lgkmcnt(4)
	v_mfma_f32_16x16x32_bf16 v[76:79], v[128:131], v[196:199], v[76:79]
	v_mfma_f32_16x16x32_bf16 v[72:75], v[136:139], v[196:199], v[72:75]
	s_waitcnt lgkmcnt(3)
	v_mfma_f32_16x16x32_bf16 v[124:127], v[132:135], v[148:151], v[124:127]
	v_mfma_f32_16x16x32_bf16 v[120:123], v[140:143], v[148:151], v[120:123]
	s_waitcnt lgkmcnt(2)
	v_mfma_f32_16x16x32_bf16 v[108:111], v[132:135], v[166:169], v[108:111]
	v_mfma_f32_16x16x32_bf16 v[104:107], v[140:143], v[166:169], v[104:107]
	s_waitcnt lgkmcnt(1)
	v_mfma_f32_16x16x32_bf16 v[92:95], v[132:135], v[188:191], v[92:95]
	v_mfma_f32_16x16x32_bf16 v[88:91], v[140:143], v[188:191], v[88:91]
	s_waitcnt lgkmcnt(0)
	v_mfma_f32_16x16x32_bf16 v[76:79], v[132:135], v[200:203], v[76:79]
	v_mfma_f32_16x16x32_bf16 v[72:75], v[140:143], v[200:203], v[72:75]
	s_barrier
	s_add_i32 s28, 0, 0x14000
	s_add_i32 s29, s88, s47
	ds_read_b128 v[204:207], v174 offset:16384
	ds_read_b128 v[208:211], v174 offset:17408
	ds_read_b128 v[212:215], v174 offset:18432
	ds_read_b128 v[232:235], v174 offset:19456
	s_mov_b32 m0, s29
	s_nop 0
	global_load_lds_dwordx4 v176, s[68:69]
	s_add_i32 m0, s29, 0x2000
	s_nop 0
	global_load_lds_dwordx4 v156, s[68:69]
	s_barrier
	s_waitcnt lgkmcnt(3)
	v_mfma_f32_16x16x32_bf16 v[116:119], v[204:207], v[144:147], v[116:119]
	s_waitcnt lgkmcnt(1)
	v_mfma_f32_16x16x32_bf16 v[112:115], v[212:215], v[144:147], v[112:115]
	v_mfma_f32_16x16x32_bf16 v[100:103], v[204:207], v[162:165], v[100:103]
	v_mfma_f32_16x16x32_bf16 v[96:99], v[212:215], v[162:165], v[96:99]
	v_mfma_f32_16x16x32_bf16 v[84:87], v[204:207], v[170:173], v[84:87]
	v_mfma_f32_16x16x32_bf16 v[80:83], v[212:215], v[170:173], v[80:83]
	v_mfma_f32_16x16x32_bf16 v[68:71], v[204:207], v[196:199], v[68:71]
	v_mfma_f32_16x16x32_bf16 v[64:67], v[212:215], v[196:199], v[64:67]
	v_mfma_f32_16x16x32_bf16 v[116:119], v[208:211], v[148:151], v[116:119]
	s_waitcnt lgkmcnt(0)
	v_mfma_f32_16x16x32_bf16 v[112:115], v[232:235], v[148:151], v[112:115]
	v_mfma_f32_16x16x32_bf16 v[100:103], v[208:211], v[166:169], v[100:103]
	v_mfma_f32_16x16x32_bf16 v[96:99], v[232:235], v[166:169], v[96:99]
	v_mfma_f32_16x16x32_bf16 v[84:87], v[208:211], v[188:191], v[84:87]
	v_mfma_f32_16x16x32_bf16 v[80:83], v[232:235], v[188:191], v[80:83]
	v_mfma_f32_16x16x32_bf16 v[68:71], v[208:211], v[200:203], v[68:71]
	v_mfma_f32_16x16x32_bf16 v[64:67], v[232:235], v[200:203], v[64:67]
	s_mov_b32 m0, s70
	s_barrier
	ds_read_b128 v[144:147], v195 offset:16384
	ds_read_b128 v[162:165], v195 offset:18432
	ds_read_b128 v[170:173], v195 offset:20480
	ds_read_b128 v[196:199], v195 offset:22528
	ds_read_b128 v[148:151], v195 offset:17408
	ds_read_b128 v[166:169], v195 offset:19456
	ds_read_b128 v[188:191], v195 offset:21504
	ds_read_b128 v[200:203], v195 offset:23552
	global_load_lds_dwordx4 v152, s[66:67]
	s_mov_b32 m0, s71
	s_nop 0
	global_load_lds_dwordx4 v154, s[66:67]
	s_barrier
	s_waitcnt lgkmcnt(7)
	v_mfma_f32_16x16x32_bf16 v[60:63], v[128:131], v[144:147], v[60:63]
	v_mfma_f32_16x16x32_bf16 v[56:59], v[136:139], v[144:147], v[56:59]
	s_waitcnt lgkmcnt(6)
	v_mfma_f32_16x16x32_bf16 v[44:47], v[128:131], v[162:165], v[44:47]
	v_mfma_f32_16x16x32_bf16 v[40:43], v[136:139], v[162:165], v[40:43]
	s_waitcnt lgkmcnt(5)
	v_mfma_f32_16x16x32_bf16 v[28:31], v[128:131], v[170:173], v[28:31]
	v_mfma_f32_16x16x32_bf16 v[24:27], v[136:139], v[170:173], v[24:27]
	s_waitcnt lgkmcnt(4)
	v_mfma_f32_16x16x32_bf16 v[12:15], v[128:131], v[196:199], v[12:15]
	v_mfma_f32_16x16x32_bf16 v[8:11], v[136:139], v[196:199], v[8:11]
	s_waitcnt lgkmcnt(3)
	v_mfma_f32_16x16x32_bf16 v[60:63], v[132:135], v[148:151], v[60:63]
	v_mfma_f32_16x16x32_bf16 v[56:59], v[140:143], v[148:151], v[56:59]
	s_waitcnt lgkmcnt(2)
	v_mfma_f32_16x16x32_bf16 v[44:47], v[132:135], v[166:169], v[44:47]
	v_mfma_f32_16x16x32_bf16 v[40:43], v[140:143], v[166:169], v[40:43]
	s_waitcnt lgkmcnt(1)
	v_mfma_f32_16x16x32_bf16 v[28:31], v[132:135], v[188:191], v[28:31]
	v_mfma_f32_16x16x32_bf16 v[24:27], v[140:143], v[188:191], v[24:27]
	s_waitcnt lgkmcnt(0)
	v_mfma_f32_16x16x32_bf16 v[12:15], v[132:135], v[200:203], v[12:15]
	v_mfma_f32_16x16x32_bf16 v[8:11], v[140:143], v[200:203], v[8:11]
	s_barrier
	s_add_u32 s98, s68, s58
	s_addc_u32 s99, s69, 0
	s_add_i32 s28, s28, s47
	s_mov_b32 m0, s28
	s_nop 0
	global_load_lds_dwordx4 v176, s[98:99]
	s_add_i32 m0, s28, 0x2000
	s_nop 0
	global_load_lds_dwordx4 v156, s[98:99]
	s_waitcnt vmcnt(6)
	s_barrier
	v_mfma_f32_16x16x32_bf16 v[52:55], v[204:207], v[144:147], v[52:55]
	v_mfma_f32_16x16x32_bf16 v[48:51], v[212:215], v[144:147], v[48:51]
	v_mfma_f32_16x16x32_bf16 v[36:39], v[204:207], v[162:165], v[36:39]
	v_mfma_f32_16x16x32_bf16 v[32:35], v[212:215], v[162:165], v[32:35]
	v_mfma_f32_16x16x32_bf16 v[20:23], v[204:207], v[170:173], v[20:23]
	v_mfma_f32_16x16x32_bf16 v[16:19], v[212:215], v[170:173], v[16:19]
	v_mfma_f32_16x16x32_bf16 v[4:7], v[204:207], v[196:199], v[4:7]
	v_mfma_f32_16x16x32_bf16 v[0:3], v[212:215], v[196:199], v[0:3]
	v_mfma_f32_16x16x32_bf16 v[52:55], v[208:211], v[148:151], v[52:55]
	v_mfma_f32_16x16x32_bf16 v[48:51], v[232:235], v[148:151], v[48:51]
	v_mfma_f32_16x16x32_bf16 v[36:39], v[208:211], v[166:169], v[36:39]
	v_mfma_f32_16x16x32_bf16 v[32:35], v[232:235], v[166:169], v[32:35]
	v_mfma_f32_16x16x32_bf16 v[20:23], v[208:211], v[188:191], v[20:23]
	v_mfma_f32_16x16x32_bf16 v[16:19], v[232:235], v[188:191], v[16:19]
	v_mfma_f32_16x16x32_bf16 v[4:7], v[208:211], v[200:203], v[4:7]
	v_mfma_f32_16x16x32_bf16 v[0:3], v[232:235], v[200:203], v[0:3]
	s_add_i32 s28, 0, 0x18000
	s_barrier
	ds_read_b128 v[128:131], v174 offset:32768
	ds_read_b128 v[132:135], v174 offset:33792
	ds_read_b128 v[136:139], v174 offset:34816
	ds_read_b128 v[140:143], v174 offset:35840
	s_add_u32 s100, s66, s58
	s_addc_u32 s101, s67, 0
	s_mov_b32 m0, s72
	ds_read_b128 v[144:147], v195 offset:32768
	ds_read_b128 v[162:165], v195 offset:34816
	ds_read_b128 v[170:173], v195 offset:36864
	ds_read_b128 v[196:199], v195 offset:38912
	ds_read_b128 v[148:151], v195 offset:33792
	ds_read_b128 v[166:169], v195 offset:35840
	ds_read_b128 v[188:191], v195 offset:37888
	ds_read_b128 v[200:203], v195 offset:39936
	global_load_lds_dwordx4 v152, s[100:101]
	s_mov_b32 m0, s73
	s_nop 0
	global_load_lds_dwordx4 v154, s[100:101]
	s_waitcnt lgkmcnt(8)
	s_barrier
	s_waitcnt lgkmcnt(7)
	v_mfma_f32_16x16x32_bf16 v[124:127], v[128:131], v[144:147], v[124:127]
	v_mfma_f32_16x16x32_bf16 v[120:123], v[136:139], v[144:147], v[120:123]
	s_waitcnt lgkmcnt(6)
	v_mfma_f32_16x16x32_bf16 v[108:111], v[128:131], v[162:165], v[108:111]
	v_mfma_f32_16x16x32_bf16 v[104:107], v[136:139], v[162:165], v[104:107]
	s_waitcnt lgkmcnt(5)
	v_mfma_f32_16x16x32_bf16 v[92:95], v[128:131], v[170:173], v[92:95]
	v_mfma_f32_16x16x32_bf16 v[88:91], v[136:139], v[170:173], v[88:91]
	s_waitcnt lgkmcnt(4)
	v_mfma_f32_16x16x32_bf16 v[76:79], v[128:131], v[196:199], v[76:79]
	v_mfma_f32_16x16x32_bf16 v[72:75], v[136:139], v[196:199], v[72:75]
	s_waitcnt lgkmcnt(3)
	v_mfma_f32_16x16x32_bf16 v[124:127], v[132:135], v[148:151], v[124:127]
	v_mfma_f32_16x16x32_bf16 v[120:123], v[140:143], v[148:151], v[120:123]
	s_waitcnt lgkmcnt(2)
	v_mfma_f32_16x16x32_bf16 v[108:111], v[132:135], v[166:169], v[108:111]
	v_mfma_f32_16x16x32_bf16 v[104:107], v[140:143], v[166:169], v[104:107]
	s_waitcnt lgkmcnt(1)
	v_mfma_f32_16x16x32_bf16 v[92:95], v[132:135], v[188:191], v[92:95]
	v_mfma_f32_16x16x32_bf16 v[88:91], v[140:143], v[188:191], v[88:91]
	s_waitcnt lgkmcnt(0)
	v_mfma_f32_16x16x32_bf16 v[76:79], v[132:135], v[200:203], v[76:79]
	v_mfma_f32_16x16x32_bf16 v[72:75], v[140:143], v[200:203], v[72:75]
	s_barrier
	s_add_i32 s29, 0, 0x1c000
	s_add_i32 s28, s28, s47
	s_add_i32 m0, s28, 0xffffff80
	ds_read_b128 v[204:207], v174 offset:49152
	ds_read_b128 v[208:211], v174 offset:50176
	ds_read_b128 v[212:215], v174 offset:51200
	ds_read_b128 v[232:235], v174 offset:52224
	global_load_lds_dwordx4 v176, s[68:69] offset:128
	s_add_i32 m0, s28, 0x1f80
	s_nop 0
	global_load_lds_dwordx4 v156, s[68:69] offset:128
	s_barrier
	s_waitcnt lgkmcnt(3)
	v_mfma_f32_16x16x32_bf16 v[116:119], v[204:207], v[144:147], v[116:119]
	s_waitcnt lgkmcnt(1)
	v_mfma_f32_16x16x32_bf16 v[112:115], v[212:215], v[144:147], v[112:115]
	v_mfma_f32_16x16x32_bf16 v[100:103], v[204:207], v[162:165], v[100:103]
	v_mfma_f32_16x16x32_bf16 v[96:99], v[212:215], v[162:165], v[96:99]
	v_mfma_f32_16x16x32_bf16 v[84:87], v[204:207], v[170:173], v[84:87]
	v_mfma_f32_16x16x32_bf16 v[80:83], v[212:215], v[170:173], v[80:83]
	v_mfma_f32_16x16x32_bf16 v[68:71], v[204:207], v[196:199], v[68:71]
	v_mfma_f32_16x16x32_bf16 v[64:67], v[212:215], v[196:199], v[64:67]
	v_mfma_f32_16x16x32_bf16 v[116:119], v[208:211], v[148:151], v[116:119]
	s_waitcnt lgkmcnt(0)
	v_mfma_f32_16x16x32_bf16 v[112:115], v[232:235], v[148:151], v[112:115]
	v_mfma_f32_16x16x32_bf16 v[100:103], v[208:211], v[166:169], v[100:103]
	v_mfma_f32_16x16x32_bf16 v[96:99], v[232:235], v[166:169], v[96:99]
	v_mfma_f32_16x16x32_bf16 v[84:87], v[208:211], v[188:191], v[84:87]
	v_mfma_f32_16x16x32_bf16 v[80:83], v[232:235], v[188:191], v[80:83]
	v_mfma_f32_16x16x32_bf16 v[68:71], v[208:211], v[200:203], v[68:71]
	v_mfma_f32_16x16x32_bf16 v[64:67], v[232:235], v[200:203], v[64:67]
	s_add_i32 m0, s74, 0xffffff80
	s_barrier
	ds_read_b128 v[144:147], v195 offset:49152
	ds_read_b128 v[162:165], v195 offset:51200
	ds_read_b128 v[170:173], v195 offset:53248
	ds_read_b128 v[196:199], v195 offset:55296
	ds_read_b128 v[148:151], v195 offset:50176
	ds_read_b128 v[166:169], v195 offset:52224
	ds_read_b128 v[188:191], v195 offset:54272
	ds_read_b128 v[200:203], v195 offset:56320
	global_load_lds_dwordx4 v152, s[66:67] offset:128
	s_add_i32 m0, s75, 0xffffff80
	s_nop 0
	global_load_lds_dwordx4 v154, s[66:67] offset:128
	s_barrier
	s_waitcnt lgkmcnt(7)
	v_mfma_f32_16x16x32_bf16 v[60:63], v[128:131], v[144:147], v[60:63]
	v_mfma_f32_16x16x32_bf16 v[56:59], v[136:139], v[144:147], v[56:59]
	s_waitcnt lgkmcnt(6)
	v_mfma_f32_16x16x32_bf16 v[44:47], v[128:131], v[162:165], v[44:47]
	v_mfma_f32_16x16x32_bf16 v[40:43], v[136:139], v[162:165], v[40:43]
	s_waitcnt lgkmcnt(5)
	v_mfma_f32_16x16x32_bf16 v[28:31], v[128:131], v[170:173], v[28:31]
	v_mfma_f32_16x16x32_bf16 v[24:27], v[136:139], v[170:173], v[24:27]
	s_waitcnt lgkmcnt(4)
	v_mfma_f32_16x16x32_bf16 v[12:15], v[128:131], v[196:199], v[12:15]
	v_mfma_f32_16x16x32_bf16 v[8:11], v[136:139], v[196:199], v[8:11]
	s_waitcnt lgkmcnt(3)
	v_mfma_f32_16x16x32_bf16 v[60:63], v[132:135], v[148:151], v[60:63]
	v_mfma_f32_16x16x32_bf16 v[56:59], v[140:143], v[148:151], v[56:59]
	s_waitcnt lgkmcnt(2)
	v_mfma_f32_16x16x32_bf16 v[44:47], v[132:135], v[166:169], v[44:47]
	v_mfma_f32_16x16x32_bf16 v[40:43], v[140:143], v[166:169], v[40:43]
	s_waitcnt lgkmcnt(1)
	v_mfma_f32_16x16x32_bf16 v[28:31], v[132:135], v[188:191], v[28:31]
	v_mfma_f32_16x16x32_bf16 v[24:27], v[140:143], v[188:191], v[24:27]
	s_waitcnt lgkmcnt(0)
	v_mfma_f32_16x16x32_bf16 v[12:15], v[132:135], v[200:203], v[12:15]
	v_mfma_f32_16x16x32_bf16 v[8:11], v[140:143], v[200:203], v[8:11]
	s_barrier
	s_add_i32 s28, s29, s47
	s_add_i32 m0, s28, 0xffffff80
	s_nop 0
	global_load_lds_dwordx4 v176, s[98:99] offset:128
	s_add_i32 m0, s28, 0x1f80
	s_nop 0
	global_load_lds_dwordx4 v156, s[98:99] offset:128
	s_waitcnt vmcnt(6)
	s_barrier
	v_mfma_f32_16x16x32_bf16 v[52:55], v[204:207], v[144:147], v[52:55]
	v_mfma_f32_16x16x32_bf16 v[48:51], v[212:215], v[144:147], v[48:51]
	v_mfma_f32_16x16x32_bf16 v[36:39], v[204:207], v[162:165], v[36:39]
	v_mfma_f32_16x16x32_bf16 v[32:35], v[212:215], v[162:165], v[32:35]
	v_mfma_f32_16x16x32_bf16 v[20:23], v[204:207], v[170:173], v[20:23]
	v_mfma_f32_16x16x32_bf16 v[16:19], v[212:215], v[170:173], v[16:19]
	v_mfma_f32_16x16x32_bf16 v[4:7], v[204:207], v[196:199], v[4:7]
	v_mfma_f32_16x16x32_bf16 v[0:3], v[212:215], v[196:199], v[0:3]
	v_mfma_f32_16x16x32_bf16 v[52:55], v[208:211], v[148:151], v[52:55]
	v_mfma_f32_16x16x32_bf16 v[48:51], v[232:235], v[148:151], v[48:51]
	v_mfma_f32_16x16x32_bf16 v[36:39], v[208:211], v[166:169], v[36:39]
	v_mfma_f32_16x16x32_bf16 v[32:35], v[232:235], v[166:169], v[32:35]
	v_mfma_f32_16x16x32_bf16 v[20:23], v[208:211], v[188:191], v[20:23]
	v_mfma_f32_16x16x32_bf16 v[16:19], v[232:235], v[188:191], v[16:19]
	v_mfma_f32_16x16x32_bf16 v[4:7], v[208:211], v[200:203], v[4:7]
	v_mfma_f32_16x16x32_bf16 v[0:3], v[232:235], v[200:203], v[0:3]
	s_add_u32 s64, s64, 0x100
	s_addc_u32 s65, s65, 0
	s_add_u32 s91, s91, 0x100
	s_addc_u32 vcc_lo, vcc_lo, 0
	s_cmp_lt_i32 vcc_hi, s76
	s_mov_b32 s66, vcc_hi
	s_barrier
	s_cbranch_scc1 .LBB0_1114
	s_lshl_b32 s28, s84, 8
	v_mov_b32_e32 v128, v193
	v_mov_b32_e32 v129, v192
	s_add_i32 s28, s28, s78
	s_lshl_b32 s64, s24, 2
	v_add_u32_e32 v166, s28, v129
	s_lshl_b32 s28, s24, 8
	s_or_b32 s28, s28, s79
	v_lshl_add_u32 v162, v128, 3, s28
	v_ashrrev_i32_e32 v163, 31, v162
	v_lshlrev_b64 v[204:205], 1, v[162:163]
	v_ashrrev_i32_e32 v167, 31, v166
	v_lshl_add_u64 v[164:165], s[12:13], 0, v[204:205]
	v_lshlrev_b64 v[206:207], 11, v[166:167]
	v_cmp_eq_u32_e32 vcc, 0, v128
	v_lshl_add_u64 v[128:129], v[164:165], 0, v[206:207]
	global_load_dwordx4 v[196:199], v[128:129], off
	global_load_dwordx4 v[200:203], v[128:129], off offset:256
	v_add_u32_e32 v188, 16, v166
	v_ashrrev_i32_e32 v189, 31, v188
	v_add_u32_e32 v172, 32, v166
	v_lshlrev_b64 v[190:191], 11, v[188:189]
	v_ashrrev_i32_e32 v173, 31, v172
	v_add_u32_e32 v168, 48, v166
	v_lshl_add_u64 v[128:129], v[164:165], 0, v[190:191]
	v_lshlrev_b64 v[174:175], 11, v[172:173]
	v_ashrrev_i32_e32 v169, 31, v168
	global_load_dwordx4 v[148:151], v[128:129], off
	global_load_dwordx4 v[144:147], v[128:129], off offset:256
	v_lshl_add_u64 v[128:129], v[164:165], 0, v[174:175]
	v_lshlrev_b64 v[170:171], 11, v[168:169]
	global_load_dwordx4 v[140:143], v[128:129], off
	global_load_dwordx4 v[136:139], v[128:129], off offset:256
	v_lshl_add_u64 v[128:129], v[164:165], 0, v[170:171]
	global_load_dwordx4 v[132:135], v[128:129], off
	s_nop 0
	global_load_dwordx4 v[128:131], v[128:129], off offset:256
	v_lshl_add_u64 v[206:207], s[12:13], 0, v[206:207]
	v_lshl_add_u64 v[204:205], v[206:207], 0, v[204:205]
	s_ashr_i32 s65, s64, 31
	s_waitcnt vmcnt(0)
	v_lshlrev_b32_e32 v208, 16, v196
	v_and_b32_e32 v209, 0xffff0000, v196
	v_lshlrev_b32_e32 v196, 16, v197
	v_and_b32_e32 v197, 0xffff0000, v197
	v_lshlrev_b32_e32 v210, 16, v198
	v_and_b32_e32 v211, 0xffff0000, v198
	v_lshlrev_b32_e32 v198, 16, v199
	v_and_b32_e32 v199, 0xffff0000, v199
	v_pk_fma_f32 v[126:127], s[62:63], v[126:127], v[196:197]
	v_pk_fma_f32 v[124:125], s[10:11], v[124:125], v[208:209]
	v_pk_fma_f32 v[196:197], s[62:63], v[122:123], v[198:199]
	v_pk_fma_f32 v[198:199], s[10:11], v[120:121], v[210:211]
	v_cvt_pk_bf16_f32 v120, v124, v125
	v_cvt_pk_bf16_f32 v121, v126, v127
	s_nop 0
	v_cvt_pk_bf16_f32 v122, v198, v199
	v_cvt_pk_bf16_f32 v123, v196, v197
	global_store_dwordx4 v[204:205], v[120:123], off
	s_nop 1
	v_pk_mul_f32 v[120:121], v[198:199], v[198:199]
	v_pk_mul_f32 v[122:123], v[196:197], v[196:197]
	v_pk_fma_f32 v[120:121], v[124:125], v[124:125], v[120:121]
	v_pk_fma_f32 v[122:123], v[126:127], v[126:127], v[122:123]
	v_add_f32_e32 v120, v120, v121
	v_add_f32_e32 v121, v122, v123
	v_add_f32_e32 v196, v120, v121
	v_lshlrev_b32_e32 v120, 16, v200
	v_and_b32_e32 v121, 0xffff0000, v200
	v_lshlrev_b32_e32 v122, 16, v201
	v_and_b32_e32 v123, 0xffff0000, v201
	v_lshlrev_b32_e32 v124, 16, v202
	v_and_b32_e32 v125, 0xffff0000, v202
	v_lshlrev_b32_e32 v126, 16, v203
	v_and_b32_e32 v127, 0xffff0000, v203
	v_pk_fma_f32 v[118:119], s[62:63], v[118:119], v[122:123]
	v_pk_fma_f32 v[116:117], s[10:11], v[116:117], v[120:121]
	v_pk_fma_f32 v[120:121], s[62:63], v[114:115], v[126:127]
	v_pk_fma_f32 v[122:123], s[10:11], v[112:113], v[124:125]
	v_cvt_pk_bf16_f32 v112, v116, v117
	v_cvt_pk_bf16_f32 v113, v118, v119
	s_nop 0
	v_cvt_pk_bf16_f32 v114, v122, v123
	v_cvt_pk_bf16_f32 v115, v120, v121
	global_store_dwordx4 v[204:205], v[112:115], off offset:256
	s_nop 1
	v_pk_mul_f32 v[112:113], v[122:123], v[122:123]
	v_pk_mul_f32 v[114:115], v[120:121], v[120:121]
	v_pk_fma_f32 v[112:113], v[116:117], v[116:117], v[112:113]
	v_pk_fma_f32 v[114:115], v[118:119], v[118:119], v[114:115]
	v_add_f32_e32 v112, v112, v113
	v_add_f32_e32 v113, v114, v115
	v_add_f32_e32 v112, v112, v113
	v_add_f32_e32 v112, v196, v112
	ds_bpermute_b32 v113, v219, v112
	s_waitcnt lgkmcnt(0)
	v_add_f32_e32 v112, v112, v113
	ds_bpermute_b32 v113, v218, v112
	s_and_saveexec_b64 s[66:67], vcc
	s_cbranch_execz .LBB0_1117
	v_lshlrev_b64 v[114:115], 6, v[166:167]
	v_lshl_add_u64 v[114:115], s[8:9], 0, v[114:115]
	v_lshl_add_u64 v[114:115], s[64:65], 2, v[114:115]
	s_lshl_b32 s24, s77, 2
	v_lshl_add_u64 v[114:115], v[114:115], 0, s[24:25]
	s_waitcnt lgkmcnt(0)
	v_add_f32_e32 v112, v112, v113
	global_store_dword v[114:115], v112, off

.LBB0_1281:
	s_add_i32 s5, s79, -2
	s_add_u32 s58, s58, 0x80
	s_addc_u32 s59, s59, 0
	s_add_u32 s21, s60, 0x100
	v_mov_b64_e32 v[0:1], 0
	v_mov_b64_e32 v[2:3], 0
	v_mov_b64_e32 v[4:5], 0
	v_mov_b64_e32 v[6:7], 0
	v_mov_b64_e32 v[8:9], 0
	v_mov_b64_e32 v[10:11], 0
	v_mov_b64_e32 v[12:13], 0
	v_mov_b64_e32 v[14:15], 0
	v_mov_b64_e32 v[16:17], 0
	v_mov_b64_e32 v[18:19], 0
	v_mov_b64_e32 v[20:21], 0
	v_mov_b64_e32 v[22:23], 0
	v_mov_b64_e32 v[24:25], 0
	v_mov_b64_e32 v[26:27], 0
	v_mov_b64_e32 v[28:29], 0
	v_mov_b64_e32 v[30:31], 0
	v_mov_b64_e32 v[32:33], 0
	v_mov_b64_e32 v[34:35], 0
	v_mov_b64_e32 v[36:37], 0
	v_mov_b64_e32 v[38:39], 0
	v_mov_b64_e32 v[40:41], 0
	v_mov_b64_e32 v[42:43], 0
	v_mov_b64_e32 v[44:45], 0
	v_mov_b64_e32 v[46:47], 0
	v_mov_b64_e32 v[48:49], 0
	v_mov_b64_e32 v[50:51], 0
	v_mov_b64_e32 v[52:53], 0
	v_mov_b64_e32 v[54:55], 0
	v_mov_b64_e32 v[56:57], 0
	v_mov_b64_e32 v[58:59], 0
	v_mov_b64_e32 v[60:61], 0
	v_mov_b64_e32 v[62:63], 0
	v_mov_b64_e32 v[64:65], 0
	v_mov_b64_e32 v[66:67], 0
	v_mov_b64_e32 v[68:69], 0
	v_mov_b64_e32 v[70:71], 0
	v_mov_b64_e32 v[72:73], 0
	v_mov_b64_e32 v[74:75], 0
	v_mov_b64_e32 v[76:77], 0
	v_mov_b64_e32 v[78:79], 0
	v_mov_b64_e32 v[80:81], 0
	v_mov_b64_e32 v[82:83], 0
	v_mov_b64_e32 v[84:85], 0
	v_mov_b64_e32 v[86:87], 0
	v_mov_b64_e32 v[88:89], 0
	v_mov_b64_e32 v[90:91], 0
	v_mov_b64_e32 v[92:93], 0
	v_mov_b64_e32 v[94:95], 0
	v_mov_b64_e32 v[96:97], 0
	v_mov_b64_e32 v[98:99], 0
	v_mov_b64_e32 v[100:101], 0
	v_mov_b64_e32 v[102:103], 0
	v_mov_b64_e32 v[104:105], 0
	v_mov_b64_e32 v[106:107], 0
	v_mov_b64_e32 v[108:109], 0
	v_mov_b64_e32 v[110:111], 0
	v_mov_b64_e32 v[112:113], 0
	v_mov_b64_e32 v[114:115], 0
	v_mov_b64_e32 v[116:117], 0
	v_mov_b64_e32 v[118:119], 0
	v_mov_b64_e32 v[120:121], 0
	v_mov_b64_e32 v[122:123], 0
	v_mov_b64_e32 v[124:125], 0
	v_mov_b64_e32 v[126:127], 0
	s_addc_u32 s80, s61, 0
	s_mov_b32 s60, 0
	s_waitcnt lgkmcnt(0)
	v_add_u32_e32 v174, 0x10000, v195
.LBB0_1282:
	s_add_i32 s81, s60, 2
	s_add_u32 s28, s58, 0x80
	s_addc_u32 s29, s59, 0
	s_add_i32 s82, 0, 0x10000
	ds_read_b128 v[128:131], v174
	ds_read_b128 v[132:135], v174 offset:1024
	ds_read_b128 v[136:139], v174 offset:2048
	ds_read_b128 v[140:143], v174 offset:3072
	s_cmp_eq_u32 s5, s60
	s_cselect_b32 s60, s56, s28
	s_cselect_b32 s61, s57, s29
	s_cselect_b32 s63, s3, s80
	s_cselect_b32 s62, s2, s21
	s_add_i32 m0, s66, 0xc000
	ds_read_b128 v[144:147], v196
	ds_read_b128 v[162:165], v196 offset:2048
	ds_read_b128 v[170:173], v196 offset:4096
	ds_read_b128 v[198:201], v196 offset:6144
	ds_read_b128 v[148:151], v196 offset:1024
	ds_read_b128 v[166:169], v196 offset:3072
	ds_read_b128 v[188:191], v196 offset:5120
	ds_read_b128 v[202:205], v196 offset:7168
	global_load_lds_dwordx4 v158, s[58:59]
	s_add_i32 m0, s66, 0xe000
	s_nop 0
	global_load_lds_dwordx4 v160, s[58:59]
	s_waitcnt lgkmcnt(8)
	s_barrier
	s_waitcnt lgkmcnt(7)
	v_mfma_f32_16x16x32_bf16 v[124:127], v[128:131], v[144:147], v[124:127]
	v_mfma_f32_16x16x32_bf16 v[120:123], v[136:139], v[144:147], v[120:123]
	s_waitcnt lgkmcnt(6)
	v_mfma_f32_16x16x32_bf16 v[108:111], v[128:131], v[162:165], v[108:111]
	v_mfma_f32_16x16x32_bf16 v[104:107], v[136:139], v[162:165], v[104:107]
	s_waitcnt lgkmcnt(5)
	v_mfma_f32_16x16x32_bf16 v[92:95], v[128:131], v[170:173], v[92:95]
	v_mfma_f32_16x16x32_bf16 v[88:91], v[136:139], v[170:173], v[88:91]
	s_waitcnt lgkmcnt(4)
	v_mfma_f32_16x16x32_bf16 v[76:79], v[128:131], v[198:201], v[76:79]
	v_mfma_f32_16x16x32_bf16 v[72:75], v[136:139], v[198:201], v[72:75]
	s_waitcnt lgkmcnt(3)
	v_mfma_f32_16x16x32_bf16 v[124:127], v[132:135], v[148:151], v[124:127]
	v_mfma_f32_16x16x32_bf16 v[120:123], v[140:143], v[148:151], v[120:123]
	s_waitcnt lgkmcnt(2)
	v_mfma_f32_16x16x32_bf16 v[108:111], v[132:135], v[166:169], v[108:111]
	v_mfma_f32_16x16x32_bf16 v[104:107], v[140:143], v[166:169], v[104:107]
	s_waitcnt lgkmcnt(1)
	v_mfma_f32_16x16x32_bf16 v[92:95], v[132:135], v[188:191], v[92:95]
	v_mfma_f32_16x16x32_bf16 v[88:91], v[140:143], v[188:191], v[88:91]
	s_waitcnt lgkmcnt(0)
	v_mfma_f32_16x16x32_bf16 v[76:79], v[132:135], v[202:205], v[76:79]
	v_mfma_f32_16x16x32_bf16 v[72:75], v[140:143], v[202:205], v[72:75]
	s_barrier
	s_add_i32 s28, 0, 0x14000
	s_add_i32 s29, s82, s65
	ds_read_b128 v[206:209], v174 offset:16384
	ds_read_b128 v[210:213], v174 offset:17408
	ds_read_b128 v[214:217], v174 offset:18432
	ds_read_b128 v[232:235], v174 offset:19456
	s_mov_b32 m0, s29
	s_nop 0
	global_load_lds_dwordx4 v176, s[62:63]
	s_add_i32 m0, s29, 0x2000
	s_nop 0
	global_load_lds_dwordx4 v156, s[62:63]
	s_barrier
	s_waitcnt lgkmcnt(3)
	v_mfma_f32_16x16x32_bf16 v[116:119], v[206:209], v[144:147], v[116:119]
	s_waitcnt lgkmcnt(1)
	v_mfma_f32_16x16x32_bf16 v[112:115], v[214:217], v[144:147], v[112:115]
	v_mfma_f32_16x16x32_bf16 v[100:103], v[206:209], v[162:165], v[100:103]
	v_mfma_f32_16x16x32_bf16 v[96:99], v[214:217], v[162:165], v[96:99]
	v_mfma_f32_16x16x32_bf16 v[84:87], v[206:209], v[170:173], v[84:87]
	v_mfma_f32_16x16x32_bf16 v[80:83], v[214:217], v[170:173], v[80:83]
	v_mfma_f32_16x16x32_bf16 v[68:71], v[206:209], v[198:201], v[68:71]
	v_mfma_f32_16x16x32_bf16 v[64:67], v[214:217], v[198:201], v[64:67]
	v_mfma_f32_16x16x32_bf16 v[116:119], v[210:213], v[148:151], v[116:119]
	s_waitcnt lgkmcnt(0)
	v_mfma_f32_16x16x32_bf16 v[112:115], v[232:235], v[148:151], v[112:115]
	v_mfma_f32_16x16x32_bf16 v[100:103], v[210:213], v[166:169], v[100:103]
	v_mfma_f32_16x16x32_bf16 v[96:99], v[232:235], v[166:169], v[96:99]
	v_mfma_f32_16x16x32_bf16 v[84:87], v[210:213], v[188:191], v[84:87]
	v_mfma_f32_16x16x32_bf16 v[80:83], v[232:235], v[188:191], v[80:83]
	v_mfma_f32_16x16x32_bf16 v[68:71], v[210:213], v[202:205], v[68:71]
	v_mfma_f32_16x16x32_bf16 v[64:67], v[232:235], v[202:205], v[64:67]
	s_mov_b32 m0, s66
	s_barrier
	ds_read_b128 v[144:147], v196 offset:16384
	ds_read_b128 v[162:165], v196 offset:18432
	ds_read_b128 v[170:173], v196 offset:20480
	ds_read_b128 v[198:201], v196 offset:22528
	ds_read_b128 v[148:151], v196 offset:17408
	ds_read_b128 v[166:169], v196 offset:19456
	ds_read_b128 v[188:191], v196 offset:21504
	ds_read_b128 v[202:205], v196 offset:23552
	global_load_lds_dwordx4 v152, s[60:61]
	s_mov_b32 m0, s67
	s_nop 0
	global_load_lds_dwordx4 v154, s[60:61]
	s_barrier
	s_waitcnt lgkmcnt(7)
	v_mfma_f32_16x16x32_bf16 v[60:63], v[128:131], v[144:147], v[60:63]
	v_mfma_f32_16x16x32_bf16 v[56:59], v[136:139], v[144:147], v[56:59]
	s_waitcnt lgkmcnt(6)
	v_mfma_f32_16x16x32_bf16 v[44:47], v[128:131], v[162:165], v[44:47]
	v_mfma_f32_16x16x32_bf16 v[40:43], v[136:139], v[162:165], v[40:43]
	s_waitcnt lgkmcnt(5)
	v_mfma_f32_16x16x32_bf16 v[28:31], v[128:131], v[170:173], v[28:31]
	v_mfma_f32_16x16x32_bf16 v[24:27], v[136:139], v[170:173], v[24:27]
	s_waitcnt lgkmcnt(4)
	v_mfma_f32_16x16x32_bf16 v[12:15], v[128:131], v[198:201], v[12:15]
	v_mfma_f32_16x16x32_bf16 v[8:11], v[136:139], v[198:201], v[8:11]
	s_waitcnt lgkmcnt(3)
	v_mfma_f32_16x16x32_bf16 v[60:63], v[132:135], v[148:151], v[60:63]
	v_mfma_f32_16x16x32_bf16 v[56:59], v[140:143], v[148:151], v[56:59]
	s_waitcnt lgkmcnt(2)
	v_mfma_f32_16x16x32_bf16 v[44:47], v[132:135], v[166:169], v[44:47]
	v_mfma_f32_16x16x32_bf16 v[40:43], v[140:143], v[166:169], v[40:43]
	s_waitcnt lgkmcnt(1)
	v_mfma_f32_16x16x32_bf16 v[28:31], v[132:135], v[188:191], v[28:31]
	v_mfma_f32_16x16x32_bf16 v[24:27], v[140:143], v[188:191], v[24:27]
	s_waitcnt lgkmcnt(0)
	v_mfma_f32_16x16x32_bf16 v[12:15], v[132:135], v[202:205], v[12:15]
	v_mfma_f32_16x16x32_bf16 v[8:11], v[140:143], v[202:205], v[8:11]
	s_barrier
	s_add_u32 s98, s62, s4
	s_addc_u32 s99, s63, 0
	s_add_i32 s28, s28, s65
	s_mov_b32 m0, s28
	s_nop 0
	global_load_lds_dwordx4 v176, s[98:99]
	s_add_i32 m0, s28, 0x2000
	s_nop 0
	global_load_lds_dwordx4 v156, s[98:99]
	s_waitcnt vmcnt(6)
	s_barrier
	v_mfma_f32_16x16x32_bf16 v[52:55], v[206:209], v[144:147], v[52:55]
	v_mfma_f32_16x16x32_bf16 v[48:51], v[214:217], v[144:147], v[48:51]
	v_mfma_f32_16x16x32_bf16 v[36:39], v[206:209], v[162:165], v[36:39]
	v_mfma_f32_16x16x32_bf16 v[32:35], v[214:217], v[162:165], v[32:35]
	v_mfma_f32_16x16x32_bf16 v[20:23], v[206:209], v[170:173], v[20:23]
	v_mfma_f32_16x16x32_bf16 v[16:19], v[214:217], v[170:173], v[16:19]
	v_mfma_f32_16x16x32_bf16 v[4:7], v[206:209], v[198:201], v[4:7]
	v_mfma_f32_16x16x32_bf16 v[0:3], v[214:217], v[198:201], v[0:3]
	v_mfma_f32_16x16x32_bf16 v[52:55], v[210:213], v[148:151], v[52:55]
	v_mfma_f32_16x16x32_bf16 v[48:51], v[232:235], v[148:151], v[48:51]
	v_mfma_f32_16x16x32_bf16 v[36:39], v[210:213], v[166:169], v[36:39]
	v_mfma_f32_16x16x32_bf16 v[32:35], v[232:235], v[166:169], v[32:35]
	v_mfma_f32_16x16x32_bf16 v[20:23], v[210:213], v[188:191], v[20:23]
	v_mfma_f32_16x16x32_bf16 v[16:19], v[232:235], v[188:191], v[16:19]
	v_mfma_f32_16x16x32_bf16 v[4:7], v[210:213], v[202:205], v[4:7]
	v_mfma_f32_16x16x32_bf16 v[0:3], v[232:235], v[202:205], v[0:3]
	s_add_i32 s28, 0, 0x18000
	s_barrier
	ds_read_b128 v[128:131], v174 offset:32768
	ds_read_b128 v[132:135], v174 offset:33792
	ds_read_b128 v[136:139], v174 offset:34816
	ds_read_b128 v[140:143], v174 offset:35840
	s_add_u32 s100, s60, s4
	s_addc_u32 s101, s61, 0
	s_mov_b32 m0, s68
	ds_read_b128 v[144:147], v196 offset:32768
	ds_read_b128 v[162:165], v196 offset:34816
	ds_read_b128 v[170:173], v196 offset:36864
	ds_read_b128 v[198:201], v196 offset:38912
	ds_read_b128 v[148:151], v196 offset:33792
	ds_read_b128 v[166:169], v196 offset:35840
	ds_read_b128 v[188:191], v196 offset:37888
	ds_read_b128 v[202:205], v196 offset:39936
	global_load_lds_dwordx4 v152, s[100:101]
	s_mov_b32 m0, s69
	s_nop 0
	global_load_lds_dwordx4 v154, s[100:101]
	s_waitcnt lgkmcnt(8)
	s_barrier
	s_waitcnt lgkmcnt(7)
	v_mfma_f32_16x16x32_bf16 v[124:127], v[128:131], v[144:147], v[124:127]
	v_mfma_f32_16x16x32_bf16 v[120:123], v[136:139], v[144:147], v[120:123]
	s_waitcnt lgkmcnt(6)
	v_mfma_f32_16x16x32_bf16 v[108:111], v[128:131], v[162:165], v[108:111]
	v_mfma_f32_16x16x32_bf16 v[104:107], v[136:139], v[162:165], v[104:107]
	s_waitcnt lgkmcnt(5)
	v_mfma_f32_16x16x32_bf16 v[92:95], v[128:131], v[170:173], v[92:95]
	v_mfma_f32_16x16x32_bf16 v[88:91], v[136:139], v[170:173], v[88:91]
	s_waitcnt lgkmcnt(4)
	v_mfma_f32_16x16x32_bf16 v[76:79], v[128:131], v[198:201], v[76:79]
	v_mfma_f32_16x16x32_bf16 v[72:75], v[136:139], v[198:201], v[72:75]
	s_waitcnt lgkmcnt(3)
	v_mfma_f32_16x16x32_bf16 v[124:127], v[132:135], v[148:151], v[124:127]
	v_mfma_f32_16x16x32_bf16 v[120:123], v[140:143], v[148:151], v[120:123]
	s_waitcnt lgkmcnt(2)
	v_mfma_f32_16x16x32_bf16 v[108:111], v[132:135], v[166:169], v[108:111]
	v_mfma_f32_16x16x32_bf16 v[104:107], v[140:143], v[166:169], v[104:107]
	s_waitcnt lgkmcnt(1)
	v_mfma_f32_16x16x32_bf16 v[92:95], v[132:135], v[188:191], v[92:95]
	v_mfma_f32_16x16x32_bf16 v[88:91], v[140:143], v[188:191], v[88:91]
	s_waitcnt lgkmcnt(0)
	v_mfma_f32_16x16x32_bf16 v[76:79], v[132:135], v[202:205], v[76:79]
	v_mfma_f32_16x16x32_bf16 v[72:75], v[140:143], v[202:205], v[72:75]
	s_barrier
	s_add_i32 s29, 0, 0x1c000
	s_add_i32 s28, s28, s65
	s_add_i32 m0, s28, 0xffffff80
	ds_read_b128 v[206:209], v174 offset:49152
	ds_read_b128 v[210:213], v174 offset:50176
	ds_read_b128 v[214:217], v174 offset:51200
	ds_read_b128 v[232:235], v174 offset:52224
	global_load_lds_dwordx4 v176, s[62:63] offset:128
	s_add_i32 m0, s28, 0x1f80
	s_nop 0
	global_load_lds_dwordx4 v156, s[62:63] offset:128
	s_barrier
	s_waitcnt lgkmcnt(3)
	v_mfma_f32_16x16x32_bf16 v[116:119], v[206:209], v[144:147], v[116:119]
	s_waitcnt lgkmcnt(1)
	v_mfma_f32_16x16x32_bf16 v[112:115], v[214:217], v[144:147], v[112:115]
	v_mfma_f32_16x16x32_bf16 v[100:103], v[206:209], v[162:165], v[100:103]
	v_mfma_f32_16x16x32_bf16 v[96:99], v[214:217], v[162:165], v[96:99]
	v_mfma_f32_16x16x32_bf16 v[84:87], v[206:209], v[170:173], v[84:87]
	v_mfma_f32_16x16x32_bf16 v[80:83], v[214:217], v[170:173], v[80:83]
	v_mfma_f32_16x16x32_bf16 v[68:71], v[206:209], v[198:201], v[68:71]
	v_mfma_f32_16x16x32_bf16 v[64:67], v[214:217], v[198:201], v[64:67]
	v_mfma_f32_16x16x32_bf16 v[116:119], v[210:213], v[148:151], v[116:119]
	s_waitcnt lgkmcnt(0)
	v_mfma_f32_16x16x32_bf16 v[112:115], v[232:235], v[148:151], v[112:115]
	v_mfma_f32_16x16x32_bf16 v[100:103], v[210:213], v[166:169], v[100:103]
	v_mfma_f32_16x16x32_bf16 v[96:99], v[232:235], v[166:169], v[96:99]
	v_mfma_f32_16x16x32_bf16 v[84:87], v[210:213], v[188:191], v[84:87]
	v_mfma_f32_16x16x32_bf16 v[80:83], v[232:235], v[188:191], v[80:83]
	v_mfma_f32_16x16x32_bf16 v[68:71], v[210:213], v[202:205], v[68:71]
	v_mfma_f32_16x16x32_bf16 v[64:67], v[232:235], v[202:205], v[64:67]
	s_add_i32 m0, s71, 0xffffff80
	s_barrier
	ds_read_b128 v[144:147], v196 offset:49152
	ds_read_b128 v[162:165], v196 offset:51200
	ds_read_b128 v[170:173], v196 offset:53248
	ds_read_b128 v[198:201], v196 offset:55296
	ds_read_b128 v[148:151], v196 offset:50176
	ds_read_b128 v[166:169], v196 offset:52224
	ds_read_b128 v[188:191], v196 offset:54272
	ds_read_b128 v[202:205], v196 offset:56320
	global_load_lds_dwordx4 v152, s[60:61] offset:128
	s_add_i32 m0, s72, 0xffffff80
	s_nop 0
	global_load_lds_dwordx4 v154, s[60:61] offset:128
	s_barrier
	s_waitcnt lgkmcnt(7)
	v_mfma_f32_16x16x32_bf16 v[60:63], v[128:131], v[144:147], v[60:63]
	v_mfma_f32_16x16x32_bf16 v[56:59], v[136:139], v[144:147], v[56:59]
	s_waitcnt lgkmcnt(6)
	v_mfma_f32_16x16x32_bf16 v[44:47], v[128:131], v[162:165], v[44:47]
	v_mfma_f32_16x16x32_bf16 v[40:43], v[136:139], v[162:165], v[40:43]
	s_waitcnt lgkmcnt(5)
	v_mfma_f32_16x16x32_bf16 v[28:31], v[128:131], v[170:173], v[28:31]
	v_mfma_f32_16x16x32_bf16 v[24:27], v[136:139], v[170:173], v[24:27]
	s_waitcnt lgkmcnt(4)
	v_mfma_f32_16x16x32_bf16 v[12:15], v[128:131], v[198:201], v[12:15]
	v_mfma_f32_16x16x32_bf16 v[8:11], v[136:139], v[198:201], v[8:11]
	s_waitcnt lgkmcnt(3)
	v_mfma_f32_16x16x32_bf16 v[60:63], v[132:135], v[148:151], v[60:63]
	v_mfma_f32_16x16x32_bf16 v[56:59], v[140:143], v[148:151], v[56:59]
	s_waitcnt lgkmcnt(2)
	v_mfma_f32_16x16x32_bf16 v[44:47], v[132:135], v[166:169], v[44:47]
	v_mfma_f32_16x16x32_bf16 v[40:43], v[140:143], v[166:169], v[40:43]
	s_waitcnt lgkmcnt(1)
	v_mfma_f32_16x16x32_bf16 v[28:31], v[132:135], v[188:191], v[28:31]
	v_mfma_f32_16x16x32_bf16 v[24:27], v[140:143], v[188:191], v[24:27]
	s_waitcnt lgkmcnt(0)
	v_mfma_f32_16x16x32_bf16 v[12:15], v[132:135], v[202:205], v[12:15]
	v_mfma_f32_16x16x32_bf16 v[8:11], v[140:143], v[202:205], v[8:11]
	s_barrier
	s_add_i32 s28, s29, s65
	s_add_i32 m0, s28, 0xffffff80
	s_nop 0
	global_load_lds_dwordx4 v176, s[98:99] offset:128
	s_add_i32 m0, s28, 0x1f80
	s_nop 0
	global_load_lds_dwordx4 v156, s[98:99] offset:128
	s_waitcnt vmcnt(6)
	s_barrier
	v_mfma_f32_16x16x32_bf16 v[52:55], v[206:209], v[144:147], v[52:55]
	v_mfma_f32_16x16x32_bf16 v[48:51], v[214:217], v[144:147], v[48:51]
	v_mfma_f32_16x16x32_bf16 v[36:39], v[206:209], v[162:165], v[36:39]
	v_mfma_f32_16x16x32_bf16 v[32:35], v[214:217], v[162:165], v[32:35]
	v_mfma_f32_16x16x32_bf16 v[20:23], v[206:209], v[170:173], v[20:23]
	v_mfma_f32_16x16x32_bf16 v[16:19], v[214:217], v[170:173], v[16:19]
	v_mfma_f32_16x16x32_bf16 v[4:7], v[206:209], v[198:201], v[4:7]
	v_mfma_f32_16x16x32_bf16 v[0:3], v[214:217], v[198:201], v[0:3]
	v_mfma_f32_16x16x32_bf16 v[52:55], v[210:213], v[148:151], v[52:55]
	v_mfma_f32_16x16x32_bf16 v[48:51], v[232:235], v[148:151], v[48:51]
	v_mfma_f32_16x16x32_bf16 v[36:39], v[210:213], v[166:169], v[36:39]
	v_mfma_f32_16x16x32_bf16 v[32:35], v[232:235], v[166:169], v[32:35]
	v_mfma_f32_16x16x32_bf16 v[20:23], v[210:213], v[188:191], v[20:23]
	v_mfma_f32_16x16x32_bf16 v[16:19], v[232:235], v[188:191], v[16:19]
	v_mfma_f32_16x16x32_bf16 v[4:7], v[210:213], v[202:205], v[4:7]
	v_mfma_f32_16x16x32_bf16 v[0:3], v[232:235], v[202:205], v[0:3]
	s_add_u32 s58, s58, 0x100
	s_addc_u32 s59, s59, 0
	s_add_u32 s21, s21, 0x100
	s_addc_u32 s80, s80, 0
	s_cmp_ge_i32 s81, s79
	s_mov_b32 s60, s81
	s_barrier
	s_cbranch_scc0 .LBB0_1282
	s_cmp_gt_i32 s24, -1
	s_mov_b64 s[58:59], -1
	s_cbranch_scc0 .LBB0_1285
	s_lshl_b64 s[58:59], s[24:25], 17
	v_mov_b32_e32 v128, v231
	s_add_u32 s58, s37, s58
	s_addc_u32 s59, s46, s59
	v_ashrrev_i32_e32 v129, 31, v128
	v_lshl_add_u64 v[128:129], v[128:129], 4, s[58:59]
	v_add_co_u32_e32 v134, vcc, s36, v128
	v_cvt_pk_bf16_f32 v130, v124, v125
	v_cvt_pk_bf16_f32 v131, v126, v127
	v_cvt_pk_bf16_f32 v132, v120, v121
	v_cvt_pk_bf16_f32 v133, v122, v123
	s_nop 1
	v_addc_co_u32_e32 v135, vcc, 0, v129, vcc
	s_movk_i32 s5, 0x4000
	global_store_dwordx4 v[128:129], v[130:133], off
	s_mov_b64 s[58:59], 0
	s_nop 0
	v_cvt_pk_bf16_f32 v130, v108, v109
	v_cvt_pk_bf16_f32 v131, v110, v111
	v_cvt_pk_bf16_f32 v132, v104, v105
	v_cvt_pk_bf16_f32 v133, v106, v107
	global_store_dwordx4 v[134:135], v[130:133], off
	v_add_co_u32_e32 v134, vcc, s5, v128
	s_movk_i32 s5, 0x6000
	s_nop 0
	v_addc_co_u32_e32 v135, vcc, 0, v129, vcc
	v_cvt_pk_bf16_f32 v130, v92, v93
	v_cvt_pk_bf16_f32 v131, v94, v95
	v_cvt_pk_bf16_f32 v132, v88, v89
	v_cvt_pk_bf16_f32 v133, v90, v91
	global_store_dwordx4 v[134:135], v[130:133], off
	v_add_co_u32_e32 v134, vcc, s5, v128
	s_nop 0
	v_cvt_pk_bf16_f32 v130, v76, v77
	v_cvt_pk_bf16_f32 v131, v78, v79
	v_cvt_pk_bf16_f32 v132, v72, v73
	v_cvt_pk_bf16_f32 v133, v74, v75
	s_nop 0
	v_addc_co_u32_e32 v135, vcc, 0, v129, vcc
	global_store_dwordx4 v[134:135], v[130:133], off
	v_add_co_u32_e32 v134, vcc, s92, v128
	s_mov_b32 s5, 0xa000
	s_nop 0
	v_addc_co_u32_e32 v135, vcc, 0, v129, vcc
	v_cvt_pk_bf16_f32 v130, v116, v117
	v_cvt_pk_bf16_f32 v131, v118, v119
	v_cvt_pk_bf16_f32 v132, v112, v113
	v_cvt_pk_bf16_f32 v133, v114, v115
	global_store_dwordx4 v[134:135], v[130:133], off
	v_add_co_u32_e32 v134, vcc, s5, v128
	s_mov_b32 s5, 0xc000
	s_nop 0
	v_addc_co_u32_e32 v135, vcc, 0, v129, vcc
	v_cvt_pk_bf16_f32 v130, v100, v101
	v_cvt_pk_bf16_f32 v131, v102, v103
	v_cvt_pk_bf16_f32 v132, v96, v97
	v_cvt_pk_bf16_f32 v133, v98, v99
	global_store_dwordx4 v[134:135], v[130:133], off
	v_add_co_u32_e32 v134, vcc, s5, v128
	s_mov_b32 s5, 0xe000
	s_nop 0
	v_addc_co_u32_e32 v135, vcc, 0, v129, vcc
	v_cvt_pk_bf16_f32 v130, v84, v85
	v_cvt_pk_bf16_f32 v131, v86, v87
	v_cvt_pk_bf16_f32 v132, v80, v81
	v_cvt_pk_bf16_f32 v133, v82, v83
	global_store_dwordx4 v[134:135], v[130:133], off
	v_add_co_u32_e32 v134, vcc, s5, v128
	s_mov_b32 s5, 0x10000
	s_nop 0
	v_addc_co_u32_e32 v135, vcc, 0, v129, vcc
	v_cvt_pk_bf16_f32 v130, v68, v69
	v_cvt_pk_bf16_f32 v131, v70, v71
	v_cvt_pk_bf16_f32 v132, v64, v65
	v_cvt_pk_bf16_f32 v133, v66, v67
	global_store_dwordx4 v[134:135], v[130:133], off
	v_add_co_u32_e32 v134, vcc, s5, v128
	s_mov_b32 s5, 0x12000
	s_nop 0
	v_addc_co_u32_e32 v135, vcc, 0, v129, vcc
	v_cvt_pk_bf16_f32 v130, v60, v61
	v_cvt_pk_bf16_f32 v131, v62, v63
	v_cvt_pk_bf16_f32 v132, v56, v57
	v_cvt_pk_bf16_f32 v133, v58, v59
	global_store_dwordx4 v[134:135], v[130:133], off
	v_add_co_u32_e32 v134, vcc, s5, v128
	s_mov_b32 s5, 0x14000
	s_nop 0
	v_addc_co_u32_e32 v135, vcc, 0, v129, vcc
	v_cvt_pk_bf16_f32 v130, v44, v45
	v_cvt_pk_bf16_f32 v131, v46, v47
	v_cvt_pk_bf16_f32 v132, v40, v41
	v_cvt_pk_bf16_f32 v133, v42, v43
	global_store_dwordx4 v[134:135], v[130:133], off
	v_add_co_u32_e32 v134, vcc, s5, v128
	s_mov_b32 s5, 0x16000
	s_nop 0
	v_addc_co_u32_e32 v135, vcc, 0, v129, vcc
	v_cvt_pk_bf16_f32 v130, v28, v29
	v_cvt_pk_bf16_f32 v131, v30, v31
	v_cvt_pk_bf16_f32 v132, v24, v25
	v_cvt_pk_bf16_f32 v133, v26, v27
	global_store_dwordx4 v[134:135], v[130:133], off
	v_add_co_u32_e32 v134, vcc, s5, v128
	s_mov_b32 s5, 0x18000
	s_nop 0
	v_addc_co_u32_e32 v135, vcc, 0, v129, vcc
	v_cvt_pk_bf16_f32 v130, v12, v13
	v_cvt_pk_bf16_f32 v131, v14, v15
	v_cvt_pk_bf16_f32 v132, v8, v9
	v_cvt_pk_bf16_f32 v133, v10, v11
	global_store_dwordx4 v[134:135], v[130:133], off
	v_add_co_u32_e32 v134, vcc, s5, v128
	s_mov_b32 s5, 0x1a000
	s_nop 0
	v_addc_co_u32_e32 v135, vcc, 0, v129, vcc
	v_cvt_pk_bf16_f32 v130, v52, v53
	v_cvt_pk_bf16_f32 v131, v54, v55
	v_cvt_pk_bf16_f32 v132, v48, v49
	v_cvt_pk_bf16_f32 v133, v50, v51
	global_store_dwordx4 v[134:135], v[130:133], off
	v_add_co_u32_e32 v134, vcc, s5, v128
	s_mov_b32 s5, 0x1c000
	s_nop 0
	v_addc_co_u32_e32 v135, vcc, 0, v129, vcc
	v_cvt_pk_bf16_f32 v130, v36, v37
	v_cvt_pk_bf16_f32 v131, v38, v39
	v_cvt_pk_bf16_f32 v132, v32, v33
	v_cvt_pk_bf16_f32 v133, v34, v35
	global_store_dwordx4 v[134:135], v[130:133], off
	v_add_co_u32_e32 v134, vcc, s5, v128
	s_nop 0
	v_cvt_pk_bf16_f32 v130, v20, v21
	v_cvt_pk_bf16_f32 v131, v22, v23
	v_cvt_pk_bf16_f32 v132, v16, v17
	v_cvt_pk_bf16_f32 v133, v18, v19
	s_nop 0
	v_addc_co_u32_e32 v135, vcc, 0, v129, vcc
	v_add_co_u32_e32 v128, vcc, 0x1e000, v128
	global_store_dwordx4 v[134:135], v[130:133], off
	s_nop 0
	v_addc_co_u32_e32 v129, vcc, 0, v129, vcc
	v_cvt_pk_bf16_f32 v130, v4, v5
	v_cvt_pk_bf16_f32 v131, v6, v7
	v_cvt_pk_bf16_f32 v132, v0, v1
	v_cvt_pk_bf16_f32 v133, v2, v3
	global_store_dwordx4 v[128:129], v[130:133], off

.LBB0_1435:
	s_ashr_i32 s17, s16, 31
	v_cmp_lt_i64_e32 vcc, s[18:19], v[186:187]
	s_lshl_b64 s[18:19], s[16:17], 19
	s_add_u32 s18, s47, s18
	s_addc_u32 s19, s54, s19
	s_and_b64 s[20:21], vcc, exec
	s_cselect_b32 s17, s19, s7
	s_cselect_b32 s66, s18, s6
	s_ashr_i32 s13, s12, 31
	s_lshl_b64 s[20:21], s[12:13], 19
	s_add_u32 s20, s37, s20
	s_addc_u32 s21, s46, s21
	s_and_b64 s[52:53], vcc, exec
	s_cselect_b32 s13, s21, s51
	s_cselect_b32 s67, s20, s50
	s_add_u32 s6, s6, 0x40080
	s_addc_u32 s7, s7, 0
	s_add_u32 s68, s50, 0x100
	v_mov_b64_e32 v[0:1], 0
	v_mov_b64_e32 v[2:3], 0
	v_mov_b64_e32 v[4:5], 0
	v_mov_b64_e32 v[6:7], 0
	v_mov_b64_e32 v[8:9], 0
	v_mov_b64_e32 v[10:11], 0
	v_mov_b64_e32 v[12:13], 0
	v_mov_b64_e32 v[14:15], 0
	v_mov_b64_e32 v[16:17], 0
	v_mov_b64_e32 v[18:19], 0
	v_mov_b64_e32 v[20:21], 0
	v_mov_b64_e32 v[22:23], 0
	v_mov_b64_e32 v[24:25], 0
	v_mov_b64_e32 v[26:27], 0
	v_mov_b64_e32 v[28:29], 0
	v_mov_b64_e32 v[30:31], 0
	v_mov_b64_e32 v[32:33], 0
	v_mov_b64_e32 v[34:35], 0
	v_mov_b64_e32 v[36:37], 0
	v_mov_b64_e32 v[38:39], 0
	v_mov_b64_e32 v[40:41], 0
	v_mov_b64_e32 v[42:43], 0
	v_mov_b64_e32 v[44:45], 0
	v_mov_b64_e32 v[46:47], 0
	v_mov_b64_e32 v[48:49], 0
	v_mov_b64_e32 v[50:51], 0
	v_mov_b64_e32 v[52:53], 0
	v_mov_b64_e32 v[54:55], 0
	v_mov_b64_e32 v[56:57], 0
	v_mov_b64_e32 v[58:59], 0
	v_mov_b64_e32 v[60:61], 0
	v_mov_b64_e32 v[62:63], 0
	v_mov_b64_e32 v[64:65], 0
	v_mov_b64_e32 v[66:67], 0
	v_mov_b64_e32 v[68:69], 0
	v_mov_b64_e32 v[70:71], 0
	v_mov_b64_e32 v[72:73], 0
	v_mov_b64_e32 v[74:75], 0
	v_mov_b64_e32 v[76:77], 0
	v_mov_b64_e32 v[78:79], 0
	v_mov_b64_e32 v[80:81], 0
	v_mov_b64_e32 v[82:83], 0
	v_mov_b64_e32 v[84:85], 0
	v_mov_b64_e32 v[86:87], 0
	v_mov_b64_e32 v[88:89], 0
	v_mov_b64_e32 v[90:91], 0
	v_mov_b64_e32 v[92:93], 0
	v_mov_b64_e32 v[94:95], 0
	v_mov_b64_e32 v[96:97], 0
	v_mov_b64_e32 v[98:99], 0
	v_mov_b64_e32 v[100:101], 0
	v_mov_b64_e32 v[102:103], 0
	v_mov_b64_e32 v[104:105], 0
	v_mov_b64_e32 v[106:107], 0
	v_mov_b64_e32 v[108:109], 0
	v_mov_b64_e32 v[110:111], 0
	v_mov_b64_e32 v[112:113], 0
	v_mov_b64_e32 v[114:115], 0
	v_mov_b64_e32 v[116:117], 0
	v_mov_b64_e32 v[118:119], 0
	v_mov_b64_e32 v[120:121], 0
	v_mov_b64_e32 v[122:123], 0
	v_mov_b64_e32 v[124:125], 0
	v_mov_b64_e32 v[126:127], 0
	s_addc_u32 s69, s51, 0
	s_mov_b32 s70, -2
	v_add_u32_e32 v174, 0x10000, v200
.LBB0_1436:
	s_add_u32 s28, s6, 0xfffc0080
	s_addc_u32 s29, s7, -1
	s_add_i32 s71, 0, 0x10000
	ds_read_b128 v[128:131], v174
	ds_read_b128 v[132:135], v174 offset:1024
	ds_read_b128 v[136:139], v174 offset:2048
	ds_read_b128 v[140:143], v174 offset:3072
	s_cmp_eq_u32 s70, 12
	s_cselect_b32 s53, s17, s29
	s_cselect_b32 s52, s66, s28
	s_cselect_b32 s51, s13, s69
	s_cselect_b32 s50, s67, s68
	s_add_i32 m0, s56, 0xc000
	ds_read_b128 v[144:147], v201
	ds_read_b128 v[152:155], v201 offset:2048
	ds_read_b128 v[170:173], v201 offset:4096
	ds_read_b128 v[192:195], v201 offset:6144
	ds_read_b128 v[148:151], v201 offset:1024
	ds_read_b128 v[166:169], v201 offset:3072
	ds_read_b128 v[188:191], v201 offset:5120
	ds_read_b128 v[202:205], v201 offset:7168
	global_load_lds_dwordx4 v162, s[6:7]
	s_add_i32 m0, s56, 0xe000
	s_nop 0
	global_load_lds_dwordx4 v164, s[6:7]
	s_waitcnt lgkmcnt(8)
	s_barrier
	s_waitcnt lgkmcnt(7)
	v_mfma_f32_16x16x32_bf16 v[124:127], v[128:131], v[144:147], v[124:127]
	v_mfma_f32_16x16x32_bf16 v[116:119], v[136:139], v[144:147], v[116:119]
	s_waitcnt lgkmcnt(6)
	v_mfma_f32_16x16x32_bf16 v[108:111], v[128:131], v[152:155], v[108:111]
	v_mfma_f32_16x16x32_bf16 v[100:103], v[136:139], v[152:155], v[100:103]
	s_waitcnt lgkmcnt(5)
	v_mfma_f32_16x16x32_bf16 v[92:95], v[128:131], v[170:173], v[92:95]
	v_mfma_f32_16x16x32_bf16 v[84:87], v[136:139], v[170:173], v[84:87]
	s_waitcnt lgkmcnt(4)
	v_mfma_f32_16x16x32_bf16 v[76:79], v[128:131], v[192:195], v[76:79]
	v_mfma_f32_16x16x32_bf16 v[68:71], v[136:139], v[192:195], v[68:71]
	s_waitcnt lgkmcnt(3)
	v_mfma_f32_16x16x32_bf16 v[124:127], v[132:135], v[148:151], v[124:127]
	v_mfma_f32_16x16x32_bf16 v[116:119], v[140:143], v[148:151], v[116:119]
	s_waitcnt lgkmcnt(2)
	v_mfma_f32_16x16x32_bf16 v[108:111], v[132:135], v[166:169], v[108:111]
	v_mfma_f32_16x16x32_bf16 v[100:103], v[140:143], v[166:169], v[100:103]
	s_waitcnt lgkmcnt(1)
	v_mfma_f32_16x16x32_bf16 v[92:95], v[132:135], v[188:191], v[92:95]
	v_mfma_f32_16x16x32_bf16 v[84:87], v[140:143], v[188:191], v[84:87]
	s_waitcnt lgkmcnt(0)
	v_mfma_f32_16x16x32_bf16 v[76:79], v[132:135], v[202:205], v[76:79]
	v_mfma_f32_16x16x32_bf16 v[68:71], v[140:143], v[202:205], v[68:71]
	s_barrier
	s_add_i32 s28, 0, 0x14000
	s_add_i32 s29, s71, s55
	ds_read_b128 v[206:209], v174 offset:16384
	ds_read_b128 v[210:213], v174 offset:17408
	ds_read_b128 v[214:217], v174 offset:18432
	ds_read_b128 v[232:235], v174 offset:19456
	s_mov_b32 m0, s29
	s_nop 0
	global_load_lds_dwordx4 v176, s[50:51]
	s_add_i32 m0, s29, 0x2000
	s_nop 0
	global_load_lds_dwordx4 v160, s[50:51]
	s_barrier
	s_waitcnt lgkmcnt(3)
	v_mfma_f32_16x16x32_bf16 v[120:123], v[206:209], v[144:147], v[120:123]
	s_waitcnt lgkmcnt(1)
	v_mfma_f32_16x16x32_bf16 v[112:115], v[214:217], v[144:147], v[112:115]
	v_mfma_f32_16x16x32_bf16 v[104:107], v[206:209], v[152:155], v[104:107]
	v_mfma_f32_16x16x32_bf16 v[96:99], v[214:217], v[152:155], v[96:99]
	v_mfma_f32_16x16x32_bf16 v[88:91], v[206:209], v[170:173], v[88:91]
	v_mfma_f32_16x16x32_bf16 v[80:83], v[214:217], v[170:173], v[80:83]
	v_mfma_f32_16x16x32_bf16 v[72:75], v[206:209], v[192:195], v[72:75]
	v_mfma_f32_16x16x32_bf16 v[64:67], v[214:217], v[192:195], v[64:67]
	v_mfma_f32_16x16x32_bf16 v[120:123], v[210:213], v[148:151], v[120:123]
	s_waitcnt lgkmcnt(0)
	v_mfma_f32_16x16x32_bf16 v[112:115], v[232:235], v[148:151], v[112:115]
	v_mfma_f32_16x16x32_bf16 v[104:107], v[210:213], v[166:169], v[104:107]
	v_mfma_f32_16x16x32_bf16 v[96:99], v[232:235], v[166:169], v[96:99]
	v_mfma_f32_16x16x32_bf16 v[88:91], v[210:213], v[188:191], v[88:91]
	v_mfma_f32_16x16x32_bf16 v[80:83], v[232:235], v[188:191], v[80:83]
	v_mfma_f32_16x16x32_bf16 v[72:75], v[210:213], v[202:205], v[72:75]
	v_mfma_f32_16x16x32_bf16 v[64:67], v[232:235], v[202:205], v[64:67]
	s_mov_b32 m0, s56
	s_barrier
	ds_read_b128 v[144:147], v201 offset:16384
	ds_read_b128 v[152:155], v201 offset:18432
	ds_read_b128 v[170:173], v201 offset:20480
	ds_read_b128 v[192:195], v201 offset:22528
	ds_read_b128 v[148:151], v201 offset:17408
	ds_read_b128 v[166:169], v201 offset:19456
	ds_read_b128 v[188:191], v201 offset:21504
	ds_read_b128 v[202:205], v201 offset:23552
	global_load_lds_dwordx4 v156, s[52:53]
	s_mov_b32 m0, s57
	s_nop 0
	global_load_lds_dwordx4 v158, s[52:53]
	s_barrier
	s_waitcnt lgkmcnt(7)
	v_mfma_f32_16x16x32_bf16 v[60:63], v[128:131], v[144:147], v[60:63]
	v_mfma_f32_16x16x32_bf16 v[52:55], v[136:139], v[144:147], v[52:55]
	s_waitcnt lgkmcnt(6)
	v_mfma_f32_16x16x32_bf16 v[44:47], v[128:131], v[152:155], v[44:47]
	v_mfma_f32_16x16x32_bf16 v[36:39], v[136:139], v[152:155], v[36:39]
	s_waitcnt lgkmcnt(5)
	v_mfma_f32_16x16x32_bf16 v[28:31], v[128:131], v[170:173], v[28:31]
	v_mfma_f32_16x16x32_bf16 v[20:23], v[136:139], v[170:173], v[20:23]
	s_waitcnt lgkmcnt(4)
	v_mfma_f32_16x16x32_bf16 v[12:15], v[128:131], v[192:195], v[12:15]
	v_mfma_f32_16x16x32_bf16 v[4:7], v[136:139], v[192:195], v[4:7]
	s_waitcnt lgkmcnt(3)
	v_mfma_f32_16x16x32_bf16 v[60:63], v[132:135], v[148:151], v[60:63]
	v_mfma_f32_16x16x32_bf16 v[52:55], v[140:143], v[148:151], v[52:55]
	s_waitcnt lgkmcnt(2)
	v_mfma_f32_16x16x32_bf16 v[44:47], v[132:135], v[166:169], v[44:47]
	v_mfma_f32_16x16x32_bf16 v[36:39], v[140:143], v[166:169], v[36:39]
	s_waitcnt lgkmcnt(1)
	v_mfma_f32_16x16x32_bf16 v[28:31], v[132:135], v[188:191], v[28:31]
	v_mfma_f32_16x16x32_bf16 v[20:23], v[140:143], v[188:191], v[20:23]
	s_waitcnt lgkmcnt(0)
	v_mfma_f32_16x16x32_bf16 v[12:15], v[132:135], v[202:205], v[12:15]
	v_mfma_f32_16x16x32_bf16 v[4:7], v[140:143], v[202:205], v[4:7]
	s_barrier
	s_add_u32 s72, s50, 0x40000
	s_addc_u32 s73, s51, 0
	s_add_i32 s28, s28, s55
	s_mov_b32 m0, s28
	s_nop 0
	global_load_lds_dwordx4 v176, s[72:73]
	s_add_i32 m0, s28, 0x2000
	s_nop 0
	global_load_lds_dwordx4 v160, s[72:73]
	s_waitcnt vmcnt(6)
	s_barrier
	v_mfma_f32_16x16x32_bf16 v[56:59], v[206:209], v[144:147], v[56:59]
	v_mfma_f32_16x16x32_bf16 v[48:51], v[214:217], v[144:147], v[48:51]
	v_mfma_f32_16x16x32_bf16 v[40:43], v[206:209], v[152:155], v[40:43]
	v_mfma_f32_16x16x32_bf16 v[32:35], v[214:217], v[152:155], v[32:35]
	v_mfma_f32_16x16x32_bf16 v[24:27], v[206:209], v[170:173], v[24:27]
	v_mfma_f32_16x16x32_bf16 v[16:19], v[214:217], v[170:173], v[16:19]
	v_mfma_f32_16x16x32_bf16 v[8:11], v[206:209], v[192:195], v[8:11]
	v_mfma_f32_16x16x32_bf16 v[0:3], v[214:217], v[192:195], v[0:3]
	v_mfma_f32_16x16x32_bf16 v[56:59], v[210:213], v[148:151], v[56:59]
	v_mfma_f32_16x16x32_bf16 v[48:51], v[232:235], v[148:151], v[48:51]
	v_mfma_f32_16x16x32_bf16 v[40:43], v[210:213], v[166:169], v[40:43]
	v_mfma_f32_16x16x32_bf16 v[32:35], v[232:235], v[166:169], v[32:35]
	v_mfma_f32_16x16x32_bf16 v[24:27], v[210:213], v[188:191], v[24:27]
	v_mfma_f32_16x16x32_bf16 v[16:19], v[232:235], v[188:191], v[16:19]
	v_mfma_f32_16x16x32_bf16 v[8:11], v[210:213], v[202:205], v[8:11]
	v_mfma_f32_16x16x32_bf16 v[0:3], v[232:235], v[202:205], v[0:3]
	s_add_i32 s28, 0, 0x18000
	s_barrier
	ds_read_b128 v[128:131], v174 offset:32768
	ds_read_b128 v[132:135], v174 offset:33792
	ds_read_b128 v[136:139], v174 offset:34816
	ds_read_b128 v[140:143], v174 offset:35840
	s_add_u32 s98, s52, 0x40000
	s_addc_u32 s99, s53, 0
	s_mov_b32 m0, s58
	ds_read_b128 v[144:147], v201 offset:32768
	ds_read_b128 v[152:155], v201 offset:34816
	ds_read_b128 v[170:173], v201 offset:36864
	ds_read_b128 v[192:195], v201 offset:38912
	ds_read_b128 v[148:151], v201 offset:33792
	ds_read_b128 v[166:169], v201 offset:35840
	ds_read_b128 v[188:191], v201 offset:37888
	ds_read_b128 v[202:205], v201 offset:39936
	global_load_lds_dwordx4 v156, s[98:99]
	s_mov_b32 m0, s59
	s_nop 0
	global_load_lds_dwordx4 v158, s[98:99]
	s_waitcnt lgkmcnt(8)
	s_barrier
	s_waitcnt lgkmcnt(7)
	v_mfma_f32_16x16x32_bf16 v[124:127], v[128:131], v[144:147], v[124:127]
	v_mfma_f32_16x16x32_bf16 v[116:119], v[136:139], v[144:147], v[116:119]
	s_waitcnt lgkmcnt(6)
	v_mfma_f32_16x16x32_bf16 v[108:111], v[128:131], v[152:155], v[108:111]
	v_mfma_f32_16x16x32_bf16 v[100:103], v[136:139], v[152:155], v[100:103]
	s_waitcnt lgkmcnt(5)
	v_mfma_f32_16x16x32_bf16 v[92:95], v[128:131], v[170:173], v[92:95]
	v_mfma_f32_16x16x32_bf16 v[84:87], v[136:139], v[170:173], v[84:87]
	s_waitcnt lgkmcnt(4)
	v_mfma_f32_16x16x32_bf16 v[76:79], v[128:131], v[192:195], v[76:79]
	v_mfma_f32_16x16x32_bf16 v[68:71], v[136:139], v[192:195], v[68:71]
	s_waitcnt lgkmcnt(3)
	v_mfma_f32_16x16x32_bf16 v[124:127], v[132:135], v[148:151], v[124:127]
	v_mfma_f32_16x16x32_bf16 v[116:119], v[140:143], v[148:151], v[116:119]
	s_waitcnt lgkmcnt(2)
	v_mfma_f32_16x16x32_bf16 v[108:111], v[132:135], v[166:169], v[108:111]
	v_mfma_f32_16x16x32_bf16 v[100:103], v[140:143], v[166:169], v[100:103]
	s_waitcnt lgkmcnt(1)
	v_mfma_f32_16x16x32_bf16 v[92:95], v[132:135], v[188:191], v[92:95]
	v_mfma_f32_16x16x32_bf16 v[84:87], v[140:143], v[188:191], v[84:87]
	s_waitcnt lgkmcnt(0)
	v_mfma_f32_16x16x32_bf16 v[76:79], v[132:135], v[202:205], v[76:79]
	v_mfma_f32_16x16x32_bf16 v[68:71], v[140:143], v[202:205], v[68:71]
	s_barrier
	s_add_i32 s29, 0, 0x1c000
	s_add_i32 s28, s28, s55
	s_add_i32 m0, s28, 0xffffff80
	ds_read_b128 v[206:209], v174 offset:49152
	ds_read_b128 v[210:213], v174 offset:50176
	ds_read_b128 v[214:217], v174 offset:51200
	ds_read_b128 v[232:235], v174 offset:52224
	global_load_lds_dwordx4 v176, s[50:51] offset:128
	s_add_i32 m0, s28, 0x1f80
	s_nop 0
	global_load_lds_dwordx4 v160, s[50:51] offset:128
	s_barrier
	s_waitcnt lgkmcnt(3)
	v_mfma_f32_16x16x32_bf16 v[120:123], v[206:209], v[144:147], v[120:123]
	s_waitcnt lgkmcnt(1)
	v_mfma_f32_16x16x32_bf16 v[112:115], v[214:217], v[144:147], v[112:115]
	v_mfma_f32_16x16x32_bf16 v[104:107], v[206:209], v[152:155], v[104:107]
	v_mfma_f32_16x16x32_bf16 v[96:99], v[214:217], v[152:155], v[96:99]
	v_mfma_f32_16x16x32_bf16 v[88:91], v[206:209], v[170:173], v[88:91]
	v_mfma_f32_16x16x32_bf16 v[80:83], v[214:217], v[170:173], v[80:83]
	v_mfma_f32_16x16x32_bf16 v[72:75], v[206:209], v[192:195], v[72:75]
	v_mfma_f32_16x16x32_bf16 v[64:67], v[214:217], v[192:195], v[64:67]
	v_mfma_f32_16x16x32_bf16 v[120:123], v[210:213], v[148:151], v[120:123]
	s_waitcnt lgkmcnt(0)
	v_mfma_f32_16x16x32_bf16 v[112:115], v[232:235], v[148:151], v[112:115]
	v_mfma_f32_16x16x32_bf16 v[104:107], v[210:213], v[166:169], v[104:107]
	v_mfma_f32_16x16x32_bf16 v[96:99], v[232:235], v[166:169], v[96:99]
	v_mfma_f32_16x16x32_bf16 v[88:91], v[210:213], v[188:191], v[88:91]
	v_mfma_f32_16x16x32_bf16 v[80:83], v[232:235], v[188:191], v[80:83]
	v_mfma_f32_16x16x32_bf16 v[72:75], v[210:213], v[202:205], v[72:75]
	v_mfma_f32_16x16x32_bf16 v[64:67], v[232:235], v[202:205], v[64:67]
	s_add_i32 m0, s62, 0xffffff80
	s_barrier
	ds_read_b128 v[144:147], v201 offset:49152
	ds_read_b128 v[152:155], v201 offset:51200
	ds_read_b128 v[170:173], v201 offset:53248
	ds_read_b128 v[192:195], v201 offset:55296
	ds_read_b128 v[148:151], v201 offset:50176
	ds_read_b128 v[166:169], v201 offset:52224
	ds_read_b128 v[188:191], v201 offset:54272
	ds_read_b128 v[202:205], v201 offset:56320
	global_load_lds_dwordx4 v156, s[52:53] offset:128
	s_add_i32 m0, s63, 0xffffff80
	s_nop 0
	global_load_lds_dwordx4 v158, s[52:53] offset:128
	s_barrier
	s_waitcnt lgkmcnt(7)
	v_mfma_f32_16x16x32_bf16 v[60:63], v[128:131], v[144:147], v[60:63]
	v_mfma_f32_16x16x32_bf16 v[52:55], v[136:139], v[144:147], v[52:55]
	s_waitcnt lgkmcnt(6)
	v_mfma_f32_16x16x32_bf16 v[44:47], v[128:131], v[152:155], v[44:47]
	v_mfma_f32_16x16x32_bf16 v[36:39], v[136:139], v[152:155], v[36:39]
	s_waitcnt lgkmcnt(5)
	v_mfma_f32_16x16x32_bf16 v[28:31], v[128:131], v[170:173], v[28:31]
	v_mfma_f32_16x16x32_bf16 v[20:23], v[136:139], v[170:173], v[20:23]
	s_waitcnt lgkmcnt(4)
	v_mfma_f32_16x16x32_bf16 v[12:15], v[128:131], v[192:195], v[12:15]
	v_mfma_f32_16x16x32_bf16 v[4:7], v[136:139], v[192:195], v[4:7]
	s_waitcnt lgkmcnt(3)
	v_mfma_f32_16x16x32_bf16 v[60:63], v[132:135], v[148:151], v[60:63]
	v_mfma_f32_16x16x32_bf16 v[52:55], v[140:143], v[148:151], v[52:55]
	s_waitcnt lgkmcnt(2)
	v_mfma_f32_16x16x32_bf16 v[44:47], v[132:135], v[166:169], v[44:47]
	v_mfma_f32_16x16x32_bf16 v[36:39], v[140:143], v[166:169], v[36:39]
	s_waitcnt lgkmcnt(1)
	v_mfma_f32_16x16x32_bf16 v[28:31], v[132:135], v[188:191], v[28:31]
	v_mfma_f32_16x16x32_bf16 v[20:23], v[140:143], v[188:191], v[20:23]
	s_waitcnt lgkmcnt(0)
	v_mfma_f32_16x16x32_bf16 v[12:15], v[132:135], v[202:205], v[12:15]
	v_mfma_f32_16x16x32_bf16 v[4:7], v[140:143], v[202:205], v[4:7]
	s_barrier
	s_add_u32 s50, s50, 0x40080
	s_addc_u32 s51, s51, 0
	s_add_i32 s28, s29, s55
	s_mov_b32 m0, s28
	s_nop 0
	global_load_lds_dwordx4 v176, s[50:51]
	s_add_i32 m0, s28, 0x2000
	s_nop 0
	global_load_lds_dwordx4 v160, s[50:51]
	s_waitcnt vmcnt(6)
	s_barrier
	v_mfma_f32_16x16x32_bf16 v[56:59], v[206:209], v[144:147], v[56:59]
	v_mfma_f32_16x16x32_bf16 v[48:51], v[214:217], v[144:147], v[48:51]
	v_mfma_f32_16x16x32_bf16 v[40:43], v[206:209], v[152:155], v[40:43]
	v_mfma_f32_16x16x32_bf16 v[32:35], v[214:217], v[152:155], v[32:35]
	v_mfma_f32_16x16x32_bf16 v[24:27], v[206:209], v[170:173], v[24:27]
	v_mfma_f32_16x16x32_bf16 v[16:19], v[214:217], v[170:173], v[16:19]
	v_mfma_f32_16x16x32_bf16 v[8:11], v[206:209], v[192:195], v[8:11]
	v_mfma_f32_16x16x32_bf16 v[0:3], v[214:217], v[192:195], v[0:3]
	v_mfma_f32_16x16x32_bf16 v[56:59], v[210:213], v[148:151], v[56:59]
	v_mfma_f32_16x16x32_bf16 v[48:51], v[232:235], v[148:151], v[48:51]
	v_mfma_f32_16x16x32_bf16 v[40:43], v[210:213], v[166:169], v[40:43]
	v_mfma_f32_16x16x32_bf16 v[32:35], v[232:235], v[166:169], v[32:35]
	v_mfma_f32_16x16x32_bf16 v[24:27], v[210:213], v[188:191], v[24:27]
	v_mfma_f32_16x16x32_bf16 v[16:19], v[232:235], v[188:191], v[16:19]
	v_mfma_f32_16x16x32_bf16 v[8:11], v[210:213], v[202:205], v[8:11]
	v_mfma_f32_16x16x32_bf16 v[0:3], v[232:235], v[202:205], v[0:3]
	s_add_i32 s70, s70, 2
	s_add_u32 s6, s6, 0x100
	s_addc_u32 s7, s7, 0
	s_add_u32 s68, s68, 0x100
	s_addc_u32 s69, s69, 0
	s_cmp_lt_u32 s70, 14
	s_barrier
	s_cbranch_scc1 .LBB0_1436
	v_mov_b32_e32 v134, v199
	v_mov_b32_e32 v128, v198
	s_lshl_b32 s4, s4, 8
	s_add_i32 s4, s4, s60
	v_add_u32_e32 v192, s4, v128
	v_lshlrev_b32_e32 v128, 2, v134
	v_ashrrev_i32_e32 v129, 31, v128
	v_ashrrev_i32_e32 v193, 31, v192
	v_add_u32_e32 v190, 16, v192
	v_lshl_add_u64 v[132:133], v[128:129], 2, s[8:9]
	v_lshlrev_b64 v[128:129], 6, v[192:193]
	v_ashrrev_i32_e32 v191, 31, v190
	v_add_u32_e32 v188, 32, v192
	v_lshl_add_u64 v[128:129], v[132:133], 0, v[128:129]
	v_lshlrev_b64 v[130:131], 6, v[190:191]
	v_ashrrev_i32_e32 v189, 31, v188
	v_lshl_add_u64 v[130:131], v[132:133], 0, v[130:131]
	global_load_dwordx4 v[202:205], v[128:129], off
	global_load_dwordx4 v[144:147], v[130:131], off
	v_lshlrev_b64 v[128:129], 6, v[188:189]
	v_add_u32_e32 v174, 48, v192
	v_lshl_add_u64 v[128:129], v[132:133], 0, v[128:129]
	v_ashrrev_i32_e32 v175, 31, v174
	global_load_dwordx4 v[148:151], v[128:129], off
	v_lshlrev_b64 v[128:129], 6, v[174:175]
	v_lshl_add_u64 v[128:129], v[132:133], 0, v[128:129]
	global_load_dwordx4 v[152:155], v[128:129], off
	v_add_u32_e32 v172, 0x80, v192
	v_ashrrev_i32_e32 v173, 31, v172
	v_lshlrev_b64 v[128:129], 6, v[172:173]
	v_lshl_add_u64 v[128:129], v[132:133], 0, v[128:129]
	global_load_dwordx4 v[140:143], v[128:129], off
	v_add_u32_e32 v170, 0x90, v192
	v_ashrrev_i32_e32 v171, 31, v170
	v_lshlrev_b64 v[128:129], 6, v[170:171]
	v_lshl_add_u64 v[128:129], v[132:133], 0, v[128:129]
	global_load_dwordx4 v[128:131], v[128:129], off
	s_lshl_b32 s5, s5, 7
	v_add_u32_e32 v168, 0xa0, v192
	v_add_u32_e32 v166, 0xb0, v192
	s_or_b32 s5, s5, s61
	v_ashrrev_i32_e32 v169, 31, v168
	v_ashrrev_i32_e32 v167, 31, v166
	v_lshl_add_u32 v194, v134, 3, s5
	v_lshlrev_b64 v[134:135], 6, v[168:169]
	v_lshlrev_b64 v[136:137], 6, v[166:167]
	v_lshl_add_u64 v[134:135], v[132:133], 0, v[134:135]
	v_lshl_add_u64 v[132:133], v[132:133], 0, v[136:137]
	global_load_dwordx4 v[136:139], v[134:135], off
	s_nop 0
	global_load_dwordx4 v[132:135], v[132:133], off
	s_mov_b32 s4, 0x358637bd
	v_mov_b64_e32 v[196:197], s[4:5]
	v_ashrrev_i32_e32 v195, 31, v194
	s_mov_b64 s[50:51], s[20:21]
	s_waitcnt vmcnt(0)
	v_mov_b32_e32 v206, v203
	v_mov_b32_e32 v207, v204
	v_mov_b32_e32 v203, v205
	v_mov_b32_e32 v204, v145
	v_mov_b32_e32 v205, v146
	v_mov_b32_e32 v145, v147
	v_pk_add_f32 v[202:203], v[206:207], v[202:203]
	v_mov_b32_e32 v146, v149
	v_mov_b32_e32 v147, v150
	v_mov_b32_e32 v149, v151
	v_mov_b32_e32 v150, v153
	v_mov_b32_e32 v151, v154
	v_mov_b32_e32 v153, v155
	v_pk_add_f32 v[144:145], v[204:205], v[144:145]
	v_mov_b32_e32 v155, v202
	v_pk_add_f32 v[146:147], v[146:147], v[148:149]
	v_pk_add_f32 v[148:149], v[150:151], v[152:153]
	v_mov_b32_e32 v154, v144
	v_mov_b32_e32 v202, v145
	v_mov_b32_e32 v144, v148
	v_mov_b32_e32 v145, v146
	v_mov_b32_e32 v146, v149
	v_pk_add_f32 v[148:149], v[154:155], v[202:203]
	v_pk_add_f32 v[144:145], v[144:145], v[146:147]
	ds_bpermute_b32 v147, v219, v149
	ds_bpermute_b32 v146, v219, v148
	ds_bpermute_b32 v151, v219, v145
	ds_bpermute_b32 v150, v219, v144
	v_mov_b32_e32 v152, v141
	v_mov_b32_e32 v153, v142
	v_mov_b32_e32 v141, v143
	s_waitcnt lgkmcnt(0)
	v_pk_add_f32 v[142:143], v[148:149], v[146:147]
	ds_bpermute_b32 v147, v218, v143
	ds_bpermute_b32 v146, v218, v142
	v_pk_add_f32 v[144:145], v[144:145], v[150:151]
	ds_bpermute_b32 v149, v218, v145
	ds_bpermute_b32 v148, v218, v144
	v_mov_b32_e32 v150, v129
	s_waitcnt lgkmcnt(2)
	v_pk_add_f32 v[142:143], v[142:143], v[146:147]
	v_mov_b32_e32 v151, v130
	v_pk_fma_f32 v[142:143], v[142:143], s[30:31], v[196:197] op_sel_hi:[1,0,0]
	s_waitcnt lgkmcnt(0)
	v_pk_add_f32 v[144:145], v[144:145], v[148:149]
	v_mul_f32_e32 v129, 0x4b800000, v143
	v_cmp_gt_f32_e32 vcc, s86, v143
	v_pk_fma_f32 v[146:147], v[144:145], s[30:31], v[196:197] op_sel_hi:[1,0,0]
	v_mul_f32_e32 v130, 0x4b800000, v142
	v_cndmask_b32_e32 v129, v143, v129, vcc
	v_rsq_f32_e32 v129, v129
	v_cmp_gt_f32_e64 s[4:5], s86, v142
	v_mul_f32_e32 v144, 0x4b800000, v147
	v_cmp_gt_f32_e64 s[6:7], s86, v147
	v_cndmask_b32_e64 v130, v142, v130, s[4:5]
	v_rsq_f32_e32 v142, v130
	v_cndmask_b32_e64 v130, v147, v144, s[6:7]
	v_rsq_f32_e32 v143, v130
	v_mul_f32_e32 v130, 0x45800000, v129
	v_cndmask_b32_e32 v144, v129, v130, vcc
	v_mov_b32_e32 v129, v131
	v_pk_add_f32 v[140:141], v[152:153], v[140:141]
	v_pk_add_f32 v[128:129], v[150:151], v[128:129]
	v_mov_b32_e32 v131, v140
	v_mov_b32_e32 v130, v128
	v_mov_b32_e32 v140, v129
	v_pk_add_f32 v[128:129], v[130:131], v[140:141]
	ds_bpermute_b32 v131, v219, v129
	ds_bpermute_b32 v130, v219, v128
	v_mul_f32_e32 v145, 0x45800000, v142
	v_cndmask_b32_e64 v142, v142, v145, s[4:5]
	v_mul_f32_e32 v140, 0x4b800000, v146
	v_cmp_gt_f32_e32 vcc, s86, v146
	s_waitcnt lgkmcnt(0)
	v_pk_add_f32 v[128:129], v[128:129], v[130:131]
	ds_bpermute_b32 v131, v218, v129
	ds_bpermute_b32 v130, v218, v128
	v_cndmask_b32_e32 v140, v146, v140, vcc
	v_rsq_f32_e32 v141, v140
	v_mul_f32_e32 v140, 0x45800000, v143
	v_cndmask_b32_e64 v140, v143, v140, s[6:7]
	s_waitcnt lgkmcnt(0)
	v_pk_add_f32 v[128:129], v[128:129], v[130:131]
	v_mov_b32_e32 v131, v138
	v_pk_fma_f32 v[128:129], v[128:129], s[30:31], v[196:197] op_sel_hi:[1,0,0]
	v_mul_f32_e32 v143, 0x45800000, v141
	v_mul_f32_e32 v130, 0x4b800000, v129
	v_cmp_gt_f32_e64 s[4:5], s86, v129
	v_cmp_gt_f32_e64 s[6:7], s86, v128
	v_pk_mul_f32 v[110:111], v[110:111], v[142:143] op_sel_hi:[1,0]
	v_cndmask_b32_e64 v129, v129, v130, s[4:5]
	v_mov_b32_e32 v130, v137
	v_mov_b32_e32 v137, v139
	v_pk_add_f32 v[130:131], v[130:131], v[136:137]
	v_mov_b32_e32 v136, v133
	v_mov_b32_e32 v137, v134
	v_mov_b32_e32 v133, v135
	v_pk_add_f32 v[132:133], v[136:137], v[132:133]
	v_mov_b32_e32 v135, v130
	v_mov_b32_e32 v134, v132
	v_mov_b32_e32 v130, v133
	v_pk_add_f32 v[130:131], v[134:135], v[130:131]
	ds_bpermute_b32 v133, v219, v131
	ds_bpermute_b32 v132, v219, v130
	v_rsq_f32_e32 v145, v129
	v_mul_f32_e32 v129, 0x4b800000, v128
	v_cndmask_b32_e64 v128, v128, v129, s[6:7]
	v_rsq_f32_e32 v135, v128
	s_waitcnt lgkmcnt(0)
	v_pk_add_f32 v[128:129], v[130:131], v[132:133]
	ds_bpermute_b32 v131, v218, v129
	ds_bpermute_b32 v130, v218, v128
	v_pk_mul_f32 v[126:127], v[126:127], v[144:145] op_sel_hi:[1,0]
	v_pk_mul_f32 v[122:123], v[122:123], v[144:145] op_sel_hi:[1,0]
	v_pk_mul_f32 v[116:117], v[116:117], v[144:145] op_sel_hi:[1,0]
	v_pk_mul_f32 v[124:125], v[124:125], v[144:145] op_sel_hi:[1,0]
	v_pk_mul_f32 v[138:139], v[126:127], s[44:45] op_sel_hi:[1,0]
	v_pk_mul_f32 v[120:121], v[120:121], v[144:145] op_sel_hi:[1,0]
	v_pk_mul_f32 v[122:123], v[126:127], v[122:123]
	v_pk_mul_f32 v[118:119], v[118:119], v[144:145] op_sel_hi:[1,0]
	v_pk_mul_f32 v[126:127], v[116:117], s[44:45] op_sel_hi:[1,0]
	v_pk_mul_f32 v[146:147], v[124:125], s[44:45] op_sel_hi:[1,0]
	v_pk_mul_f32 v[120:121], v[124:125], v[120:121]
	v_pk_mul_f32 v[124:125], v[118:119], s[44:45] op_sel_hi:[1,0]
	v_exp_f32_e32 v126, v126
	v_exp_f32_e32 v127, v127
	s_waitcnt lgkmcnt(0)
	v_pk_add_f32 v[128:129], v[128:129], v[130:131]
	v_exp_f32_e32 v146, v146
	v_exp_f32_e32 v138, v138
	v_exp_f32_e32 v139, v139
	v_exp_f32_e32 v147, v147
	v_exp_f32_e32 v124, v124
	v_exp_f32_e32 v125, v125
	v_pk_fma_f32 v[128:129], v[128:129], s[30:31], v[196:197] op_sel_hi:[1,0,0]
	v_cndmask_b32_e32 v136, v141, v143, vcc
	v_mul_f32_e32 v132, 0x45800000, v145
	v_mul_f32_e32 v130, 0x4b800000, v129
	v_cmp_gt_f32_e32 vcc, s86, v129
	v_cndmask_b32_e64 v134, v145, v132, s[4:5]
	v_cmp_gt_f32_e64 s[4:5], s86, v128
	v_cndmask_b32_e32 v129, v129, v130, vcc
	v_mul_f32_e32 v130, 0x4b800000, v128
	v_pk_add_f32 v[126:127], v[126:127], 1.0 op_sel_hi:[1,0]
	v_rsq_f32_e32 v129, v129
	v_cndmask_b32_e64 v128, v128, v130, s[4:5]
	v_pk_add_f32 v[138:139], v[138:139], 1.0 op_sel_hi:[1,0]
	v_pk_add_f32 v[146:147], v[146:147], 1.0 op_sel_hi:[1,0]
	v_pk_add_f32 v[124:125], v[124:125], 1.0 op_sel_hi:[1,0]
	v_rcp_f32_e32 v126, v126
	v_rcp_f32_e32 v127, v127
	v_rsq_f32_e32 v128, v128
	v_rcp_f32_e32 v146, v146
	v_rcp_f32_e32 v138, v138
	v_rcp_f32_e32 v139, v139
	v_rcp_f32_e32 v147, v147
	v_rcp_f32_e32 v124, v124
	v_rcp_f32_e32 v125, v125
	v_pk_mul_f32 v[112:113], v[112:113], v[144:145] op_sel_hi:[1,0]
	v_pk_mul_f32 v[114:115], v[114:115], v[144:145] op_sel_hi:[1,0]
	v_pk_mul_f32 v[112:113], v[116:117], v[112:113]
	v_mul_f32_e32 v130, 0x45800000, v129
	v_pk_mul_f32 v[114:115], v[118:119], v[114:115]
	v_pk_mul_f32 v[112:113], v[112:113], v[126:127]
	v_cndmask_b32_e32 v130, v129, v130, vcc
	v_mul_f32_e32 v129, 0x45800000, v128
	v_pk_mul_f32 v[122:123], v[122:123], v[138:139]
	v_pk_mul_f32 v[120:121], v[120:121], v[146:147]
	v_pk_mul_f32 v[114:115], v[114:115], v[124:125]
	v_cvt_pk_bf16_f32 v116, v120, v121
	v_cvt_pk_bf16_f32 v117, v122, v123
	v_cvt_pk_bf16_f32 v118, v112, v113
	v_mov_b64_e32 v[112:113], s[10:11]
	v_cndmask_b32_e64 v128, v128, v129, s[4:5]
	v_cvt_pk_bf16_f32 v119, v114, v115
	v_mad_i64_i32 v[120:121], s[4:5], v192, s35, v[112:113]
	v_lshlrev_b64 v[114:115], 1, v[194:195]
	v_lshl_add_u64 v[120:121], v[120:121], 0, v[114:115]
	v_pk_mul_f32 v[108:109], v[108:109], v[142:143] op_sel_hi:[1,0]
	v_pk_mul_f32 v[106:107], v[106:107], v[142:143] op_sel_hi:[1,0]
	v_pk_mul_f32 v[104:105], v[104:105], v[142:143] op_sel_hi:[1,0]
	v_pk_mul_f32 v[102:103], v[102:103], v[142:143] op_sel_hi:[1,0]
	v_pk_mul_f32 v[100:101], v[100:101], v[142:143] op_sel_hi:[1,0]
	global_store_dwordx4 v[120:121], v[116:119], off
	v_pk_mul_f32 v[104:105], v[108:109], v[104:105]
	v_pk_mul_f32 v[106:107], v[110:111], v[106:107]
	v_pk_mul_f32 v[116:117], v[110:111], s[44:45] op_sel_hi:[1,0]
	v_pk_mul_f32 v[118:119], v[108:109], s[44:45] op_sel_hi:[1,0]
	v_pk_mul_f32 v[108:109], v[102:103], s[44:45] op_sel_hi:[1,0]
	v_pk_mul_f32 v[110:111], v[100:101], s[44:45] op_sel_hi:[1,0]
	v_exp_f32_e32 v108, v108
	v_exp_f32_e32 v110, v110
	v_exp_f32_e32 v109, v109
	v_exp_f32_e32 v111, v111
	v_exp_f32_e32 v118, v118
	v_exp_f32_e32 v116, v116
	v_exp_f32_e32 v117, v117
	v_exp_f32_e32 v119, v119
	v_pk_add_f32 v[108:109], v[108:109], 1.0 op_sel_hi:[1,0]
	v_pk_add_f32 v[110:111], v[110:111], 1.0 op_sel_hi:[1,0]
	v_pk_add_f32 v[116:117], v[116:117], 1.0 op_sel_hi:[1,0]
	v_pk_add_f32 v[118:119], v[118:119], 1.0 op_sel_hi:[1,0]
	v_rcp_f32_e32 v110, v110
	v_rcp_f32_e32 v108, v108
	v_rcp_f32_e32 v109, v109
	v_rcp_f32_e32 v111, v111
	v_rcp_f32_e32 v118, v118
	v_rcp_f32_e32 v116, v116
	v_rcp_f32_e32 v117, v117
	v_rcp_f32_e32 v119, v119
	v_pk_mul_f32 v[98:99], v[98:99], v[142:143] op_sel_hi:[1,0]
	v_pk_mul_f32 v[96:97], v[96:97], v[142:143] op_sel_hi:[1,0]
	v_pk_mul_f32 v[98:99], v[102:103], v[98:99]
	v_pk_mul_f32 v[96:97], v[100:101], v[96:97]
	v_pk_mul_f32 v[100:101], v[98:99], v[108:109]
	v_pk_mul_f32 v[98:99], v[96:97], v[110:111]
	v_pk_mul_f32 v[106:107], v[106:107], v[116:117]
	v_pk_mul_f32 v[104:105], v[104:105], v[118:119]
	v_pk_mul_f32 v[94:95], v[94:95], v[140:141] op_sel_hi:[1,0]
	v_cvt_pk_bf16_f32 v96, v104, v105
	v_cvt_pk_bf16_f32 v97, v106, v107
	v_cvt_pk_bf16_f32 v98, v98, v99
	v_cvt_pk_bf16_f32 v99, v100, v101
	v_mad_i64_i32 v[100:101], s[4:5], v190, s35, v[112:113]
	v_lshl_add_u64 v[100:101], v[100:101], 0, v[114:115]
	v_pk_mul_f32 v[92:93], v[92:93], v[140:141] op_sel_hi:[1,0]
	v_pk_mul_f32 v[90:91], v[90:91], v[140:141] op_sel_hi:[1,0]
	v_pk_mul_f32 v[88:89], v[88:89], v[140:141] op_sel_hi:[1,0]
	v_pk_mul_f32 v[86:87], v[86:87], v[140:141] op_sel_hi:[1,0]
	v_pk_mul_f32 v[84:85], v[84:85], v[140:141] op_sel_hi:[1,0]
	global_store_dwordx4 v[100:101], v[96:99], off
	v_pk_mul_f32 v[88:89], v[92:93], v[88:89]
	v_pk_mul_f32 v[90:91], v[94:95], v[90:91]
	v_pk_mul_f32 v[96:97], v[94:95], s[44:45] op_sel_hi:[1,0]
	v_pk_mul_f32 v[98:99], v[92:93], s[44:45] op_sel_hi:[1,0]
	v_pk_mul_f32 v[92:93], v[86:87], s[44:45] op_sel_hi:[1,0]
	v_pk_mul_f32 v[94:95], v[84:85], s[44:45] op_sel_hi:[1,0]
	v_exp_f32_e32 v92, v92
	v_exp_f32_e32 v94, v94
	v_exp_f32_e32 v93, v93
	v_exp_f32_e32 v95, v95
	v_exp_f32_e32 v98, v98
	v_exp_f32_e32 v96, v96
	v_exp_f32_e32 v97, v97
	v_exp_f32_e32 v99, v99
	v_pk_add_f32 v[92:93], v[92:93], 1.0 op_sel_hi:[1,0]
	v_pk_add_f32 v[94:95], v[94:95], 1.0 op_sel_hi:[1,0]
	v_pk_add_f32 v[96:97], v[96:97], 1.0 op_sel_hi:[1,0]
	v_pk_add_f32 v[98:99], v[98:99], 1.0 op_sel_hi:[1,0]
	v_rcp_f32_e32 v94, v94
	v_rcp_f32_e32 v92, v92
	v_rcp_f32_e32 v93, v93
	v_rcp_f32_e32 v95, v95
	v_rcp_f32_e32 v98, v98
	v_rcp_f32_e32 v96, v96
	v_rcp_f32_e32 v97, v97
	v_rcp_f32_e32 v99, v99
	v_pk_mul_f32 v[82:83], v[82:83], v[140:141] op_sel_hi:[1,0]
	v_pk_mul_f32 v[80:81], v[80:81], v[140:141] op_sel_hi:[1,0]
	v_pk_mul_f32 v[82:83], v[86:87], v[82:83]
	v_pk_mul_f32 v[80:81], v[84:85], v[80:81]
	v_pk_mul_f32 v[84:85], v[82:83], v[92:93]
	v_pk_mul_f32 v[82:83], v[80:81], v[94:95]
	v_pk_mul_f32 v[90:91], v[90:91], v[96:97]
	v_pk_mul_f32 v[88:89], v[88:89], v[98:99]
	v_pk_mul_f32 v[78:79], v[78:79], v[136:137] op_sel_hi:[1,0]
	v_cvt_pk_bf16_f32 v80, v88, v89
	v_cvt_pk_bf16_f32 v81, v90, v91
	v_cvt_pk_bf16_f32 v82, v82, v83
	v_cvt_pk_bf16_f32 v83, v84, v85
	v_mad_i64_i32 v[84:85], s[4:5], v188, s35, v[112:113]
	v_lshl_add_u64 v[84:85], v[84:85], 0, v[114:115]
	v_pk_mul_f32 v[76:77], v[76:77], v[136:137] op_sel_hi:[1,0]
	v_pk_mul_f32 v[74:75], v[74:75], v[136:137] op_sel_hi:[1,0]
	v_pk_mul_f32 v[72:73], v[72:73], v[136:137] op_sel_hi:[1,0]
	v_pk_mul_f32 v[70:71], v[70:71], v[136:137] op_sel_hi:[1,0]
	v_pk_mul_f32 v[68:69], v[68:69], v[136:137] op_sel_hi:[1,0]
	global_store_dwordx4 v[84:85], v[80:83], off
	v_pk_mul_f32 v[72:73], v[76:77], v[72:73]
	v_pk_mul_f32 v[74:75], v[78:79], v[74:75]
	v_pk_mul_f32 v[80:81], v[78:79], s[44:45] op_sel_hi:[1,0]
	v_pk_mul_f32 v[82:83], v[76:77], s[44:45] op_sel_hi:[1,0]
	v_pk_mul_f32 v[76:77], v[70:71], s[44:45] op_sel_hi:[1,0]
	v_pk_mul_f32 v[78:79], v[68:69], s[44:45] op_sel_hi:[1,0]
	v_exp_f32_e32 v76, v76
	v_exp_f32_e32 v78, v78
	v_exp_f32_e32 v77, v77
	v_exp_f32_e32 v79, v79
	v_exp_f32_e32 v82, v82
	v_exp_f32_e32 v80, v80
	v_exp_f32_e32 v81, v81
	v_exp_f32_e32 v83, v83
	v_pk_add_f32 v[76:77], v[76:77], 1.0 op_sel_hi:[1,0]
	v_pk_add_f32 v[78:79], v[78:79], 1.0 op_sel_hi:[1,0]
	v_pk_add_f32 v[80:81], v[80:81], 1.0 op_sel_hi:[1,0]
	v_pk_add_f32 v[82:83], v[82:83], 1.0 op_sel_hi:[1,0]
	v_rcp_f32_e32 v78, v78
	v_rcp_f32_e32 v76, v76
	v_rcp_f32_e32 v77, v77
	v_rcp_f32_e32 v79, v79
	v_rcp_f32_e32 v82, v82
	v_rcp_f32_e32 v80, v80
	v_rcp_f32_e32 v81, v81
	v_rcp_f32_e32 v83, v83
	v_pk_mul_f32 v[66:67], v[66:67], v[136:137] op_sel_hi:[1,0]
	v_pk_mul_f32 v[64:65], v[64:65], v[136:137] op_sel_hi:[1,0]
	v_pk_mul_f32 v[66:67], v[70:71], v[66:67]
	v_pk_mul_f32 v[64:65], v[68:69], v[64:65]
	v_pk_mul_f32 v[68:69], v[66:67], v[76:77]
	v_pk_mul_f32 v[66:67], v[64:65], v[78:79]
	v_pk_mul_f32 v[74:75], v[74:75], v[80:81]
	v_pk_mul_f32 v[72:73], v[72:73], v[82:83]
	v_pk_mul_f32 v[62:63], v[62:63], v[134:135] op_sel_hi:[1,0]
	v_cvt_pk_bf16_f32 v64, v72, v73
	v_cvt_pk_bf16_f32 v65, v74, v75
	v_cvt_pk_bf16_f32 v66, v66, v67
	v_cvt_pk_bf16_f32 v67, v68, v69
	v_mad_i64_i32 v[68:69], s[4:5], v174, s35, v[112:113]
	v_lshl_add_u64 v[68:69], v[68:69], 0, v[114:115]
	v_pk_mul_f32 v[60:61], v[60:61], v[134:135] op_sel_hi:[1,0]
	v_pk_mul_f32 v[58:59], v[58:59], v[134:135] op_sel_hi:[1,0]
	v_pk_mul_f32 v[56:57], v[56:57], v[134:135] op_sel_hi:[1,0]
	v_pk_mul_f32 v[54:55], v[54:55], v[134:135] op_sel_hi:[1,0]
	v_pk_mul_f32 v[52:53], v[52:53], v[134:135] op_sel_hi:[1,0]
	global_store_dwordx4 v[68:69], v[64:67], off
	v_pk_mul_f32 v[56:57], v[60:61], v[56:57]
	v_pk_mul_f32 v[58:59], v[62:63], v[58:59]
	v_pk_mul_f32 v[64:65], v[62:63], s[44:45] op_sel_hi:[1,0]
	v_pk_mul_f32 v[66:67], v[60:61], s[44:45] op_sel_hi:[1,0]
	v_pk_mul_f32 v[60:61], v[54:55], s[44:45] op_sel_hi:[1,0]
	v_pk_mul_f32 v[62:63], v[52:53], s[44:45] op_sel_hi:[1,0]
	v_exp_f32_e32 v60, v60
	v_exp_f32_e32 v62, v62
	v_exp_f32_e32 v61, v61
	v_exp_f32_e32 v63, v63
	v_exp_f32_e32 v66, v66
	v_exp_f32_e32 v64, v64
	v_exp_f32_e32 v65, v65
	v_exp_f32_e32 v67, v67
	v_pk_add_f32 v[60:61], v[60:61], 1.0 op_sel_hi:[1,0]
	v_pk_add_f32 v[62:63], v[62:63], 1.0 op_sel_hi:[1,0]
	v_pk_add_f32 v[64:65], v[64:65], 1.0 op_sel_hi:[1,0]
	v_pk_add_f32 v[66:67], v[66:67], 1.0 op_sel_hi:[1,0]
	v_rcp_f32_e32 v62, v62
	v_rcp_f32_e32 v60, v60
	v_rcp_f32_e32 v61, v61
	v_rcp_f32_e32 v63, v63
	v_rcp_f32_e32 v66, v66
	v_rcp_f32_e32 v64, v64
	v_rcp_f32_e32 v65, v65
	v_rcp_f32_e32 v67, v67
	v_pk_mul_f32 v[50:51], v[50:51], v[134:135] op_sel_hi:[1,0]
	v_pk_mul_f32 v[48:49], v[48:49], v[134:135] op_sel_hi:[1,0]
	v_pk_mul_f32 v[50:51], v[54:55], v[50:51]
	v_pk_mul_f32 v[48:49], v[52:53], v[48:49]
	v_mul_f32_e32 v132, 0x45800000, v135
	v_pk_mul_f32 v[52:53], v[50:51], v[60:61]
	v_pk_mul_f32 v[50:51], v[48:49], v[62:63]
	v_cndmask_b32_e64 v132, v135, v132, s[6:7]
	v_pk_mul_f32 v[58:59], v[58:59], v[64:65]
	v_pk_mul_f32 v[56:57], v[56:57], v[66:67]
	v_pk_mul_f32 v[46:47], v[46:47], v[132:133] op_sel_hi:[1,0]
	v_cvt_pk_bf16_f32 v48, v56, v57
	v_cvt_pk_bf16_f32 v49, v58, v59
	v_cvt_pk_bf16_f32 v50, v50, v51
	v_cvt_pk_bf16_f32 v51, v52, v53
	v_mad_i64_i32 v[52:53], s[4:5], v172, s35, v[112:113]
	v_lshl_add_u64 v[52:53], v[52:53], 0, v[114:115]
	v_pk_mul_f32 v[44:45], v[44:45], v[132:133] op_sel_hi:[1,0]
	v_pk_mul_f32 v[42:43], v[42:43], v[132:133] op_sel_hi:[1,0]
	v_pk_mul_f32 v[40:41], v[40:41], v[132:133] op_sel_hi:[1,0]
	v_pk_mul_f32 v[38:39], v[38:39], v[132:133] op_sel_hi:[1,0]
	v_pk_mul_f32 v[36:37], v[36:37], v[132:133] op_sel_hi:[1,0]
	global_store_dwordx4 v[52:53], v[48:51], off
	v_pk_mul_f32 v[40:41], v[44:45], v[40:41]
	v_pk_mul_f32 v[42:43], v[46:47], v[42:43]
	v_pk_mul_f32 v[48:49], v[46:47], s[44:45] op_sel_hi:[1,0]
	v_pk_mul_f32 v[50:51], v[44:45], s[44:45] op_sel_hi:[1,0]
	v_pk_mul_f32 v[44:45], v[38:39], s[44:45] op_sel_hi:[1,0]
	v_pk_mul_f32 v[46:47], v[36:37], s[44:45] op_sel_hi:[1,0]
	v_exp_f32_e32 v44, v44
	v_exp_f32_e32 v46, v46
	v_exp_f32_e32 v45, v45
	v_exp_f32_e32 v47, v47
	v_exp_f32_e32 v50, v50
	v_exp_f32_e32 v48, v48
	v_exp_f32_e32 v49, v49
	v_exp_f32_e32 v51, v51
	v_pk_add_f32 v[44:45], v[44:45], 1.0 op_sel_hi:[1,0]
	v_pk_add_f32 v[46:47], v[46:47], 1.0 op_sel_hi:[1,0]
	v_pk_add_f32 v[48:49], v[48:49], 1.0 op_sel_hi:[1,0]
	v_pk_add_f32 v[50:51], v[50:51], 1.0 op_sel_hi:[1,0]
	v_rcp_f32_e32 v46, v46
	v_rcp_f32_e32 v44, v44
	v_rcp_f32_e32 v45, v45
	v_rcp_f32_e32 v47, v47
	v_rcp_f32_e32 v50, v50
	v_rcp_f32_e32 v48, v48
	v_rcp_f32_e32 v49, v49
	v_rcp_f32_e32 v51, v51
	v_pk_mul_f32 v[34:35], v[34:35], v[132:133] op_sel_hi:[1,0]
	v_pk_mul_f32 v[32:33], v[32:33], v[132:133] op_sel_hi:[1,0]
	v_pk_mul_f32 v[34:35], v[38:39], v[34:35]
	v_pk_mul_f32 v[32:33], v[36:37], v[32:33]
	v_pk_mul_f32 v[36:37], v[34:35], v[44:45]
	v_pk_mul_f32 v[34:35], v[32:33], v[46:47]
	v_pk_mul_f32 v[42:43], v[42:43], v[48:49]
	v_pk_mul_f32 v[40:41], v[40:41], v[50:51]
	v_pk_mul_f32 v[30:31], v[30:31], v[130:131] op_sel_hi:[1,0]
	v_cvt_pk_bf16_f32 v32, v40, v41
	v_cvt_pk_bf16_f32 v33, v42, v43
	v_cvt_pk_bf16_f32 v34, v34, v35
	v_cvt_pk_bf16_f32 v35, v36, v37
	v_mad_i64_i32 v[36:37], s[4:5], v170, s35, v[112:113]
	v_lshl_add_u64 v[36:37], v[36:37], 0, v[114:115]
	v_pk_mul_f32 v[28:29], v[28:29], v[130:131] op_sel_hi:[1,0]
	v_pk_mul_f32 v[26:27], v[26:27], v[130:131] op_sel_hi:[1,0]
	v_pk_mul_f32 v[24:25], v[24:25], v[130:131] op_sel_hi:[1,0]
	v_pk_mul_f32 v[22:23], v[22:23], v[130:131] op_sel_hi:[1,0]
	v_pk_mul_f32 v[20:21], v[20:21], v[130:131] op_sel_hi:[1,0]
	global_store_dwordx4 v[36:37], v[32:35], off
	v_pk_mul_f32 v[24:25], v[28:29], v[24:25]
	v_pk_mul_f32 v[26:27], v[30:31], v[26:27]
	v_pk_mul_f32 v[32:33], v[30:31], s[44:45] op_sel_hi:[1,0]
	v_pk_mul_f32 v[34:35], v[28:29], s[44:45] op_sel_hi:[1,0]
	v_pk_mul_f32 v[28:29], v[22:23], s[44:45] op_sel_hi:[1,0]
	v_pk_mul_f32 v[30:31], v[20:21], s[44:45] op_sel_hi:[1,0]
	v_exp_f32_e32 v28, v28
	v_exp_f32_e32 v30, v30
	v_exp_f32_e32 v29, v29
	v_exp_f32_e32 v31, v31
	v_exp_f32_e32 v34, v34
	v_exp_f32_e32 v32, v32
	v_exp_f32_e32 v33, v33
	v_exp_f32_e32 v35, v35
	v_pk_add_f32 v[28:29], v[28:29], 1.0 op_sel_hi:[1,0]
	v_pk_add_f32 v[30:31], v[30:31], 1.0 op_sel_hi:[1,0]
	v_pk_add_f32 v[32:33], v[32:33], 1.0 op_sel_hi:[1,0]
	v_pk_add_f32 v[34:35], v[34:35], 1.0 op_sel_hi:[1,0]
	v_rcp_f32_e32 v30, v30
	v_rcp_f32_e32 v28, v28
	v_rcp_f32_e32 v29, v29
	v_rcp_f32_e32 v31, v31
	v_rcp_f32_e32 v34, v34
	v_rcp_f32_e32 v32, v32
	v_rcp_f32_e32 v33, v33
	v_rcp_f32_e32 v35, v35
	v_pk_mul_f32 v[18:19], v[18:19], v[130:131] op_sel_hi:[1,0]
	v_pk_mul_f32 v[16:17], v[16:17], v[130:131] op_sel_hi:[1,0]
	v_pk_mul_f32 v[18:19], v[22:23], v[18:19]
	v_pk_mul_f32 v[16:17], v[20:21], v[16:17]
	v_pk_mul_f32 v[20:21], v[18:19], v[28:29]
	v_pk_mul_f32 v[18:19], v[16:17], v[30:31]
	v_pk_mul_f32 v[26:27], v[26:27], v[32:33]
	v_pk_mul_f32 v[24:25], v[24:25], v[34:35]
	v_pk_mul_f32 v[14:15], v[14:15], v[128:129] op_sel_hi:[1,0]
	v_cvt_pk_bf16_f32 v16, v24, v25
	v_cvt_pk_bf16_f32 v17, v26, v27
	v_cvt_pk_bf16_f32 v18, v18, v19
	v_cvt_pk_bf16_f32 v19, v20, v21
	v_mad_i64_i32 v[20:21], s[4:5], v168, s35, v[112:113]
	v_lshl_add_u64 v[20:21], v[20:21], 0, v[114:115]
	v_pk_mul_f32 v[12:13], v[12:13], v[128:129] op_sel_hi:[1,0]
	v_pk_mul_f32 v[10:11], v[10:11], v[128:129] op_sel_hi:[1,0]
	v_pk_mul_f32 v[8:9], v[8:9], v[128:129] op_sel_hi:[1,0]
	v_pk_mul_f32 v[6:7], v[6:7], v[128:129] op_sel_hi:[1,0]
	v_pk_mul_f32 v[4:5], v[4:5], v[128:129] op_sel_hi:[1,0]
	global_store_dwordx4 v[20:21], v[16:19], off
	v_pk_mul_f32 v[8:9], v[12:13], v[8:9]
	v_pk_mul_f32 v[10:11], v[14:15], v[10:11]
	v_pk_mul_f32 v[16:17], v[14:15], s[44:45] op_sel_hi:[1,0]
	v_pk_mul_f32 v[18:19], v[12:13], s[44:45] op_sel_hi:[1,0]
	v_pk_mul_f32 v[12:13], v[6:7], s[44:45] op_sel_hi:[1,0]
	v_pk_mul_f32 v[14:15], v[4:5], s[44:45] op_sel_hi:[1,0]
	v_exp_f32_e32 v12, v12
	v_exp_f32_e32 v14, v14
	v_exp_f32_e32 v13, v13
	v_exp_f32_e32 v15, v15
	v_exp_f32_e32 v18, v18
	v_exp_f32_e32 v16, v16
	v_exp_f32_e32 v17, v17
	v_exp_f32_e32 v19, v19
	v_pk_add_f32 v[12:13], v[12:13], 1.0 op_sel_hi:[1,0]
	v_pk_add_f32 v[14:15], v[14:15], 1.0 op_sel_hi:[1,0]
	v_pk_add_f32 v[16:17], v[16:17], 1.0 op_sel_hi:[1,0]
	v_pk_add_f32 v[18:19], v[18:19], 1.0 op_sel_hi:[1,0]
	v_rcp_f32_e32 v14, v14
	v_rcp_f32_e32 v12, v12
	v_rcp_f32_e32 v13, v13
	v_rcp_f32_e32 v15, v15
	v_rcp_f32_e32 v18, v18
	v_rcp_f32_e32 v16, v16
	v_rcp_f32_e32 v17, v17
	v_rcp_f32_e32 v19, v19
	v_pk_mul_f32 v[2:3], v[2:3], v[128:129] op_sel_hi:[1,0]
	v_pk_mul_f32 v[0:1], v[0:1], v[128:129] op_sel_hi:[1,0]
	v_pk_mul_f32 v[2:3], v[6:7], v[2:3]
	v_pk_mul_f32 v[0:1], v[4:5], v[0:1]
	v_pk_mul_f32 v[4:5], v[2:3], v[12:13]
	v_pk_mul_f32 v[2:3], v[0:1], v[14:15]
	v_pk_mul_f32 v[10:11], v[10:11], v[16:17]
	v_pk_mul_f32 v[8:9], v[8:9], v[18:19]
	s_andn2_b64 vcc, exec, s[2:3]
	v_cvt_pk_bf16_f32 v0, v8, v9
	v_cvt_pk_bf16_f32 v1, v10, v11
	v_cvt_pk_bf16_f32 v2, v2, v3
	v_cvt_pk_bf16_f32 v3, v4, v5
	v_mad_i64_i32 v[4:5], s[4:5], v166, s35, v[112:113]
	v_lshl_add_u64 v[4:5], v[4:5], 0, v[114:115]
	s_mov_b32 s4, s16
	s_mov_b32 s5, s12
	s_mov_b64 s[6:7], s[18:19]
	global_store_dwordx4 v[4:5], v[0:3], off
	s_cbranch_vccnz .LBB0_1429
	s_waitcnt vmcnt(0)
	s_cmpk_gt_u32 s24, 0xff
	s_cbranch_scc1 .LBB0_1440
	s_barrier
